# priority flips moved across the barriers (s_setprio 1 before the opening barrier, s_setprio 0 after the closing one) so each 32-MFMA segment is barrier, 32 MFMAs, barrier with nothing else on the pace
# speedup vs baseline: 1.0096x; 1.0030x over previous
; #define PG8_STAGE(bufoff, gbase, voff) do { _Pragma("unroll") for (int _i = 0; _i < 2; ++_i) \
;         __builtin_amdgcn_global_load_lds((const unsigned*)((const char*)(gbase) + (voff)[_i]), (PG8_LAS unsigned*)(lds + (bufoff) + ldsw + _i * 8192), 16, 0, 0); } while (0)
; #define PG8_LDA(dst, b, h) do { _Pragma("unroll") for (int m = 0; m < 4; ++m) _Pragma("unroll") for (int k = 0; k < 2; ++k) dst[m][k] = *(const PG8_LAS bf16x8*)(lds + PG8_SA(b, h) + aoff + m * 2048 + k * 1024); } while (0)
; #define PG8_LDB(dst, b, h) do { _Pragma("unroll") for (int n = 0; n < 2; ++n) _Pragma("unroll") for (int k = 0; k < 2; ++k) dst[n][k] = *(const PG8_LAS bf16x8*)(lds + PG8_SB(b, h) + boff + n * 2048 + k * 1024); } while (0)
; #define PG8_WAIT_V(n) asm volatile("s_waitcnt vmcnt(" #n ")" ::: "memory")
; #define PG8_WAIT_L(n) asm volatile("s_waitcnt lgkmcnt(" #n ")" ::: "memory")
; #define PG8_BAR __builtin_amdgcn_s_barrier()
; #define PG8_SCHED __builtin_amdgcn_sched_barrier(0)
; template <class Epi, class Sched, bool ALIGN_EPI = false, bool SP2 = false>
; __device__ __forceinline__ void gemm_phase(PG8_LAS unsigned char* lds, const Gemm g, const Sched& S, const Epi& E) {
;     ...
;         const bool has_next = S.next(ui + 1, nxt);
;         const char* nA = has_next ? (const char*)g.A + (size_t)nxt.pm * tstep : cA; const char* nB = has_next ? (const char*)g.Bt + (size_t)nxt.pn * tstep : cB;
;         for (int t = 0; t < nt; t += 2) {
;             const bool last = (t == nt - 2);
;             const char* a1 = cA + (size_t)(t + 1) * kstep;
;             const char* a2 = last ? nA : cA + (size_t)(t + 2) * kstep; const char* b2 = last ? nB : cB + (size_t)(t + 2) * kstep;
;             const char* a3 = a2 + kstep; const char* b3 = b2 + kstep;
;             if (last && has_next) S.a_ready(nxt);
;             if constexpr (SP2) {
;             PG8_LDB(B0, 0, 0); PG8_LDB(B1, 0, 1); PG8_SCHED; PG8_LDA(At, 0, 0); PG8_STAGE(PG8_SA(1, 1), a1 + hstep, voffA);
;             PG8_WAIT_V(8); PG8_WAIT_L(0); PG8_BAR; PG8_MMA(0, 0, At, B0); PG8_MMA(0, 1, At, B1); PG8_BAR; PG8_SCHED;
;             PG8_LDA(At, 0, 1); PG8_STAGE(PG8_SB(0, 0), b2, voffB); PG8_STAGE(PG8_SB(0, 1), b2 + hstep, voffB); PG8_STAGE(PG8_SA(0, 0), a2, voffA);
;             PG8_WAIT_V(8); PG8_WAIT_L(0); PG8_BAR; PG8_MMA(1, 0, At, B0); PG8_MMA(1, 1, At, B1); PG8_BAR; PG8_SCHED;
.LBB0_84:
	s_ashr_i32 s11, s10, 31
	s_lshl_b64 s[12:13], s[10:11], 20
	s_add_u32 s12, s46, s12
	s_addc_u32 s13, s47, s13
	s_and_b64 s[14:15], s[2:3], exec
	s_cselect_b32 s11, s13, s19
	s_cselect_b32 s42, s12, s18
	s_ashr_i32 s9, s8, 31
	s_lshl_b64 s[14:15], s[8:9], 20
	v_readlane_b32 s9, v255, 30
	s_add_u32 s14, s9, s14
	v_readlane_b32 s9, v255, 31
	s_addc_u32 s15, s9, s15
	s_and_b64 s[22:23], s[2:3], exec
	s_cselect_b32 s9, s15, s21
	s_cselect_b32 s44, s14, s20
	s_add_u32 s18, s18, 0x80080
	s_addc_u32 s19, s19, 0
	s_add_u32 s45, s20, 0x100
	s_addc_u32 s50, s21, 0
	s_mov_b32 s51, -2
	s_add_u32 s20, s18, 0xfff80080
	s_addc_u32 s21, s19, -1
	s_add_i32 s56, 0, 0x10000
	s_cmp_eq_u32 s51, 28
	s_cselect_b32 s23, s11, s21
	s_cselect_b32 s22, s42, s20
	v_add_u32_e32 v150, s56, v153
	s_cselect_b32 s21, s9, s50
	s_cselect_b32 s20, s44, s45
	s_add_i32 s63, 0, 0x14000
	ds_read_b128 v[184:187], v150
	ds_read_b128 v[188:191], v150 offset:1024
	ds_read_b128 v[192:195], v150 offset:2048
	ds_read_b128 v[196:199], v150 offset:3072
	v_add_u32_e32 v150, s63, v153
	ds_read_b128 v[200:203], v150
	ds_read_b128 v[204:207], v150 offset:1024
	ds_read_b128 v[208:211], v150 offset:2048
	ds_read_b128 v[212:215], v150 offset:3072
	s_add_i32 m0, s27, 0xc000
	ds_read_b128 v[216:219], v155
	ds_read_b128 v[220:223], v155 offset:1024
	ds_read_b128 v[224:227], v155 offset:2048
	ds_read_b128 v[228:231], v155 offset:3072
	ds_read_b128 v[232:235], v155 offset:4096
	ds_read_b128 v[236:239], v155 offset:5120
	ds_read_b128 v[240:243], v155 offset:6144
	ds_read_b128 v[244:247], v155 offset:7168
	global_load_lds_dwordx4 v136, s[18:19]
	s_add_i32 m0, s27, 0xe000
	s_nop 0
	global_load_lds_dwordx4 v138, s[18:19]
	s_waitcnt vmcnt(8)
	s_waitcnt lgkmcnt(0)
	s_setprio 1
	s_barrier
	v_mfma_f32_16x16x32_bf16 v[128:131], v[184:187], v[216:219], 0
	v_mfma_f32_16x16x32_bf16 v[120:123], v[192:195], v[216:219], 0
	v_mfma_f32_16x16x32_bf16 v[112:115], v[184:187], v[224:227], 0
	v_mfma_f32_16x16x32_bf16 v[104:107], v[192:195], v[224:227], 0
	v_mfma_f32_16x16x32_bf16 v[96:99], v[184:187], v[232:235], 0
	v_mfma_f32_16x16x32_bf16 v[88:91], v[192:195], v[232:235], 0
	v_mfma_f32_16x16x32_bf16 v[80:83], v[184:187], v[240:243], 0
	v_mfma_f32_16x16x32_bf16 v[72:75], v[192:195], v[240:243], 0
	v_mfma_f32_16x16x32_bf16 v[128:131], v[188:191], v[220:223], v[128:131]
	v_mfma_f32_16x16x32_bf16 v[120:123], v[196:199], v[220:223], v[120:123]
	v_mfma_f32_16x16x32_bf16 v[112:115], v[188:191], v[228:231], v[112:115]
	v_mfma_f32_16x16x32_bf16 v[104:107], v[196:199], v[228:231], v[104:107]
	v_mfma_f32_16x16x32_bf16 v[96:99], v[188:191], v[236:239], v[96:99]
	v_mfma_f32_16x16x32_bf16 v[88:91], v[196:199], v[236:239], v[88:91]
	v_mfma_f32_16x16x32_bf16 v[80:83], v[188:191], v[244:247], v[80:83]
	v_mfma_f32_16x16x32_bf16 v[72:75], v[196:199], v[244:247], v[72:75]
	v_mfma_f32_16x16x32_bf16 v[124:127], v[200:203], v[216:219], 0
	v_mfma_f32_16x16x32_bf16 v[116:119], v[208:211], v[216:219], 0
	v_mfma_f32_16x16x32_bf16 v[108:111], v[200:203], v[224:227], 0
	v_mfma_f32_16x16x32_bf16 v[100:103], v[208:211], v[224:227], 0
	v_mfma_f32_16x16x32_bf16 v[92:95], v[200:203], v[232:235], 0
	v_mfma_f32_16x16x32_bf16 v[84:87], v[208:211], v[232:235], 0
	v_mfma_f32_16x16x32_bf16 v[76:79], v[200:203], v[240:243], 0
	v_mfma_f32_16x16x32_bf16 v[68:71], v[208:211], v[240:243], 0
	v_mfma_f32_16x16x32_bf16 v[124:127], v[204:207], v[220:223], v[124:127]
	v_mfma_f32_16x16x32_bf16 v[116:119], v[212:215], v[220:223], v[116:119]
	v_mfma_f32_16x16x32_bf16 v[108:111], v[204:207], v[228:231], v[108:111]
	v_mfma_f32_16x16x32_bf16 v[100:103], v[212:215], v[228:231], v[100:103]
	v_mfma_f32_16x16x32_bf16 v[92:95], v[204:207], v[236:239], v[92:95]
	v_mfma_f32_16x16x32_bf16 v[84:87], v[212:215], v[236:239], v[84:87]
	v_mfma_f32_16x16x32_bf16 v[76:79], v[204:207], v[244:247], v[76:79]
	v_mfma_f32_16x16x32_bf16 v[68:71], v[212:215], v[244:247], v[68:71]
	s_barrier
	s_setprio 0
	s_add_i32 s56, s56, s25
	s_mov_b32 m0, s56
	ds_read_b128 v[216:219], v155 offset:16384
	ds_read_b128 v[220:223], v155 offset:17408
	ds_read_b128 v[224:227], v155 offset:18432
	ds_read_b128 v[228:231], v155 offset:19456
	ds_read_b128 v[232:235], v155 offset:20480
	ds_read_b128 v[236:239], v155 offset:21504
	ds_read_b128 v[240:243], v155 offset:22528
	ds_read_b128 v[244:247], v155 offset:23552
	global_load_lds_dwordx4 v2, s[20:21]
	s_add_i32 m0, s56, 0x2000
	s_add_u32 s56, s20, 0x80000
	s_addc_u32 s57, s21, 0
	s_add_i32 s63, s63, s25
	global_load_lds_dwordx4 v0, s[20:21]
	s_mov_b32 m0, s63
	v_lshl_add_u64 v[252:253], s[22:23], 0, v[132:133]
	global_load_lds_dwordx4 v2, s[56:57]
	s_add_i32 m0, s63, 0x2000
	s_nop 0
	global_load_lds_dwordx4 v0, s[56:57]
	v_lshl_add_u64 v[250:251], s[22:23], 0, v[134:135]
	s_mov_b32 m0, s27
	s_nop 0
	global_load_lds_dwordx4 v[250:251], off
	s_mov_b32 m0, s28
	s_nop 0
	global_load_lds_dwordx4 v[252:253], off
	s_waitcnt vmcnt(8)
	s_waitcnt lgkmcnt(0)
	s_setprio 1
	s_barrier
; #define PG8_STAGE(bufoff, gbase, voff) do { _Pragma("unroll") for (int _i = 0; _i < 2; ++_i) \
;         __builtin_amdgcn_global_load_lds((const unsigned*)((const char*)(gbase) + (voff)[_i]), (PG8_LAS unsigned*)(lds + (bufoff) + ldsw + _i * 8192), 16, 0, 0); } while (0)
; #define PG8_LDA(dst, b, h) do { _Pragma("unroll") for (int m = 0; m < 4; ++m) _Pragma("unroll") for (int k = 0; k < 2; ++k) dst[m][k] = *(const PG8_LAS bf16x8*)(lds + PG8_SA(b, h) + aoff + m * 2048 + k * 1024); } while (0)
; #define PG8_LDB(dst, b, h) do { _Pragma("unroll") for (int n = 0; n < 2; ++n) _Pragma("unroll") for (int k = 0; k < 2; ++k) dst[n][k] = *(const PG8_LAS bf16x8*)(lds + PG8_SB(b, h) + boff + n * 2048 + k * 1024); } while (0)
; #define PG8_MMA(ai, bj, At, Bt) do { __builtin_amdgcn_s_setprio(1); _Pragma("unroll") for (int m = 0; m < 4; ++m) _Pragma("unroll") for (int n = 0; n < 2; ++n) _Pragma("unroll") for (int k = 0; k < 2; ++k) \
;         acc[ai][bj][m][n] = __builtin_amdgcn_mfma_f32_16x16x32_bf16(Bt[n][k], At[m][k], acc[ai][bj][m][n], 0, 0, 0); __builtin_amdgcn_s_setprio(0); } while (0)
; #define PG8_WAIT_V(n) asm volatile("s_waitcnt vmcnt(" #n ")" ::: "memory")
; #define PG8_WAIT_L(n) asm volatile("s_waitcnt lgkmcnt(" #n ")" ::: "memory")
; #define PG8_BAR __builtin_amdgcn_s_barrier()
; #define PG8_SCHED __builtin_amdgcn_sched_barrier(0)
; template <class Epi, class Sched, bool ALIGN_EPI = false, bool SP2 = false>
; __device__ __forceinline__ void gemm_phase(PG8_LAS unsigned char* lds, const Gemm g, const Sched& S, const Epi& E) {
;     ...
;             PG8_WAIT_V(8); PG8_WAIT_L(0); PG8_BAR; PG8_MMA(1, 0, At, B0); PG8_MMA(1, 1, At, B1); PG8_BAR; PG8_SCHED;
;             PG8_LDB(B0, 1, 0); PG8_LDB(B1, 1, 1); PG8_SCHED; PG8_LDA(At, 1, 0); PG8_STAGE(PG8_SA(0, 1), a2 + hstep, voffA);
;             PG8_WAIT_V(8); PG8_WAIT_L(0); PG8_BAR; PG8_MMA(0, 0, At, B0); PG8_MMA(0, 1, At, B1); PG8_BAR; PG8_SCHED;
	v_mfma_f32_16x16x32_bf16 v[64:67], v[184:187], v[216:219], 0
	v_mfma_f32_16x16x32_bf16 v[56:59], v[192:195], v[216:219], 0
	v_mfma_f32_16x16x32_bf16 v[48:51], v[184:187], v[224:227], 0
	v_mfma_f32_16x16x32_bf16 v[40:43], v[192:195], v[224:227], 0
	v_mfma_f32_16x16x32_bf16 v[32:35], v[184:187], v[232:235], 0
	v_mfma_f32_16x16x32_bf16 v[24:27], v[192:195], v[232:235], 0
	v_mfma_f32_16x16x32_bf16 v[16:19], v[184:187], v[240:243], 0
	v_mfma_f32_16x16x32_bf16 v[8:11], v[192:195], v[240:243], 0
	v_mfma_f32_16x16x32_bf16 v[64:67], v[188:191], v[220:223], v[64:67]
	v_mfma_f32_16x16x32_bf16 v[56:59], v[196:199], v[220:223], v[56:59]
	v_mfma_f32_16x16x32_bf16 v[48:51], v[188:191], v[228:231], v[48:51]
	v_mfma_f32_16x16x32_bf16 v[40:43], v[196:199], v[228:231], v[40:43]
	v_mfma_f32_16x16x32_bf16 v[32:35], v[188:191], v[236:239], v[32:35]
	v_mfma_f32_16x16x32_bf16 v[24:27], v[196:199], v[236:239], v[24:27]
	v_mfma_f32_16x16x32_bf16 v[16:19], v[188:191], v[244:247], v[16:19]
	v_mfma_f32_16x16x32_bf16 v[8:11], v[196:199], v[244:247], v[8:11]
	v_mfma_f32_16x16x32_bf16 v[60:63], v[200:203], v[216:219], 0
	v_mfma_f32_16x16x32_bf16 v[52:55], v[208:211], v[216:219], 0
	v_mfma_f32_16x16x32_bf16 v[44:47], v[200:203], v[224:227], 0
	v_mfma_f32_16x16x32_bf16 v[36:39], v[208:211], v[224:227], 0
	v_mfma_f32_16x16x32_bf16 v[28:31], v[200:203], v[232:235], 0
	v_mfma_f32_16x16x32_bf16 v[20:23], v[208:211], v[232:235], 0
	v_mfma_f32_16x16x32_bf16 v[12:15], v[200:203], v[240:243], 0
	v_mfma_f32_16x16x32_bf16 v[4:7], v[208:211], v[240:243], 0
	v_mfma_f32_16x16x32_bf16 v[60:63], v[204:207], v[220:223], v[60:63]
	v_mfma_f32_16x16x32_bf16 v[52:55], v[212:215], v[220:223], v[52:55]
	v_mfma_f32_16x16x32_bf16 v[44:47], v[204:207], v[228:231], v[44:47]
	v_mfma_f32_16x16x32_bf16 v[36:39], v[212:215], v[228:231], v[36:39]
	v_mfma_f32_16x16x32_bf16 v[28:31], v[204:207], v[236:239], v[28:31]
	v_mfma_f32_16x16x32_bf16 v[20:23], v[212:215], v[236:239], v[20:23]
	v_mfma_f32_16x16x32_bf16 v[12:15], v[204:207], v[244:247], v[12:15]
	v_mfma_f32_16x16x32_bf16 v[4:7], v[212:215], v[244:247], v[4:7]
	s_barrier
	s_setprio 0
	s_add_i32 s56, 0, 0x18000
	v_add_u32_e32 v161, s56, v153
	s_add_i32 s57, 0, 0x1c000
	ds_read_b128 v[184:187], v161
	ds_read_b128 v[188:191], v161 offset:1024
	ds_read_b128 v[192:195], v161 offset:2048
	ds_read_b128 v[196:199], v161 offset:3072
	v_add_u32_e32 v161, s57, v153
	ds_read_b128 v[200:203], v161
	ds_read_b128 v[204:207], v161 offset:1024
	ds_read_b128 v[208:211], v161 offset:2048
	ds_read_b128 v[212:215], v161 offset:3072
	s_add_u32 s22, s22, 0x80000
	s_addc_u32 s23, s23, 0
	s_mov_b32 m0, s29
	ds_read_b128 v[216:219], v155 offset:32768
	ds_read_b128 v[220:223], v155 offset:33792
	ds_read_b128 v[224:227], v155 offset:34816
	ds_read_b128 v[228:231], v155 offset:35840
	ds_read_b128 v[232:235], v155 offset:36864
	ds_read_b128 v[236:239], v155 offset:37888
	ds_read_b128 v[240:243], v155 offset:38912
	ds_read_b128 v[244:247], v155 offset:39936
	global_load_lds_dwordx4 v134, s[22:23]
	s_mov_b32 m0, s30
	s_nop 0
	global_load_lds_dwordx4 v132, s[22:23]
	s_waitcnt vmcnt(8)
	s_waitcnt lgkmcnt(0)
	s_setprio 1
	s_barrier
	v_mfma_f32_16x16x32_bf16 v[128:131], v[184:187], v[216:219], v[128:131]
	v_mfma_f32_16x16x32_bf16 v[120:123], v[192:195], v[216:219], v[120:123]
	v_mfma_f32_16x16x32_bf16 v[112:115], v[184:187], v[224:227], v[112:115]
	v_mfma_f32_16x16x32_bf16 v[104:107], v[192:195], v[224:227], v[104:107]
	v_mfma_f32_16x16x32_bf16 v[96:99], v[184:187], v[232:235], v[96:99]
	v_mfma_f32_16x16x32_bf16 v[88:91], v[192:195], v[232:235], v[88:91]
	v_mfma_f32_16x16x32_bf16 v[80:83], v[184:187], v[240:243], v[80:83]
	v_mfma_f32_16x16x32_bf16 v[72:75], v[192:195], v[240:243], v[72:75]
	v_mfma_f32_16x16x32_bf16 v[128:131], v[188:191], v[220:223], v[128:131]
	v_mfma_f32_16x16x32_bf16 v[120:123], v[196:199], v[220:223], v[120:123]
	v_mfma_f32_16x16x32_bf16 v[112:115], v[188:191], v[228:231], v[112:115]
	v_mfma_f32_16x16x32_bf16 v[104:107], v[196:199], v[228:231], v[104:107]
	v_mfma_f32_16x16x32_bf16 v[96:99], v[188:191], v[236:239], v[96:99]
	v_mfma_f32_16x16x32_bf16 v[88:91], v[196:199], v[236:239], v[88:91]
	v_mfma_f32_16x16x32_bf16 v[80:83], v[188:191], v[244:247], v[80:83]
	v_mfma_f32_16x16x32_bf16 v[72:75], v[196:199], v[244:247], v[72:75]
	v_mfma_f32_16x16x32_bf16 v[124:127], v[200:203], v[216:219], v[124:127]
	v_mfma_f32_16x16x32_bf16 v[116:119], v[208:211], v[216:219], v[116:119]
	v_mfma_f32_16x16x32_bf16 v[108:111], v[200:203], v[224:227], v[108:111]
	v_mfma_f32_16x16x32_bf16 v[100:103], v[208:211], v[224:227], v[100:103]
	v_mfma_f32_16x16x32_bf16 v[92:95], v[200:203], v[232:235], v[92:95]
	v_mfma_f32_16x16x32_bf16 v[84:87], v[208:211], v[232:235], v[84:87]
	v_mfma_f32_16x16x32_bf16 v[76:79], v[200:203], v[240:243], v[76:79]
	v_mfma_f32_16x16x32_bf16 v[68:71], v[208:211], v[240:243], v[68:71]
	v_mfma_f32_16x16x32_bf16 v[124:127], v[204:207], v[220:223], v[124:127]
	v_mfma_f32_16x16x32_bf16 v[116:119], v[212:215], v[220:223], v[116:119]
	v_mfma_f32_16x16x32_bf16 v[108:111], v[204:207], v[228:231], v[108:111]
	v_mfma_f32_16x16x32_bf16 v[100:103], v[212:215], v[228:231], v[100:103]
	v_mfma_f32_16x16x32_bf16 v[92:95], v[204:207], v[236:239], v[92:95]
	v_mfma_f32_16x16x32_bf16 v[84:87], v[212:215], v[236:239], v[84:87]
	v_mfma_f32_16x16x32_bf16 v[76:79], v[204:207], v[244:247], v[76:79]
	v_mfma_f32_16x16x32_bf16 v[68:71], v[212:215], v[244:247], v[68:71]
	s_barrier
; #define PG8_STAGE(bufoff, gbase, voff) do { _Pragma("unroll") for (int _i = 0; _i < 2; ++_i) \
;         __builtin_amdgcn_global_load_lds((const unsigned*)((const char*)(gbase) + (voff)[_i]), (PG8_LAS unsigned*)(lds + (bufoff) + ldsw + _i * 8192), 16, 0, 0); } while (0)
; #define PG8_LDA(dst, b, h) do { _Pragma("unroll") for (int m = 0; m < 4; ++m) _Pragma("unroll") for (int k = 0; k < 2; ++k) dst[m][k] = *(const PG8_LAS bf16x8*)(lds + PG8_SA(b, h) + aoff + m * 2048 + k * 1024); } while (0)
; #define PG8_LDB(dst, b, h) do { _Pragma("unroll") for (int n = 0; n < 2; ++n) _Pragma("unroll") for (int k = 0; k < 2; ++k) dst[n][k] = *(const PG8_LAS bf16x8*)(lds + PG8_SB(b, h) + boff + n * 2048 + k * 1024); } while (0)
; #define PG8_MMA(ai, bj, At, Bt) do { __builtin_amdgcn_s_setprio(1); _Pragma("unroll") for (int m = 0; m < 4; ++m) _Pragma("unroll") for (int n = 0; n < 2; ++n) _Pragma("unroll") for (int k = 0; k < 2; ++k) \
;         acc[ai][bj][m][n] = __builtin_amdgcn_mfma_f32_16x16x32_bf16(Bt[n][k], At[m][k], acc[ai][bj][m][n], 0, 0, 0); __builtin_amdgcn_s_setprio(0); } while (0)
; #define PG8_WAIT_V(n) asm volatile("s_waitcnt vmcnt(" #n ")" ::: "memory")
; template <class Epi, class Sched, bool ALIGN_EPI = false, bool SP2 = false>
; __device__ __forceinline__ void gemm_phase(PG8_LAS unsigned char* lds, const Gemm g, const Sched& S, const Epi& E) {
;     ...
;             PG8_LDB(B0, 0, 0); PG8_LDB(B1, 0, 1); PG8_SCHED; PG8_LDA(At, 0, 0); PG8_STAGE(PG8_SA(1, 1), a1 + hstep, voffA);
;             PG8_WAIT_V(8); PG8_WAIT_L(0); PG8_BAR; PG8_MMA(0, 0, At, B0); PG8_MMA(0, 1, At, B1); PG8_BAR; PG8_SCHED;
;             PG8_LDA(At, 0, 1); PG8_STAGE(PG8_SB(0, 0), b2, voffB); PG8_STAGE(PG8_SB(0, 1), b2 + hstep, voffB); PG8_STAGE(PG8_SA(0, 0), a2, voffA);
;             PG8_WAIT_V(8); PG8_WAIT_L(0); PG8_BAR; PG8_MMA(1, 0, At, B0); PG8_MMA(1, 1, At, B1); PG8_BAR; PG8_SCHED;
;             PG8_LDB(B0, 1, 0); PG8_LDB(B1, 1, 1); PG8_SCHED; PG8_LDA(At, 1, 0); PG8_STAGE(PG8_SA(0, 1), a2 + hstep, voffA);
;             PG8_WAIT_V(8); PG8_WAIT_L(0); PG8_BAR; PG8_MMA(0, 0, At, B0); PG8_MMA(0, 1, At, B1); PG8_BAR; PG8_SCHED;
;             PG8_LDA(At, 1, 1); PG8_STAGE(PG8_SB(1, 0), b3, voffB); PG8_STAGE(PG8_SB(1, 1), b3 + hstep, voffB); PG8_STAGE(PG8_SA(1, 0), a3, voffA);
;             PG8_WAIT_V(8); PG8_WAIT_L(0); PG8_BAR; PG8_MMA(1, 0, At, B0); PG8_MMA(1, 1, At, B1); PG8_BAR; PG8_SCHED;
	s_setprio 0
	s_add_i32 s22, s56, s25
	s_mov_b32 m0, s22
	ds_read_b128 v[216:219], v155 offset:49152
	ds_read_b128 v[220:223], v155 offset:50176
	ds_read_b128 v[224:227], v155 offset:51200
	ds_read_b128 v[228:231], v155 offset:52224
	ds_read_b128 v[232:235], v155 offset:53248
	ds_read_b128 v[236:239], v155 offset:54272
	ds_read_b128 v[240:243], v155 offset:55296
	ds_read_b128 v[244:247], v155 offset:56320
	s_add_u32 vcc_lo, s20, 0x80
	s_addc_u32 vcc_hi, s21, 0
	global_load_lds_dwordx4 v2, vcc
	s_add_i32 m0, s22, 0x2000
	s_add_u32 s20, s20, 0x80080
	s_addc_u32 s21, s21, 0
	s_add_i32 s22, s57, s25
	s_add_u32 vcc_lo, s20, 0xfff80000
	s_addc_u32 vcc_hi, s21, -1
	global_load_lds_dwordx4 v0, vcc
	s_mov_b32 m0, s22
	s_nop 0
	global_load_lds_dwordx4 v2, s[20:21]
	s_add_i32 m0, s22, 0x2000
	s_nop 0
	global_load_lds_dwordx4 v0, s[20:21]
	v_lshl_add_u64 v[150:151], v[250:251], 0, s[36:37]
	s_mov_b32 m0, s31
	s_nop 0
	global_load_lds_dwordx4 v[150:151], off
	v_lshl_add_u64 v[150:151], v[252:253], 0, s[36:37]
	s_mov_b32 m0, s34
	s_nop 0
	global_load_lds_dwordx4 v[150:151], off
	s_waitcnt vmcnt(8)
	s_waitcnt lgkmcnt(0)
	s_setprio 1
	s_barrier
	v_mfma_f32_16x16x32_bf16 v[64:67], v[184:187], v[216:219], v[64:67]
	v_mfma_f32_16x16x32_bf16 v[56:59], v[192:195], v[216:219], v[56:59]
	v_mfma_f32_16x16x32_bf16 v[48:51], v[184:187], v[224:227], v[48:51]
	v_mfma_f32_16x16x32_bf16 v[40:43], v[192:195], v[224:227], v[40:43]
	v_mfma_f32_16x16x32_bf16 v[32:35], v[184:187], v[232:235], v[32:35]
	v_mfma_f32_16x16x32_bf16 v[24:27], v[192:195], v[232:235], v[24:27]
	v_mfma_f32_16x16x32_bf16 v[16:19], v[184:187], v[240:243], v[16:19]
	v_mfma_f32_16x16x32_bf16 v[8:11], v[192:195], v[240:243], v[8:11]
	v_mfma_f32_16x16x32_bf16 v[64:67], v[188:191], v[220:223], v[64:67]
	v_mfma_f32_16x16x32_bf16 v[56:59], v[196:199], v[220:223], v[56:59]
	v_mfma_f32_16x16x32_bf16 v[48:51], v[188:191], v[228:231], v[48:51]
	v_mfma_f32_16x16x32_bf16 v[40:43], v[196:199], v[228:231], v[40:43]
	v_mfma_f32_16x16x32_bf16 v[32:35], v[188:191], v[236:239], v[32:35]
	v_mfma_f32_16x16x32_bf16 v[24:27], v[196:199], v[236:239], v[24:27]
	v_mfma_f32_16x16x32_bf16 v[16:19], v[188:191], v[244:247], v[16:19]
	v_mfma_f32_16x16x32_bf16 v[8:11], v[196:199], v[244:247], v[8:11]
	v_mfma_f32_16x16x32_bf16 v[60:63], v[200:203], v[216:219], v[60:63]
	v_mfma_f32_16x16x32_bf16 v[52:55], v[208:211], v[216:219], v[52:55]
	v_mfma_f32_16x16x32_bf16 v[44:47], v[200:203], v[224:227], v[44:47]
	v_mfma_f32_16x16x32_bf16 v[36:39], v[208:211], v[224:227], v[36:39]
	v_mfma_f32_16x16x32_bf16 v[28:31], v[200:203], v[232:235], v[28:31]
	v_mfma_f32_16x16x32_bf16 v[20:23], v[208:211], v[232:235], v[20:23]
	v_mfma_f32_16x16x32_bf16 v[12:15], v[200:203], v[240:243], v[12:15]
	v_mfma_f32_16x16x32_bf16 v[4:7], v[208:211], v[240:243], v[4:7]
	v_mfma_f32_16x16x32_bf16 v[60:63], v[204:207], v[220:223], v[60:63]
	v_mfma_f32_16x16x32_bf16 v[52:55], v[212:215], v[220:223], v[52:55]
	v_mfma_f32_16x16x32_bf16 v[44:47], v[204:207], v[228:231], v[44:47]
	v_mfma_f32_16x16x32_bf16 v[36:39], v[212:215], v[228:231], v[36:39]
	v_mfma_f32_16x16x32_bf16 v[28:31], v[204:207], v[236:239], v[28:31]
	v_mfma_f32_16x16x32_bf16 v[20:23], v[212:215], v[236:239], v[20:23]
	v_mfma_f32_16x16x32_bf16 v[12:15], v[204:207], v[244:247], v[12:15]
	v_mfma_f32_16x16x32_bf16 v[4:7], v[212:215], v[244:247], v[4:7]
	s_barrier
	s_setprio 0
	s_add_i32 s51, s51, 2
	s_add_u32 s18, s18, 0x100
	s_addc_u32 s19, s19, 0
	s_add_u32 s45, s45, 0x100
	s_addc_u32 s50, s50, 0
	s_cmp_gt_u32 s51, 29
.LBB0_85:
	s_add_u32 s20, s18, 0xfff80080
	s_addc_u32 s21, s19, -1
	s_add_i32 s56, 0, 0x10000
	s_cmp_eq_u32 s51, 28
	s_cselect_b32 s23, s11, s21
	s_cselect_b32 s22, s42, s20
	v_add_u32_e32 v150, s56, v153
	s_cselect_b32 s21, s9, s50
	s_cselect_b32 s20, s44, s45
	s_add_i32 s63, 0, 0x14000
	ds_read_b128 v[184:187], v150
	ds_read_b128 v[188:191], v150 offset:1024
	ds_read_b128 v[192:195], v150 offset:2048
	ds_read_b128 v[196:199], v150 offset:3072
	v_add_u32_e32 v150, s63, v153
	ds_read_b128 v[200:203], v150
	ds_read_b128 v[204:207], v150 offset:1024
	ds_read_b128 v[208:211], v150 offset:2048
	ds_read_b128 v[212:215], v150 offset:3072
	s_add_i32 m0, s27, 0xc000
	ds_read_b128 v[216:219], v155
	ds_read_b128 v[220:223], v155 offset:1024
	ds_read_b128 v[224:227], v155 offset:2048
	ds_read_b128 v[228:231], v155 offset:3072
	ds_read_b128 v[232:235], v155 offset:4096
	ds_read_b128 v[236:239], v155 offset:5120
	ds_read_b128 v[240:243], v155 offset:6144
	ds_read_b128 v[244:247], v155 offset:7168
	global_load_lds_dwordx4 v136, s[18:19]
	s_add_i32 m0, s27, 0xe000
	s_nop 0
	global_load_lds_dwordx4 v138, s[18:19]
	s_waitcnt vmcnt(8)
	s_waitcnt lgkmcnt(0)
	s_setprio 1
	s_barrier
; #define PG8_STAGE(bufoff, gbase, voff) do { _Pragma("unroll") for (int _i = 0; _i < 2; ++_i) \
;         __builtin_amdgcn_global_load_lds((const unsigned*)((const char*)(gbase) + (voff)[_i]), (PG8_LAS unsigned*)(lds + (bufoff) + ldsw + _i * 8192), 16, 0, 0); } while (0)
; #define PG8_LDA(dst, b, h) do { _Pragma("unroll") for (int m = 0; m < 4; ++m) _Pragma("unroll") for (int k = 0; k < 2; ++k) dst[m][k] = *(const PG8_LAS bf16x8*)(lds + PG8_SA(b, h) + aoff + m * 2048 + k * 1024); } while (0)
; #define PG8_LDB(dst, b, h) do { _Pragma("unroll") for (int n = 0; n < 2; ++n) _Pragma("unroll") for (int k = 0; k < 2; ++k) dst[n][k] = *(const PG8_LAS bf16x8*)(lds + PG8_SB(b, h) + boff + n * 2048 + k * 1024); } while (0)
; #define PG8_MMA(ai, bj, At, Bt) do { __builtin_amdgcn_s_setprio(1); _Pragma("unroll") for (int m = 0; m < 4; ++m) _Pragma("unroll") for (int n = 0; n < 2; ++n) _Pragma("unroll") for (int k = 0; k < 2; ++k) \
;         acc[ai][bj][m][n] = __builtin_amdgcn_mfma_f32_16x16x32_bf16(Bt[n][k], At[m][k], acc[ai][bj][m][n], 0, 0, 0); __builtin_amdgcn_s_setprio(0); } while (0)
; #define PG8_WAIT_V(n) asm volatile("s_waitcnt vmcnt(" #n ")" ::: "memory")
; #define PG8_WAIT_L(n) asm volatile("s_waitcnt lgkmcnt(" #n ")" ::: "memory")
; #define PG8_BAR __builtin_amdgcn_s_barrier()
; #define PG8_SCHED __builtin_amdgcn_sched_barrier(0)
; template <class Epi, class Sched, bool ALIGN_EPI = false, bool SP2 = false>
; __device__ __forceinline__ void gemm_phase(PG8_LAS unsigned char* lds, const Gemm g, const Sched& S, const Epi& E) {
;     ...
;             PG8_LDB(B0, 0, 0); PG8_LDB(B1, 0, 1); PG8_SCHED; PG8_LDA(At, 0, 0); PG8_STAGE(PG8_SA(1, 1), a1 + hstep, voffA);
;             PG8_WAIT_V(8); PG8_WAIT_L(0); PG8_BAR; PG8_MMA(0, 0, At, B0); PG8_MMA(0, 1, At, B1); PG8_BAR; PG8_SCHED;
;             PG8_LDA(At, 0, 1); PG8_STAGE(PG8_SB(0, 0), b2, voffB); PG8_STAGE(PG8_SB(0, 1), b2 + hstep, voffB); PG8_STAGE(PG8_SA(0, 0), a2, voffA);
;             PG8_WAIT_V(8); PG8_WAIT_L(0); PG8_BAR; PG8_MMA(1, 0, At, B0); PG8_MMA(1, 1, At, B1); PG8_BAR; PG8_SCHED;
	v_mfma_f32_16x16x32_bf16 v[128:131], v[184:187], v[216:219], v[128:131]
	v_mfma_f32_16x16x32_bf16 v[120:123], v[192:195], v[216:219], v[120:123]
	v_mfma_f32_16x16x32_bf16 v[112:115], v[184:187], v[224:227], v[112:115]
	v_mfma_f32_16x16x32_bf16 v[104:107], v[192:195], v[224:227], v[104:107]
	v_mfma_f32_16x16x32_bf16 v[96:99], v[184:187], v[232:235], v[96:99]
	v_mfma_f32_16x16x32_bf16 v[88:91], v[192:195], v[232:235], v[88:91]
	v_mfma_f32_16x16x32_bf16 v[80:83], v[184:187], v[240:243], v[80:83]
	v_mfma_f32_16x16x32_bf16 v[72:75], v[192:195], v[240:243], v[72:75]
	v_mfma_f32_16x16x32_bf16 v[128:131], v[188:191], v[220:223], v[128:131]
	v_mfma_f32_16x16x32_bf16 v[120:123], v[196:199], v[220:223], v[120:123]
	v_mfma_f32_16x16x32_bf16 v[112:115], v[188:191], v[228:231], v[112:115]
	v_mfma_f32_16x16x32_bf16 v[104:107], v[196:199], v[228:231], v[104:107]
	v_mfma_f32_16x16x32_bf16 v[96:99], v[188:191], v[236:239], v[96:99]
	v_mfma_f32_16x16x32_bf16 v[88:91], v[196:199], v[236:239], v[88:91]
	v_mfma_f32_16x16x32_bf16 v[80:83], v[188:191], v[244:247], v[80:83]
	v_mfma_f32_16x16x32_bf16 v[72:75], v[196:199], v[244:247], v[72:75]
	v_mfma_f32_16x16x32_bf16 v[124:127], v[200:203], v[216:219], v[124:127]
	v_mfma_f32_16x16x32_bf16 v[116:119], v[208:211], v[216:219], v[116:119]
	v_mfma_f32_16x16x32_bf16 v[108:111], v[200:203], v[224:227], v[108:111]
	v_mfma_f32_16x16x32_bf16 v[100:103], v[208:211], v[224:227], v[100:103]
	v_mfma_f32_16x16x32_bf16 v[92:95], v[200:203], v[232:235], v[92:95]
	v_mfma_f32_16x16x32_bf16 v[84:87], v[208:211], v[232:235], v[84:87]
	v_mfma_f32_16x16x32_bf16 v[76:79], v[200:203], v[240:243], v[76:79]
	v_mfma_f32_16x16x32_bf16 v[68:71], v[208:211], v[240:243], v[68:71]
	v_mfma_f32_16x16x32_bf16 v[124:127], v[204:207], v[220:223], v[124:127]
	v_mfma_f32_16x16x32_bf16 v[116:119], v[212:215], v[220:223], v[116:119]
	v_mfma_f32_16x16x32_bf16 v[108:111], v[204:207], v[228:231], v[108:111]
	v_mfma_f32_16x16x32_bf16 v[100:103], v[212:215], v[228:231], v[100:103]
	v_mfma_f32_16x16x32_bf16 v[92:95], v[204:207], v[236:239], v[92:95]
	v_mfma_f32_16x16x32_bf16 v[84:87], v[212:215], v[236:239], v[84:87]
	v_mfma_f32_16x16x32_bf16 v[76:79], v[204:207], v[244:247], v[76:79]
	v_mfma_f32_16x16x32_bf16 v[68:71], v[212:215], v[244:247], v[68:71]
	s_barrier
	s_setprio 0
	s_add_i32 s56, s56, s25
	s_mov_b32 m0, s56
	ds_read_b128 v[216:219], v155 offset:16384
	ds_read_b128 v[220:223], v155 offset:17408
	ds_read_b128 v[224:227], v155 offset:18432
	ds_read_b128 v[228:231], v155 offset:19456
	ds_read_b128 v[232:235], v155 offset:20480
	ds_read_b128 v[236:239], v155 offset:21504
	ds_read_b128 v[240:243], v155 offset:22528
	ds_read_b128 v[244:247], v155 offset:23552
	global_load_lds_dwordx4 v2, s[20:21]
	s_add_i32 m0, s56, 0x2000
	s_add_u32 s56, s20, 0x80000
	s_addc_u32 s57, s21, 0
	s_add_i32 s63, s63, s25
	global_load_lds_dwordx4 v0, s[20:21]
	s_mov_b32 m0, s63
	v_lshl_add_u64 v[252:253], s[22:23], 0, v[132:133]
	global_load_lds_dwordx4 v2, s[56:57]
	s_add_i32 m0, s63, 0x2000
	s_nop 0
	global_load_lds_dwordx4 v0, s[56:57]
	v_lshl_add_u64 v[250:251], s[22:23], 0, v[134:135]
	s_mov_b32 m0, s27
	s_nop 0
	global_load_lds_dwordx4 v[250:251], off
	s_mov_b32 m0, s28
	s_nop 0
	global_load_lds_dwordx4 v[252:253], off
	s_waitcnt vmcnt(8)
	s_waitcnt lgkmcnt(0)
	s_setprio 1
	s_barrier
	v_mfma_f32_16x16x32_bf16 v[64:67], v[184:187], v[216:219], v[64:67]
	v_mfma_f32_16x16x32_bf16 v[56:59], v[192:195], v[216:219], v[56:59]
	v_mfma_f32_16x16x32_bf16 v[48:51], v[184:187], v[224:227], v[48:51]
	v_mfma_f32_16x16x32_bf16 v[40:43], v[192:195], v[224:227], v[40:43]
	v_mfma_f32_16x16x32_bf16 v[32:35], v[184:187], v[232:235], v[32:35]
	v_mfma_f32_16x16x32_bf16 v[24:27], v[192:195], v[232:235], v[24:27]
	v_mfma_f32_16x16x32_bf16 v[16:19], v[184:187], v[240:243], v[16:19]
	v_mfma_f32_16x16x32_bf16 v[8:11], v[192:195], v[240:243], v[8:11]
	v_mfma_f32_16x16x32_bf16 v[64:67], v[188:191], v[220:223], v[64:67]
	v_mfma_f32_16x16x32_bf16 v[56:59], v[196:199], v[220:223], v[56:59]
	v_mfma_f32_16x16x32_bf16 v[48:51], v[188:191], v[228:231], v[48:51]
	v_mfma_f32_16x16x32_bf16 v[40:43], v[196:199], v[228:231], v[40:43]
	v_mfma_f32_16x16x32_bf16 v[32:35], v[188:191], v[236:239], v[32:35]
	v_mfma_f32_16x16x32_bf16 v[24:27], v[196:199], v[236:239], v[24:27]
	v_mfma_f32_16x16x32_bf16 v[16:19], v[188:191], v[244:247], v[16:19]
	v_mfma_f32_16x16x32_bf16 v[8:11], v[196:199], v[244:247], v[8:11]
	v_mfma_f32_16x16x32_bf16 v[60:63], v[200:203], v[216:219], v[60:63]
	v_mfma_f32_16x16x32_bf16 v[52:55], v[208:211], v[216:219], v[52:55]
	v_mfma_f32_16x16x32_bf16 v[44:47], v[200:203], v[224:227], v[44:47]
	v_mfma_f32_16x16x32_bf16 v[36:39], v[208:211], v[224:227], v[36:39]
	v_mfma_f32_16x16x32_bf16 v[28:31], v[200:203], v[232:235], v[28:31]
	v_mfma_f32_16x16x32_bf16 v[20:23], v[208:211], v[232:235], v[20:23]
	v_mfma_f32_16x16x32_bf16 v[12:15], v[200:203], v[240:243], v[12:15]
	v_mfma_f32_16x16x32_bf16 v[4:7], v[208:211], v[240:243], v[4:7]
	v_mfma_f32_16x16x32_bf16 v[60:63], v[204:207], v[220:223], v[60:63]
	v_mfma_f32_16x16x32_bf16 v[52:55], v[212:215], v[220:223], v[52:55]
	v_mfma_f32_16x16x32_bf16 v[44:47], v[204:207], v[228:231], v[44:47]
	v_mfma_f32_16x16x32_bf16 v[36:39], v[212:215], v[228:231], v[36:39]
	v_mfma_f32_16x16x32_bf16 v[28:31], v[204:207], v[236:239], v[28:31]
	v_mfma_f32_16x16x32_bf16 v[20:23], v[212:215], v[236:239], v[20:23]
	v_mfma_f32_16x16x32_bf16 v[12:15], v[204:207], v[244:247], v[12:15]
	v_mfma_f32_16x16x32_bf16 v[4:7], v[212:215], v[244:247], v[4:7]
	s_barrier
; #define PG8_STAGE(bufoff, gbase, voff) do { _Pragma("unroll") for (int _i = 0; _i < 2; ++_i) \
;         __builtin_amdgcn_global_load_lds((const unsigned*)((const char*)(gbase) + (voff)[_i]), (PG8_LAS unsigned*)(lds + (bufoff) + ldsw + _i * 8192), 16, 0, 0); } while (0)
; #define PG8_LDA(dst, b, h) do { _Pragma("unroll") for (int m = 0; m < 4; ++m) _Pragma("unroll") for (int k = 0; k < 2; ++k) dst[m][k] = *(const PG8_LAS bf16x8*)(lds + PG8_SA(b, h) + aoff + m * 2048 + k * 1024); } while (0)
; #define PG8_LDB(dst, b, h) do { _Pragma("unroll") for (int n = 0; n < 2; ++n) _Pragma("unroll") for (int k = 0; k < 2; ++k) dst[n][k] = *(const PG8_LAS bf16x8*)(lds + PG8_SB(b, h) + boff + n * 2048 + k * 1024); } while (0)
; #define PG8_MMA(ai, bj, At, Bt) do { __builtin_amdgcn_s_setprio(1); _Pragma("unroll") for (int m = 0; m < 4; ++m) _Pragma("unroll") for (int n = 0; n < 2; ++n) _Pragma("unroll") for (int k = 0; k < 2; ++k) \
;         acc[ai][bj][m][n] = __builtin_amdgcn_mfma_f32_16x16x32_bf16(Bt[n][k], At[m][k], acc[ai][bj][m][n], 0, 0, 0); __builtin_amdgcn_s_setprio(0); } while (0)
; #define PG8_WAIT_V(n) asm volatile("s_waitcnt vmcnt(" #n ")" ::: "memory")
; #define PG8_WAIT_L(n) asm volatile("s_waitcnt lgkmcnt(" #n ")" ::: "memory")
; #define PG8_BAR __builtin_amdgcn_s_barrier()
; #define PG8_SCHED __builtin_amdgcn_sched_barrier(0)
; template <class Epi, class Sched, bool ALIGN_EPI = false, bool SP2 = false>
; __device__ __forceinline__ void gemm_phase(PG8_LAS unsigned char* lds, const Gemm g, const Sched& S, const Epi& E) {
;     ...
;             PG8_LDB(B0, 1, 0); PG8_LDB(B1, 1, 1); PG8_SCHED; PG8_LDA(At, 1, 0); PG8_STAGE(PG8_SA(0, 1), a2 + hstep, voffA);
;             PG8_WAIT_V(8); PG8_WAIT_L(0); PG8_BAR; PG8_MMA(0, 0, At, B0); PG8_MMA(0, 1, At, B1); PG8_BAR; PG8_SCHED;
;             PG8_LDA(At, 1, 1); PG8_STAGE(PG8_SB(1, 0), b3, voffB); PG8_STAGE(PG8_SB(1, 1), b3 + hstep, voffB); PG8_STAGE(PG8_SA(1, 0), a3, voffA);
;             PG8_WAIT_V(8); PG8_WAIT_L(0); PG8_BAR; PG8_MMA(1, 0, At, B0); PG8_MMA(1, 1, At, B1); PG8_BAR; PG8_SCHED;
;     ...
;         if constexpr (ALIGN_EPI) { if (wr == 0) PG8_BAR; }
	s_setprio 0
	s_add_i32 s56, 0, 0x18000
	v_add_u32_e32 v161, s56, v153
	s_add_i32 s57, 0, 0x1c000
	ds_read_b128 v[184:187], v161
	ds_read_b128 v[188:191], v161 offset:1024
	ds_read_b128 v[192:195], v161 offset:2048
	ds_read_b128 v[196:199], v161 offset:3072
	v_add_u32_e32 v161, s57, v153
	ds_read_b128 v[200:203], v161
	ds_read_b128 v[204:207], v161 offset:1024
	ds_read_b128 v[208:211], v161 offset:2048
	ds_read_b128 v[212:215], v161 offset:3072
	s_add_u32 s22, s22, 0x80000
	s_addc_u32 s23, s23, 0
	s_mov_b32 m0, s29
	ds_read_b128 v[216:219], v155 offset:32768
	ds_read_b128 v[220:223], v155 offset:33792
	ds_read_b128 v[224:227], v155 offset:34816
	ds_read_b128 v[228:231], v155 offset:35840
	ds_read_b128 v[232:235], v155 offset:36864
	ds_read_b128 v[236:239], v155 offset:37888
	ds_read_b128 v[240:243], v155 offset:38912
	ds_read_b128 v[244:247], v155 offset:39936
	global_load_lds_dwordx4 v134, s[22:23]
	s_mov_b32 m0, s30
	s_nop 0
	global_load_lds_dwordx4 v132, s[22:23]
	s_waitcnt vmcnt(8)
	s_waitcnt lgkmcnt(0)
	s_setprio 1
	s_barrier
	v_mfma_f32_16x16x32_bf16 v[128:131], v[184:187], v[216:219], v[128:131]
	v_mfma_f32_16x16x32_bf16 v[120:123], v[192:195], v[216:219], v[120:123]
	v_mfma_f32_16x16x32_bf16 v[112:115], v[184:187], v[224:227], v[112:115]
	v_mfma_f32_16x16x32_bf16 v[104:107], v[192:195], v[224:227], v[104:107]
	v_mfma_f32_16x16x32_bf16 v[96:99], v[184:187], v[232:235], v[96:99]
	v_mfma_f32_16x16x32_bf16 v[88:91], v[192:195], v[232:235], v[88:91]
	v_mfma_f32_16x16x32_bf16 v[80:83], v[184:187], v[240:243], v[80:83]
	v_mfma_f32_16x16x32_bf16 v[72:75], v[192:195], v[240:243], v[72:75]
	v_mfma_f32_16x16x32_bf16 v[128:131], v[188:191], v[220:223], v[128:131]
	v_mfma_f32_16x16x32_bf16 v[120:123], v[196:199], v[220:223], v[120:123]
	v_mfma_f32_16x16x32_bf16 v[112:115], v[188:191], v[228:231], v[112:115]
	v_mfma_f32_16x16x32_bf16 v[104:107], v[196:199], v[228:231], v[104:107]
	v_mfma_f32_16x16x32_bf16 v[96:99], v[188:191], v[236:239], v[96:99]
	v_mfma_f32_16x16x32_bf16 v[88:91], v[196:199], v[236:239], v[88:91]
	v_mfma_f32_16x16x32_bf16 v[80:83], v[188:191], v[244:247], v[80:83]
	v_mfma_f32_16x16x32_bf16 v[72:75], v[196:199], v[244:247], v[72:75]
	v_mfma_f32_16x16x32_bf16 v[124:127], v[200:203], v[216:219], v[124:127]
	v_mfma_f32_16x16x32_bf16 v[116:119], v[208:211], v[216:219], v[116:119]
	v_mfma_f32_16x16x32_bf16 v[108:111], v[200:203], v[224:227], v[108:111]
	v_mfma_f32_16x16x32_bf16 v[100:103], v[208:211], v[224:227], v[100:103]
	v_mfma_f32_16x16x32_bf16 v[92:95], v[200:203], v[232:235], v[92:95]
	v_mfma_f32_16x16x32_bf16 v[84:87], v[208:211], v[232:235], v[84:87]
	v_mfma_f32_16x16x32_bf16 v[76:79], v[200:203], v[240:243], v[76:79]
	v_mfma_f32_16x16x32_bf16 v[68:71], v[208:211], v[240:243], v[68:71]
	v_mfma_f32_16x16x32_bf16 v[124:127], v[204:207], v[220:223], v[124:127]
	v_mfma_f32_16x16x32_bf16 v[116:119], v[212:215], v[220:223], v[116:119]
	v_mfma_f32_16x16x32_bf16 v[108:111], v[204:207], v[228:231], v[108:111]
	v_mfma_f32_16x16x32_bf16 v[100:103], v[212:215], v[228:231], v[100:103]
	v_mfma_f32_16x16x32_bf16 v[92:95], v[204:207], v[236:239], v[92:95]
	v_mfma_f32_16x16x32_bf16 v[84:87], v[212:215], v[236:239], v[84:87]
	v_mfma_f32_16x16x32_bf16 v[76:79], v[204:207], v[244:247], v[76:79]
	v_mfma_f32_16x16x32_bf16 v[68:71], v[212:215], v[244:247], v[68:71]
	s_barrier
	s_setprio 0
	s_add_i32 s22, s56, s25
	s_mov_b32 m0, s22
	ds_read_b128 v[216:219], v155 offset:49152
	ds_read_b128 v[220:223], v155 offset:50176
	ds_read_b128 v[224:227], v155 offset:51200
	ds_read_b128 v[228:231], v155 offset:52224
	ds_read_b128 v[232:235], v155 offset:53248
	ds_read_b128 v[236:239], v155 offset:54272
	ds_read_b128 v[240:243], v155 offset:55296
	ds_read_b128 v[244:247], v155 offset:56320
	s_add_u32 vcc_lo, s20, 0x80
	s_addc_u32 vcc_hi, s21, 0
	global_load_lds_dwordx4 v2, vcc
	s_add_i32 m0, s22, 0x2000
	s_add_u32 s20, s20, 0x80080
	s_addc_u32 s21, s21, 0
	s_add_i32 s22, s57, s25
	s_add_u32 vcc_lo, s20, 0xfff80000
	s_addc_u32 vcc_hi, s21, -1
	global_load_lds_dwordx4 v0, vcc
	s_mov_b32 m0, s22
	s_nop 0
	global_load_lds_dwordx4 v2, s[20:21]
	s_add_i32 m0, s22, 0x2000
	s_nop 0
	global_load_lds_dwordx4 v0, s[20:21]
	v_lshl_add_u64 v[150:151], v[250:251], 0, s[36:37]
	s_mov_b32 m0, s31
	s_nop 0
	global_load_lds_dwordx4 v[150:151], off
	v_lshl_add_u64 v[150:151], v[252:253], 0, s[36:37]
	s_mov_b32 m0, s34
	s_nop 0
	global_load_lds_dwordx4 v[150:151], off
	s_waitcnt vmcnt(8)
	s_waitcnt lgkmcnt(0)
	s_setprio 1
	s_barrier
	v_mfma_f32_16x16x32_bf16 v[64:67], v[184:187], v[216:219], v[64:67]
	v_mfma_f32_16x16x32_bf16 v[56:59], v[192:195], v[216:219], v[56:59]
	v_mfma_f32_16x16x32_bf16 v[48:51], v[184:187], v[224:227], v[48:51]
	v_mfma_f32_16x16x32_bf16 v[40:43], v[192:195], v[224:227], v[40:43]
	v_mfma_f32_16x16x32_bf16 v[32:35], v[184:187], v[232:235], v[32:35]
	v_mfma_f32_16x16x32_bf16 v[24:27], v[192:195], v[232:235], v[24:27]
	v_mfma_f32_16x16x32_bf16 v[16:19], v[184:187], v[240:243], v[16:19]
	v_mfma_f32_16x16x32_bf16 v[8:11], v[192:195], v[240:243], v[8:11]
	v_mfma_f32_16x16x32_bf16 v[64:67], v[188:191], v[220:223], v[64:67]
	v_mfma_f32_16x16x32_bf16 v[56:59], v[196:199], v[220:223], v[56:59]
	v_mfma_f32_16x16x32_bf16 v[48:51], v[188:191], v[228:231], v[48:51]
	v_mfma_f32_16x16x32_bf16 v[40:43], v[196:199], v[228:231], v[40:43]
	v_mfma_f32_16x16x32_bf16 v[32:35], v[188:191], v[236:239], v[32:35]
	v_mfma_f32_16x16x32_bf16 v[24:27], v[196:199], v[236:239], v[24:27]
	v_mfma_f32_16x16x32_bf16 v[16:19], v[188:191], v[244:247], v[16:19]
	v_mfma_f32_16x16x32_bf16 v[8:11], v[196:199], v[244:247], v[8:11]
	v_mfma_f32_16x16x32_bf16 v[60:63], v[200:203], v[216:219], v[60:63]
	v_mfma_f32_16x16x32_bf16 v[52:55], v[208:211], v[216:219], v[52:55]
	v_mfma_f32_16x16x32_bf16 v[44:47], v[200:203], v[224:227], v[44:47]
	v_mfma_f32_16x16x32_bf16 v[36:39], v[208:211], v[224:227], v[36:39]
	v_mfma_f32_16x16x32_bf16 v[28:31], v[200:203], v[232:235], v[28:31]
	v_mfma_f32_16x16x32_bf16 v[20:23], v[208:211], v[232:235], v[20:23]
	v_mfma_f32_16x16x32_bf16 v[12:15], v[200:203], v[240:243], v[12:15]
	v_mfma_f32_16x16x32_bf16 v[4:7], v[208:211], v[240:243], v[4:7]
	v_mfma_f32_16x16x32_bf16 v[60:63], v[204:207], v[220:223], v[60:63]
	v_mfma_f32_16x16x32_bf16 v[52:55], v[212:215], v[220:223], v[52:55]
	v_mfma_f32_16x16x32_bf16 v[44:47], v[204:207], v[228:231], v[44:47]
	v_mfma_f32_16x16x32_bf16 v[36:39], v[212:215], v[228:231], v[36:39]
	v_mfma_f32_16x16x32_bf16 v[28:31], v[204:207], v[236:239], v[28:31]
	v_mfma_f32_16x16x32_bf16 v[20:23], v[212:215], v[236:239], v[20:23]
	v_mfma_f32_16x16x32_bf16 v[12:15], v[204:207], v[244:247], v[12:15]
	v_mfma_f32_16x16x32_bf16 v[4:7], v[212:215], v[244:247], v[4:7]
	s_barrier
	s_setprio 0
	s_add_i32 s51, s51, 2
	s_add_u32 s18, s18, 0x100
	s_addc_u32 s19, s19, 0
	s_add_u32 s45, s45, 0x100
	s_addc_u32 s50, s50, 0
	s_cmp_gt_u32 s51, 29
	s_cbranch_scc0 .LBB0_85
	s_and_b64 vcc, exec, s[6:7]
	s_cbranch_vccz .LBB0_88
	s_barrier

; #define PG8_STAGE(bufoff, gbase, voff) do { _Pragma("unroll") for (int _i = 0; _i < 2; ++_i) \
;         __builtin_amdgcn_global_load_lds((const unsigned*)((const char*)(gbase) + (voff)[_i]), (PG8_LAS unsigned*)(lds + (bufoff) + ldsw + _i * 8192), 16, 0, 0); } while (0)
; #define PG8_LDA(dst, b, h) do { _Pragma("unroll") for (int m = 0; m < 4; ++m) _Pragma("unroll") for (int k = 0; k < 2; ++k) dst[m][k] = *(const PG8_LAS bf16x8*)(lds + PG8_SA(b, h) + aoff + m * 2048 + k * 1024); } while (0)
; #define PG8_LDB(dst, b, h) do { _Pragma("unroll") for (int n = 0; n < 2; ++n) _Pragma("unroll") for (int k = 0; k < 2; ++k) dst[n][k] = *(const PG8_LAS bf16x8*)(lds + PG8_SB(b, h) + boff + n * 2048 + k * 1024); } while (0)
; #define PG8_MMA(ai, bj, At, Bt) do { __builtin_amdgcn_s_setprio(1); _Pragma("unroll") for (int m = 0; m < 4; ++m) _Pragma("unroll") for (int n = 0; n < 2; ++n) _Pragma("unroll") for (int k = 0; k < 2; ++k) \
;         acc[ai][bj][m][n] = __builtin_amdgcn_mfma_f32_16x16x32_bf16(Bt[n][k], At[m][k], acc[ai][bj][m][n], 0, 0, 0); __builtin_amdgcn_s_setprio(0); } while (0)
; #define PG8_WAIT_V(n) asm volatile("s_waitcnt vmcnt(" #n ")" ::: "memory")
; #define PG8_WAIT_L(n) asm volatile("s_waitcnt lgkmcnt(" #n ")" ::: "memory")
; template <class Epi, class Sched, bool ALIGN_EPI = false, bool SP2 = false>
; __device__ __forceinline__ void gemm_phase(PG8_LAS unsigned char* lds, const Gemm g, const Sched& S, const Epi& E) {
;     ...
;             const bool last = (t == nt - 2);
;             const char* a1 = cA + (size_t)(t + 1) * kstep;
;             const char* a2 = last ? nA : cA + (size_t)(t + 2) * kstep; const char* b2 = last ? nB : cB + (size_t)(t + 2) * kstep;
;             const char* a3 = a2 + kstep; const char* b3 = b2 + kstep;
;             if (last && has_next) S.a_ready(nxt);
;             if constexpr (SP2) {
;             PG8_LDB(B0, 0, 0); PG8_LDB(B1, 0, 1); PG8_SCHED; PG8_LDA(At, 0, 0); PG8_STAGE(PG8_SA(1, 1), a1 + hstep, voffA);
;             PG8_WAIT_V(8); PG8_WAIT_L(0); PG8_BAR; PG8_MMA(0, 0, At, B0); PG8_MMA(0, 1, At, B1); PG8_BAR; PG8_SCHED;
;             PG8_LDA(At, 0, 1); PG8_STAGE(PG8_SB(0, 0), b2, voffB); PG8_STAGE(PG8_SB(0, 1), b2 + hstep, voffB); PG8_STAGE(PG8_SA(0, 0), a2, voffA);
;             PG8_WAIT_V(8); PG8_WAIT_L(0); PG8_BAR; PG8_MMA(1, 0, At, B0); PG8_MMA(1, 1, At, B1); PG8_BAR; PG8_SCHED;
.LBB0_166:
	s_add_u32 s51, s16, 0x100
	s_addc_u32 s56, s17, 0
	s_mov_b32 s57, -2
	s_waitcnt lgkmcnt(0)
	s_add_u32 s16, s14, 0x100
	s_addc_u32 s17, s15, 0
	s_add_i32 s63, 0, 0x10000
	s_cmpk_eq_i32 s57, 0x54
	s_cselect_b32 s21, s7, s17
	s_cselect_b32 s20, s6, s16
	s_cselect_b32 s19, s13, s56
	s_cselect_b32 s18, s12, s51
	s_add_i32 s64, 0, 0x14000
	v_add_u32_e32 v162, s63, v185
	v_add_u32_e32 v166, s64, v185
	ds_read_b128 v[132:135], v162
	ds_read_b128 v[136:139], v162 offset:1024
	ds_read_b128 v[158:161], v162 offset:2048
	ds_read_b128 v[162:165], v162 offset:3072
	ds_read_b128 v[188:191], v166
	ds_read_b128 v[192:195], v166 offset:1024
	ds_read_b128 v[196:199], v166 offset:2048
	ds_read_b128 v[200:203], v166 offset:3072
	s_add_i32 m0, s26, 0xc000
	ds_read_b128 v[204:207], v187
	ds_read_b128 v[208:211], v187 offset:1024
	ds_read_b128 v[212:215], v187 offset:2048
	ds_read_b128 v[216:219], v187 offset:3072
	ds_read_b128 v[220:223], v187 offset:4096
	ds_read_b128 v[224:227], v187 offset:5120
	ds_read_b128 v[228:231], v187 offset:6144
	ds_read_b128 v[232:235], v187 offset:7168
	global_load_lds_dwordx4 v154, s[14:15]
	s_add_i32 m0, s26, 0xe000
	s_nop 0
	global_load_lds_dwordx4 v156, s[14:15]
	s_waitcnt vmcnt(8)
	s_waitcnt lgkmcnt(0)
	s_setprio 1
	s_barrier
	v_mfma_f32_16x16x32_bf16 v[128:131], v[132:135], v[204:207], 0
	v_mfma_f32_16x16x32_bf16 v[124:127], v[158:161], v[204:207], 0
	v_mfma_f32_16x16x32_bf16 v[112:115], v[132:135], v[212:215], 0
	v_mfma_f32_16x16x32_bf16 v[108:111], v[158:161], v[212:215], 0
	v_mfma_f32_16x16x32_bf16 v[96:99], v[132:135], v[220:223], 0
	v_mfma_f32_16x16x32_bf16 v[92:95], v[158:161], v[220:223], 0
	v_mfma_f32_16x16x32_bf16 v[80:83], v[132:135], v[228:231], 0
	v_mfma_f32_16x16x32_bf16 v[76:79], v[158:161], v[228:231], 0
	v_mfma_f32_16x16x32_bf16 v[128:131], v[136:139], v[208:211], v[128:131]
	v_mfma_f32_16x16x32_bf16 v[124:127], v[162:165], v[208:211], v[124:127]
	v_mfma_f32_16x16x32_bf16 v[112:115], v[136:139], v[216:219], v[112:115]
	v_mfma_f32_16x16x32_bf16 v[108:111], v[162:165], v[216:219], v[108:111]
	v_mfma_f32_16x16x32_bf16 v[96:99], v[136:139], v[224:227], v[96:99]
	v_mfma_f32_16x16x32_bf16 v[92:95], v[162:165], v[224:227], v[92:95]
	v_mfma_f32_16x16x32_bf16 v[80:83], v[136:139], v[232:235], v[80:83]
	v_mfma_f32_16x16x32_bf16 v[76:79], v[162:165], v[232:235], v[76:79]
	v_mfma_f32_16x16x32_bf16 v[120:123], v[188:191], v[204:207], 0
	v_mfma_f32_16x16x32_bf16 v[116:119], v[196:199], v[204:207], 0
	v_mfma_f32_16x16x32_bf16 v[104:107], v[188:191], v[212:215], 0
	v_mfma_f32_16x16x32_bf16 v[100:103], v[196:199], v[212:215], 0
	v_mfma_f32_16x16x32_bf16 v[88:91], v[188:191], v[220:223], 0
	v_mfma_f32_16x16x32_bf16 v[84:87], v[196:199], v[220:223], 0
	v_mfma_f32_16x16x32_bf16 v[72:75], v[188:191], v[228:231], 0
	v_mfma_f32_16x16x32_bf16 v[68:71], v[196:199], v[228:231], 0
	v_mfma_f32_16x16x32_bf16 v[120:123], v[192:195], v[208:211], v[120:123]
	v_mfma_f32_16x16x32_bf16 v[116:119], v[200:203], v[208:211], v[116:119]
	v_mfma_f32_16x16x32_bf16 v[104:107], v[192:195], v[216:219], v[104:107]
	v_mfma_f32_16x16x32_bf16 v[100:103], v[200:203], v[216:219], v[100:103]
	v_mfma_f32_16x16x32_bf16 v[88:91], v[192:195], v[224:227], v[88:91]
	v_mfma_f32_16x16x32_bf16 v[84:87], v[200:203], v[224:227], v[84:87]
	v_mfma_f32_16x16x32_bf16 v[72:75], v[192:195], v[232:235], v[72:75]
	v_mfma_f32_16x16x32_bf16 v[68:71], v[200:203], v[232:235], v[68:71]
	s_barrier
	s_setprio 0
	s_add_i32 s14, s63, s25
	s_mov_b32 m0, s14
	ds_read_b128 v[204:207], v187 offset:16384
	ds_read_b128 v[208:211], v187 offset:17408
	ds_read_b128 v[212:215], v187 offset:18432
	ds_read_b128 v[216:219], v187 offset:19456
	ds_read_b128 v[220:223], v187 offset:20480
	ds_read_b128 v[224:227], v187 offset:21504
	ds_read_b128 v[228:231], v187 offset:22528
	ds_read_b128 v[232:235], v187 offset:23552
	global_load_lds_dwordx4 v2, s[18:19]
	s_add_i32 m0, s14, 0x2000
	s_add_u32 s14, s18, 0x160000
	v_lshl_add_u64 v[236:237], s[18:19], 0, v[152:153]
	s_addc_u32 s15, s19, 0
	s_add_i32 s63, s64, s25
	global_load_lds_dwordx4 v[236:237], off
	s_mov_b32 m0, s63
	global_load_lds_dwordx4 v2, s[14:15]
	s_add_i32 m0, s63, 0x2000
	s_nop 0
	global_load_lds_dwordx4 v152, s[14:15]
	s_mov_b32 m0, s26
	s_nop 0
	global_load_lds_dwordx4 v0, s[20:21]
	s_mov_b32 m0, s27
	s_nop 0
	global_load_lds_dwordx4 v150, s[20:21]
	s_waitcnt vmcnt(8)
	s_waitcnt lgkmcnt(0)
	s_setprio 1
	s_barrier
	v_mfma_f32_16x16x32_bf16 v[64:67], v[132:135], v[204:207], 0
	v_mfma_f32_16x16x32_bf16 v[60:63], v[158:161], v[204:207], 0
	v_mfma_f32_16x16x32_bf16 v[48:51], v[132:135], v[212:215], 0
	v_mfma_f32_16x16x32_bf16 v[44:47], v[158:161], v[212:215], 0
	v_mfma_f32_16x16x32_bf16 v[32:35], v[132:135], v[220:223], 0
	v_mfma_f32_16x16x32_bf16 v[28:31], v[158:161], v[220:223], 0
	v_mfma_f32_16x16x32_bf16 v[16:19], v[132:135], v[228:231], 0
	v_mfma_f32_16x16x32_bf16 v[12:15], v[158:161], v[228:231], 0
	v_mfma_f32_16x16x32_bf16 v[64:67], v[136:139], v[208:211], v[64:67]
	v_mfma_f32_16x16x32_bf16 v[60:63], v[162:165], v[208:211], v[60:63]
	v_mfma_f32_16x16x32_bf16 v[48:51], v[136:139], v[216:219], v[48:51]
	v_mfma_f32_16x16x32_bf16 v[44:47], v[162:165], v[216:219], v[44:47]
	v_mfma_f32_16x16x32_bf16 v[32:35], v[136:139], v[224:227], v[32:35]
	v_mfma_f32_16x16x32_bf16 v[28:31], v[162:165], v[224:227], v[28:31]
	v_mfma_f32_16x16x32_bf16 v[16:19], v[136:139], v[232:235], v[16:19]
	v_mfma_f32_16x16x32_bf16 v[12:15], v[162:165], v[232:235], v[12:15]
	v_mfma_f32_16x16x32_bf16 v[56:59], v[188:191], v[204:207], 0
	v_mfma_f32_16x16x32_bf16 v[52:55], v[196:199], v[204:207], 0
	v_mfma_f32_16x16x32_bf16 v[40:43], v[188:191], v[212:215], 0
	v_mfma_f32_16x16x32_bf16 v[36:39], v[196:199], v[212:215], 0
	v_mfma_f32_16x16x32_bf16 v[24:27], v[188:191], v[220:223], 0
	v_mfma_f32_16x16x32_bf16 v[20:23], v[196:199], v[220:223], 0
	v_mfma_f32_16x16x32_bf16 v[8:11], v[188:191], v[228:231], 0
	v_mfma_f32_16x16x32_bf16 v[4:7], v[196:199], v[228:231], 0
	v_mfma_f32_16x16x32_bf16 v[56:59], v[192:195], v[208:211], v[56:59]
	v_mfma_f32_16x16x32_bf16 v[52:55], v[200:203], v[208:211], v[52:55]
	v_mfma_f32_16x16x32_bf16 v[40:43], v[192:195], v[216:219], v[40:43]
	v_mfma_f32_16x16x32_bf16 v[36:39], v[200:203], v[216:219], v[36:39]
	v_mfma_f32_16x16x32_bf16 v[24:27], v[192:195], v[224:227], v[24:27]
	v_mfma_f32_16x16x32_bf16 v[20:23], v[200:203], v[224:227], v[20:23]
	v_mfma_f32_16x16x32_bf16 v[8:11], v[192:195], v[232:235], v[8:11]
	v_mfma_f32_16x16x32_bf16 v[4:7], v[200:203], v[232:235], v[4:7]
	s_barrier
; #define PG8_STAGE(bufoff, gbase, voff) do { _Pragma("unroll") for (int _i = 0; _i < 2; ++_i) \
;         __builtin_amdgcn_global_load_lds((const unsigned*)((const char*)(gbase) + (voff)[_i]), (PG8_LAS unsigned*)(lds + (bufoff) + ldsw + _i * 8192), 16, 0, 0); } while (0)
; #define PG8_LDA(dst, b, h) do { _Pragma("unroll") for (int m = 0; m < 4; ++m) _Pragma("unroll") for (int k = 0; k < 2; ++k) dst[m][k] = *(const PG8_LAS bf16x8*)(lds + PG8_SA(b, h) + aoff + m * 2048 + k * 1024); } while (0)
; #define PG8_LDB(dst, b, h) do { _Pragma("unroll") for (int n = 0; n < 2; ++n) _Pragma("unroll") for (int k = 0; k < 2; ++k) dst[n][k] = *(const PG8_LAS bf16x8*)(lds + PG8_SB(b, h) + boff + n * 2048 + k * 1024); } while (0)
; #define PG8_MMA(ai, bj, At, Bt) do { __builtin_amdgcn_s_setprio(1); _Pragma("unroll") for (int m = 0; m < 4; ++m) _Pragma("unroll") for (int n = 0; n < 2; ++n) _Pragma("unroll") for (int k = 0; k < 2; ++k) \
;         acc[ai][bj][m][n] = __builtin_amdgcn_mfma_f32_16x16x32_bf16(Bt[n][k], At[m][k], acc[ai][bj][m][n], 0, 0, 0); __builtin_amdgcn_s_setprio(0); } while (0)
; #define PG8_WAIT_V(n) asm volatile("s_waitcnt vmcnt(" #n ")" ::: "memory")
; #define PG8_WAIT_L(n) asm volatile("s_waitcnt lgkmcnt(" #n ")" ::: "memory")
; #define PG8_BAR __builtin_amdgcn_s_barrier()
; #define PG8_SCHED __builtin_amdgcn_sched_barrier(0)
; template <class Epi, class Sched, bool ALIGN_EPI = false, bool SP2 = false>
; __device__ __forceinline__ void gemm_phase(PG8_LAS unsigned char* lds, const Gemm g, const Sched& S, const Epi& E) {
;     ...
;             PG8_LDB(B0, 1, 0); PG8_LDB(B1, 1, 1); PG8_SCHED; PG8_LDA(At, 1, 0); PG8_STAGE(PG8_SA(0, 1), a2 + hstep, voffA);
;             PG8_WAIT_V(8); PG8_WAIT_L(0); PG8_BAR; PG8_MMA(0, 0, At, B0); PG8_MMA(0, 1, At, B1); PG8_BAR; PG8_SCHED;
;             PG8_LDA(At, 1, 1); PG8_STAGE(PG8_SB(1, 0), b3, voffB); PG8_STAGE(PG8_SB(1, 1), b3 + hstep, voffB); PG8_STAGE(PG8_SA(1, 0), a3, voffA);
;             PG8_WAIT_V(8); PG8_WAIT_L(0); PG8_BAR; PG8_MMA(1, 0, At, B0); PG8_MMA(1, 1, At, B1); PG8_BAR; PG8_SCHED;
	s_setprio 0
	s_add_i32 s63, 0, 0x18000
	s_add_i32 s64, 0, 0x1c000
	v_add_u32_e32 v162, s63, v185
	v_add_u32_e32 v200, s64, v185
	ds_read_b128 v[132:135], v162
	ds_read_b128 v[136:139], v162 offset:1024
	ds_read_b128 v[158:161], v162 offset:2048
	ds_read_b128 v[162:165], v162 offset:3072
	ds_read_b128 v[188:191], v200
	ds_read_b128 v[192:195], v200 offset:1024
	ds_read_b128 v[196:199], v200 offset:2048
	ds_read_b128 v[200:203], v200 offset:3072
	s_add_u32 s14, s20, 0x160000
	s_addc_u32 s15, s21, 0
	s_mov_b32 m0, s28
	ds_read_b128 v[204:207], v187 offset:32768
	ds_read_b128 v[208:211], v187 offset:33792
	ds_read_b128 v[212:215], v187 offset:34816
	ds_read_b128 v[216:219], v187 offset:35840
	ds_read_b128 v[220:223], v187 offset:36864
	ds_read_b128 v[224:227], v187 offset:37888
	ds_read_b128 v[228:231], v187 offset:38912
	ds_read_b128 v[232:235], v187 offset:39936
	global_load_lds_dwordx4 v0, s[14:15]
	s_mov_b32 m0, s29
	s_nop 0
	global_load_lds_dwordx4 v150, s[14:15]
	s_waitcnt vmcnt(8)
	s_waitcnt lgkmcnt(0)
	s_setprio 1
	s_barrier
	v_mfma_f32_16x16x32_bf16 v[128:131], v[132:135], v[204:207], v[128:131]
	v_mfma_f32_16x16x32_bf16 v[124:127], v[158:161], v[204:207], v[124:127]
	v_mfma_f32_16x16x32_bf16 v[112:115], v[132:135], v[212:215], v[112:115]
	v_mfma_f32_16x16x32_bf16 v[108:111], v[158:161], v[212:215], v[108:111]
	v_mfma_f32_16x16x32_bf16 v[96:99], v[132:135], v[220:223], v[96:99]
	v_mfma_f32_16x16x32_bf16 v[92:95], v[158:161], v[220:223], v[92:95]
	v_mfma_f32_16x16x32_bf16 v[80:83], v[132:135], v[228:231], v[80:83]
	v_mfma_f32_16x16x32_bf16 v[76:79], v[158:161], v[228:231], v[76:79]
	v_mfma_f32_16x16x32_bf16 v[128:131], v[136:139], v[208:211], v[128:131]
	v_mfma_f32_16x16x32_bf16 v[124:127], v[162:165], v[208:211], v[124:127]
	v_mfma_f32_16x16x32_bf16 v[112:115], v[136:139], v[216:219], v[112:115]
	v_mfma_f32_16x16x32_bf16 v[108:111], v[162:165], v[216:219], v[108:111]
	v_mfma_f32_16x16x32_bf16 v[96:99], v[136:139], v[224:227], v[96:99]
	v_mfma_f32_16x16x32_bf16 v[92:95], v[162:165], v[224:227], v[92:95]
	v_mfma_f32_16x16x32_bf16 v[80:83], v[136:139], v[232:235], v[80:83]
	v_mfma_f32_16x16x32_bf16 v[76:79], v[162:165], v[232:235], v[76:79]
	v_mfma_f32_16x16x32_bf16 v[120:123], v[188:191], v[204:207], v[120:123]
	v_mfma_f32_16x16x32_bf16 v[116:119], v[196:199], v[204:207], v[116:119]
	v_mfma_f32_16x16x32_bf16 v[104:107], v[188:191], v[212:215], v[104:107]
	v_mfma_f32_16x16x32_bf16 v[100:103], v[196:199], v[212:215], v[100:103]
	v_mfma_f32_16x16x32_bf16 v[88:91], v[188:191], v[220:223], v[88:91]
	v_mfma_f32_16x16x32_bf16 v[84:87], v[196:199], v[220:223], v[84:87]
	v_mfma_f32_16x16x32_bf16 v[72:75], v[188:191], v[228:231], v[72:75]
	v_mfma_f32_16x16x32_bf16 v[68:71], v[196:199], v[228:231], v[68:71]
	v_mfma_f32_16x16x32_bf16 v[120:123], v[192:195], v[208:211], v[120:123]
	v_mfma_f32_16x16x32_bf16 v[116:119], v[200:203], v[208:211], v[116:119]
	v_mfma_f32_16x16x32_bf16 v[104:107], v[192:195], v[216:219], v[104:107]
	v_mfma_f32_16x16x32_bf16 v[100:103], v[200:203], v[216:219], v[100:103]
	v_mfma_f32_16x16x32_bf16 v[88:91], v[192:195], v[224:227], v[88:91]
	v_mfma_f32_16x16x32_bf16 v[84:87], v[200:203], v[224:227], v[84:87]
	v_mfma_f32_16x16x32_bf16 v[72:75], v[192:195], v[232:235], v[72:75]
	v_mfma_f32_16x16x32_bf16 v[68:71], v[200:203], v[232:235], v[68:71]
	s_barrier
	s_setprio 0
	s_add_i32 s14, s63, s25
	s_mov_b32 m0, s14
	ds_read_b128 v[204:207], v187 offset:49152
	ds_read_b128 v[208:211], v187 offset:50176
	ds_read_b128 v[212:215], v187 offset:51200
	ds_read_b128 v[216:219], v187 offset:52224
	ds_read_b128 v[220:223], v187 offset:53248
	ds_read_b128 v[224:227], v187 offset:54272
	ds_read_b128 v[228:231], v187 offset:55296
	ds_read_b128 v[232:235], v187 offset:56320
	s_add_u32 vcc_lo, s18, 0x80
	s_addc_u32 vcc_hi, s19, 0
	global_load_lds_dwordx4 v2, vcc
	s_add_i32 m0, s14, 0x2000
	s_add_u32 s14, s18, 0x160080
	v_lshl_add_u64 v[166:167], v[236:237], 0, s[36:37]
	s_addc_u32 s15, s19, 0
	s_add_i32 s18, s64, s25
	global_load_lds_dwordx4 v[166:167], off
	s_mov_b32 m0, s18
	s_nop 0
	global_load_lds_dwordx4 v2, s[14:15]
	v_lshl_add_u64 v[166:167], s[14:15], 0, v[152:153]
	s_add_i32 m0, s18, 0x2000
	s_nop 0
	global_load_lds_dwordx4 v[166:167], off
	s_mov_b32 m0, s30
	s_nop 0
	s_add_u32 vcc_lo, s20, 0x80
	s_addc_u32 vcc_hi, s21, 0
	global_load_lds_dwordx4 v0, vcc
	s_mov_b32 m0, s31
	s_nop 0
	s_add_u32 vcc_lo, s20, 0x80
	s_addc_u32 vcc_hi, s21, 0
	global_load_lds_dwordx4 v150, vcc
	s_waitcnt vmcnt(8)
	s_waitcnt lgkmcnt(0)
	s_setprio 1
	s_barrier
	v_mfma_f32_16x16x32_bf16 v[64:67], v[132:135], v[204:207], v[64:67]
	v_mfma_f32_16x16x32_bf16 v[60:63], v[158:161], v[204:207], v[60:63]
	v_mfma_f32_16x16x32_bf16 v[48:51], v[132:135], v[212:215], v[48:51]
	v_mfma_f32_16x16x32_bf16 v[44:47], v[158:161], v[212:215], v[44:47]
	v_mfma_f32_16x16x32_bf16 v[32:35], v[132:135], v[220:223], v[32:35]
	v_mfma_f32_16x16x32_bf16 v[28:31], v[158:161], v[220:223], v[28:31]
	v_mfma_f32_16x16x32_bf16 v[16:19], v[132:135], v[228:231], v[16:19]
	v_mfma_f32_16x16x32_bf16 v[12:15], v[158:161], v[228:231], v[12:15]
	v_mfma_f32_16x16x32_bf16 v[64:67], v[136:139], v[208:211], v[64:67]
	v_mfma_f32_16x16x32_bf16 v[60:63], v[162:165], v[208:211], v[60:63]
	v_mfma_f32_16x16x32_bf16 v[48:51], v[136:139], v[216:219], v[48:51]
	v_mfma_f32_16x16x32_bf16 v[44:47], v[162:165], v[216:219], v[44:47]
	v_mfma_f32_16x16x32_bf16 v[32:35], v[136:139], v[224:227], v[32:35]
	v_mfma_f32_16x16x32_bf16 v[28:31], v[162:165], v[224:227], v[28:31]
	v_mfma_f32_16x16x32_bf16 v[16:19], v[136:139], v[232:235], v[16:19]
	v_mfma_f32_16x16x32_bf16 v[12:15], v[162:165], v[232:235], v[12:15]
	v_mfma_f32_16x16x32_bf16 v[56:59], v[188:191], v[204:207], v[56:59]
	v_mfma_f32_16x16x32_bf16 v[52:55], v[196:199], v[204:207], v[52:55]
	v_mfma_f32_16x16x32_bf16 v[40:43], v[188:191], v[212:215], v[40:43]
	v_mfma_f32_16x16x32_bf16 v[36:39], v[196:199], v[212:215], v[36:39]
	v_mfma_f32_16x16x32_bf16 v[24:27], v[188:191], v[220:223], v[24:27]
	v_mfma_f32_16x16x32_bf16 v[20:23], v[196:199], v[220:223], v[20:23]
	v_mfma_f32_16x16x32_bf16 v[8:11], v[188:191], v[228:231], v[8:11]
	v_mfma_f32_16x16x32_bf16 v[4:7], v[196:199], v[228:231], v[4:7]
	v_mfma_f32_16x16x32_bf16 v[56:59], v[192:195], v[208:211], v[56:59]
	v_mfma_f32_16x16x32_bf16 v[52:55], v[200:203], v[208:211], v[52:55]
	v_mfma_f32_16x16x32_bf16 v[40:43], v[192:195], v[216:219], v[40:43]
	v_mfma_f32_16x16x32_bf16 v[36:39], v[200:203], v[216:219], v[36:39]
	v_mfma_f32_16x16x32_bf16 v[24:27], v[192:195], v[224:227], v[24:27]
	v_mfma_f32_16x16x32_bf16 v[20:23], v[200:203], v[224:227], v[20:23]
	v_mfma_f32_16x16x32_bf16 v[8:11], v[192:195], v[232:235], v[8:11]
	v_mfma_f32_16x16x32_bf16 v[4:7], v[200:203], v[232:235], v[4:7]
	s_barrier
	s_setprio 0
	s_add_i32 s57, s57, 2
	s_add_u32 s51, s51, 0x100
	s_addc_u32 s56, s56, 0
	s_cmpk_gt_u32 s57, 0x55
	s_mov_b64 s[14:15], s[16:17]
; #define PG8_STAGE(bufoff, gbase, voff) do { _Pragma("unroll") for (int _i = 0; _i < 2; ++_i) \
;         __builtin_amdgcn_global_load_lds((const unsigned*)((const char*)(gbase) + (voff)[_i]), (PG8_LAS unsigned*)(lds + (bufoff) + ldsw + _i * 8192), 16, 0, 0); } while (0)
; #define PG8_LDA(dst, b, h) do { _Pragma("unroll") for (int m = 0; m < 4; ++m) _Pragma("unroll") for (int k = 0; k < 2; ++k) dst[m][k] = *(const PG8_LAS bf16x8*)(lds + PG8_SA(b, h) + aoff + m * 2048 + k * 1024); } while (0)
; #define PG8_LDB(dst, b, h) do { _Pragma("unroll") for (int n = 0; n < 2; ++n) _Pragma("unroll") for (int k = 0; k < 2; ++k) dst[n][k] = *(const PG8_LAS bf16x8*)(lds + PG8_SB(b, h) + boff + n * 2048 + k * 1024); } while (0)
; #define PG8_MMA(ai, bj, At, Bt) do { __builtin_amdgcn_s_setprio(1); _Pragma("unroll") for (int m = 0; m < 4; ++m) _Pragma("unroll") for (int n = 0; n < 2; ++n) _Pragma("unroll") for (int k = 0; k < 2; ++k) \
;         acc[ai][bj][m][n] = __builtin_amdgcn_mfma_f32_16x16x32_bf16(Bt[n][k], At[m][k], acc[ai][bj][m][n], 0, 0, 0); __builtin_amdgcn_s_setprio(0); } while (0)
; #define PG8_WAIT_V(n) asm volatile("s_waitcnt vmcnt(" #n ")" ::: "memory")
; #define PG8_BAR __builtin_amdgcn_s_barrier()
; template <class Epi, class Sched, bool ALIGN_EPI = false, bool SP2 = false>
; __device__ __forceinline__ void gemm_phase(PG8_LAS unsigned char* lds, const Gemm g, const Sched& S, const Epi& E) {
;     ...
;         for (int t = 0; t < nt; t += 2) {
;             const bool last = (t == nt - 2);
;             const char* a1 = cA + (size_t)(t + 1) * kstep;
;             const char* a2 = last ? nA : cA + (size_t)(t + 2) * kstep; const char* b2 = last ? nB : cB + (size_t)(t + 2) * kstep;
;             const char* a3 = a2 + kstep; const char* b3 = b2 + kstep;
;             if (last && has_next) S.a_ready(nxt);
;             if constexpr (SP2) {
;             PG8_LDB(B0, 0, 0); PG8_LDB(B1, 0, 1); PG8_SCHED; PG8_LDA(At, 0, 0); PG8_STAGE(PG8_SA(1, 1), a1 + hstep, voffA);
;             PG8_WAIT_V(8); PG8_WAIT_L(0); PG8_BAR; PG8_MMA(0, 0, At, B0); PG8_MMA(0, 1, At, B1); PG8_BAR; PG8_SCHED;
;             PG8_LDA(At, 0, 1); PG8_STAGE(PG8_SB(0, 0), b2, voffB); PG8_STAGE(PG8_SB(0, 1), b2 + hstep, voffB); PG8_STAGE(PG8_SA(0, 0), a2, voffA);
;             PG8_WAIT_V(8); PG8_WAIT_L(0); PG8_BAR; PG8_MMA(1, 0, At, B0); PG8_MMA(1, 1, At, B1); PG8_BAR; PG8_SCHED;
.LBB0_167:
	s_add_u32 s16, s14, 0x100
	s_addc_u32 s17, s15, 0
	s_add_i32 s63, 0, 0x10000
	s_cmpk_eq_i32 s57, 0x54
	s_cselect_b32 s21, s7, s17
	s_cselect_b32 s20, s6, s16
	s_cselect_b32 s19, s13, s56
	s_cselect_b32 s18, s12, s51
	s_add_i32 s64, 0, 0x14000
	v_add_u32_e32 v162, s63, v185
	v_add_u32_e32 v166, s64, v185
	ds_read_b128 v[132:135], v162
	ds_read_b128 v[136:139], v162 offset:1024
	ds_read_b128 v[158:161], v162 offset:2048
	ds_read_b128 v[162:165], v162 offset:3072
	ds_read_b128 v[188:191], v166
	ds_read_b128 v[192:195], v166 offset:1024
	ds_read_b128 v[196:199], v166 offset:2048
	ds_read_b128 v[200:203], v166 offset:3072
	s_add_i32 m0, s26, 0xc000
	ds_read_b128 v[204:207], v187
	ds_read_b128 v[208:211], v187 offset:1024
	ds_read_b128 v[212:215], v187 offset:2048
	ds_read_b128 v[216:219], v187 offset:3072
	ds_read_b128 v[220:223], v187 offset:4096
	ds_read_b128 v[224:227], v187 offset:5120
	ds_read_b128 v[228:231], v187 offset:6144
	ds_read_b128 v[232:235], v187 offset:7168
	global_load_lds_dwordx4 v154, s[14:15]
	s_add_i32 m0, s26, 0xe000
	s_nop 0
	global_load_lds_dwordx4 v156, s[14:15]
	s_waitcnt vmcnt(8)
	s_waitcnt lgkmcnt(0)
	s_setprio 1
	s_barrier
	v_mfma_f32_16x16x32_bf16 v[128:131], v[132:135], v[204:207], v[128:131]
	v_mfma_f32_16x16x32_bf16 v[124:127], v[158:161], v[204:207], v[124:127]
	v_mfma_f32_16x16x32_bf16 v[112:115], v[132:135], v[212:215], v[112:115]
	v_mfma_f32_16x16x32_bf16 v[108:111], v[158:161], v[212:215], v[108:111]
	v_mfma_f32_16x16x32_bf16 v[96:99], v[132:135], v[220:223], v[96:99]
	v_mfma_f32_16x16x32_bf16 v[92:95], v[158:161], v[220:223], v[92:95]
	v_mfma_f32_16x16x32_bf16 v[80:83], v[132:135], v[228:231], v[80:83]
	v_mfma_f32_16x16x32_bf16 v[76:79], v[158:161], v[228:231], v[76:79]
	v_mfma_f32_16x16x32_bf16 v[128:131], v[136:139], v[208:211], v[128:131]
	v_mfma_f32_16x16x32_bf16 v[124:127], v[162:165], v[208:211], v[124:127]
	v_mfma_f32_16x16x32_bf16 v[112:115], v[136:139], v[216:219], v[112:115]
	v_mfma_f32_16x16x32_bf16 v[108:111], v[162:165], v[216:219], v[108:111]
	v_mfma_f32_16x16x32_bf16 v[96:99], v[136:139], v[224:227], v[96:99]
	v_mfma_f32_16x16x32_bf16 v[92:95], v[162:165], v[224:227], v[92:95]
	v_mfma_f32_16x16x32_bf16 v[80:83], v[136:139], v[232:235], v[80:83]
	v_mfma_f32_16x16x32_bf16 v[76:79], v[162:165], v[232:235], v[76:79]
	v_mfma_f32_16x16x32_bf16 v[120:123], v[188:191], v[204:207], v[120:123]
	v_mfma_f32_16x16x32_bf16 v[116:119], v[196:199], v[204:207], v[116:119]
	v_mfma_f32_16x16x32_bf16 v[104:107], v[188:191], v[212:215], v[104:107]
	v_mfma_f32_16x16x32_bf16 v[100:103], v[196:199], v[212:215], v[100:103]
	v_mfma_f32_16x16x32_bf16 v[88:91], v[188:191], v[220:223], v[88:91]
	v_mfma_f32_16x16x32_bf16 v[84:87], v[196:199], v[220:223], v[84:87]
	v_mfma_f32_16x16x32_bf16 v[72:75], v[188:191], v[228:231], v[72:75]
	v_mfma_f32_16x16x32_bf16 v[68:71], v[196:199], v[228:231], v[68:71]
	v_mfma_f32_16x16x32_bf16 v[120:123], v[192:195], v[208:211], v[120:123]
	v_mfma_f32_16x16x32_bf16 v[116:119], v[200:203], v[208:211], v[116:119]
	v_mfma_f32_16x16x32_bf16 v[104:107], v[192:195], v[216:219], v[104:107]
	v_mfma_f32_16x16x32_bf16 v[100:103], v[200:203], v[216:219], v[100:103]
	v_mfma_f32_16x16x32_bf16 v[88:91], v[192:195], v[224:227], v[88:91]
	v_mfma_f32_16x16x32_bf16 v[84:87], v[200:203], v[224:227], v[84:87]
	v_mfma_f32_16x16x32_bf16 v[72:75], v[192:195], v[232:235], v[72:75]
	v_mfma_f32_16x16x32_bf16 v[68:71], v[200:203], v[232:235], v[68:71]
	s_barrier
	s_setprio 0
	s_add_i32 s14, s63, s25
	s_mov_b32 m0, s14
	ds_read_b128 v[204:207], v187 offset:16384
	ds_read_b128 v[208:211], v187 offset:17408
	ds_read_b128 v[212:215], v187 offset:18432
	ds_read_b128 v[216:219], v187 offset:19456
	ds_read_b128 v[220:223], v187 offset:20480
	ds_read_b128 v[224:227], v187 offset:21504
	ds_read_b128 v[228:231], v187 offset:22528
	ds_read_b128 v[232:235], v187 offset:23552
	global_load_lds_dwordx4 v2, s[18:19]
	s_add_i32 m0, s14, 0x2000
	s_add_u32 s14, s18, 0x160000
	v_lshl_add_u64 v[236:237], s[18:19], 0, v[152:153]
	s_addc_u32 s15, s19, 0
	s_add_i32 s63, s64, s25
	global_load_lds_dwordx4 v[236:237], off
	s_mov_b32 m0, s63
	global_load_lds_dwordx4 v2, s[14:15]
	s_add_i32 m0, s63, 0x2000
	s_nop 0
	global_load_lds_dwordx4 v152, s[14:15]
	s_mov_b32 m0, s26
	s_nop 0
	global_load_lds_dwordx4 v0, s[20:21]
	s_mov_b32 m0, s27
	s_nop 0
	global_load_lds_dwordx4 v150, s[20:21]
	s_waitcnt vmcnt(8)
	s_waitcnt lgkmcnt(0)
	s_setprio 1
	s_barrier
	v_mfma_f32_16x16x32_bf16 v[64:67], v[132:135], v[204:207], v[64:67]
	v_mfma_f32_16x16x32_bf16 v[60:63], v[158:161], v[204:207], v[60:63]
	v_mfma_f32_16x16x32_bf16 v[48:51], v[132:135], v[212:215], v[48:51]
	v_mfma_f32_16x16x32_bf16 v[44:47], v[158:161], v[212:215], v[44:47]
	v_mfma_f32_16x16x32_bf16 v[32:35], v[132:135], v[220:223], v[32:35]
	v_mfma_f32_16x16x32_bf16 v[28:31], v[158:161], v[220:223], v[28:31]
	v_mfma_f32_16x16x32_bf16 v[16:19], v[132:135], v[228:231], v[16:19]
	v_mfma_f32_16x16x32_bf16 v[12:15], v[158:161], v[228:231], v[12:15]
	v_mfma_f32_16x16x32_bf16 v[64:67], v[136:139], v[208:211], v[64:67]
	v_mfma_f32_16x16x32_bf16 v[60:63], v[162:165], v[208:211], v[60:63]
	v_mfma_f32_16x16x32_bf16 v[48:51], v[136:139], v[216:219], v[48:51]
	v_mfma_f32_16x16x32_bf16 v[44:47], v[162:165], v[216:219], v[44:47]
	v_mfma_f32_16x16x32_bf16 v[32:35], v[136:139], v[224:227], v[32:35]
	v_mfma_f32_16x16x32_bf16 v[28:31], v[162:165], v[224:227], v[28:31]
	v_mfma_f32_16x16x32_bf16 v[16:19], v[136:139], v[232:235], v[16:19]
	v_mfma_f32_16x16x32_bf16 v[12:15], v[162:165], v[232:235], v[12:15]
	v_mfma_f32_16x16x32_bf16 v[56:59], v[188:191], v[204:207], v[56:59]
	v_mfma_f32_16x16x32_bf16 v[52:55], v[196:199], v[204:207], v[52:55]
	v_mfma_f32_16x16x32_bf16 v[40:43], v[188:191], v[212:215], v[40:43]
	v_mfma_f32_16x16x32_bf16 v[36:39], v[196:199], v[212:215], v[36:39]
	v_mfma_f32_16x16x32_bf16 v[24:27], v[188:191], v[220:223], v[24:27]
	v_mfma_f32_16x16x32_bf16 v[20:23], v[196:199], v[220:223], v[20:23]
	v_mfma_f32_16x16x32_bf16 v[8:11], v[188:191], v[228:231], v[8:11]
	v_mfma_f32_16x16x32_bf16 v[4:7], v[196:199], v[228:231], v[4:7]
	v_mfma_f32_16x16x32_bf16 v[56:59], v[192:195], v[208:211], v[56:59]
	v_mfma_f32_16x16x32_bf16 v[52:55], v[200:203], v[208:211], v[52:55]
	v_mfma_f32_16x16x32_bf16 v[40:43], v[192:195], v[216:219], v[40:43]
	v_mfma_f32_16x16x32_bf16 v[36:39], v[200:203], v[216:219], v[36:39]
	v_mfma_f32_16x16x32_bf16 v[24:27], v[192:195], v[224:227], v[24:27]
	v_mfma_f32_16x16x32_bf16 v[20:23], v[200:203], v[224:227], v[20:23]
	v_mfma_f32_16x16x32_bf16 v[8:11], v[192:195], v[232:235], v[8:11]
	v_mfma_f32_16x16x32_bf16 v[4:7], v[200:203], v[232:235], v[4:7]
	s_barrier
; #define PG8_STAGE(bufoff, gbase, voff) do { _Pragma("unroll") for (int _i = 0; _i < 2; ++_i) \
;         __builtin_amdgcn_global_load_lds((const unsigned*)((const char*)(gbase) + (voff)[_i]), (PG8_LAS unsigned*)(lds + (bufoff) + ldsw + _i * 8192), 16, 0, 0); } while (0)
; #define PG8_LDA(dst, b, h) do { _Pragma("unroll") for (int m = 0; m < 4; ++m) _Pragma("unroll") for (int k = 0; k < 2; ++k) dst[m][k] = *(const PG8_LAS bf16x8*)(lds + PG8_SA(b, h) + aoff + m * 2048 + k * 1024); } while (0)
; #define PG8_LDB(dst, b, h) do { _Pragma("unroll") for (int n = 0; n < 2; ++n) _Pragma("unroll") for (int k = 0; k < 2; ++k) dst[n][k] = *(const PG8_LAS bf16x8*)(lds + PG8_SB(b, h) + boff + n * 2048 + k * 1024); } while (0)
; #define PG8_MMA(ai, bj, At, Bt) do { __builtin_amdgcn_s_setprio(1); _Pragma("unroll") for (int m = 0; m < 4; ++m) _Pragma("unroll") for (int n = 0; n < 2; ++n) _Pragma("unroll") for (int k = 0; k < 2; ++k) \
;         acc[ai][bj][m][n] = __builtin_amdgcn_mfma_f32_16x16x32_bf16(Bt[n][k], At[m][k], acc[ai][bj][m][n], 0, 0, 0); __builtin_amdgcn_s_setprio(0); } while (0)
; #define PG8_WAIT_V(n) asm volatile("s_waitcnt vmcnt(" #n ")" ::: "memory")
; #define PG8_WAIT_L(n) asm volatile("s_waitcnt lgkmcnt(" #n ")" ::: "memory")
; #define PG8_BAR __builtin_amdgcn_s_barrier()
; #define PG8_SCHED __builtin_amdgcn_sched_barrier(0)
; template <class Epi, class Sched, bool ALIGN_EPI = false, bool SP2 = false>
; __device__ __forceinline__ void gemm_phase(PG8_LAS unsigned char* lds, const Gemm g, const Sched& S, const Epi& E) {
;     ...
;             PG8_LDB(B0, 1, 0); PG8_LDB(B1, 1, 1); PG8_SCHED; PG8_LDA(At, 1, 0); PG8_STAGE(PG8_SA(0, 1), a2 + hstep, voffA);
;             PG8_WAIT_V(8); PG8_WAIT_L(0); PG8_BAR; PG8_MMA(0, 0, At, B0); PG8_MMA(0, 1, At, B1); PG8_BAR; PG8_SCHED;
;             PG8_LDA(At, 1, 1); PG8_STAGE(PG8_SB(1, 0), b3, voffB); PG8_STAGE(PG8_SB(1, 1), b3 + hstep, voffB); PG8_STAGE(PG8_SA(1, 0), a3, voffA);
;             PG8_WAIT_V(8); PG8_WAIT_L(0); PG8_BAR; PG8_MMA(1, 0, At, B0); PG8_MMA(1, 1, At, B1); PG8_BAR; PG8_SCHED;
;     ...
;         if constexpr (ALIGN_EPI) { if (wr == 0) PG8_BAR; }
	s_setprio 0
	s_add_i32 s63, 0, 0x18000
	s_add_i32 s64, 0, 0x1c000
	v_add_u32_e32 v162, s63, v185
	v_add_u32_e32 v200, s64, v185
	ds_read_b128 v[132:135], v162
	ds_read_b128 v[136:139], v162 offset:1024
	ds_read_b128 v[158:161], v162 offset:2048
	ds_read_b128 v[162:165], v162 offset:3072
	ds_read_b128 v[188:191], v200
	ds_read_b128 v[192:195], v200 offset:1024
	ds_read_b128 v[196:199], v200 offset:2048
	ds_read_b128 v[200:203], v200 offset:3072
	s_add_u32 s14, s20, 0x160000
	s_addc_u32 s15, s21, 0
	s_mov_b32 m0, s28
	ds_read_b128 v[204:207], v187 offset:32768
	ds_read_b128 v[208:211], v187 offset:33792
	ds_read_b128 v[212:215], v187 offset:34816
	ds_read_b128 v[216:219], v187 offset:35840
	ds_read_b128 v[220:223], v187 offset:36864
	ds_read_b128 v[224:227], v187 offset:37888
	ds_read_b128 v[228:231], v187 offset:38912
	ds_read_b128 v[232:235], v187 offset:39936
	global_load_lds_dwordx4 v0, s[14:15]
	s_mov_b32 m0, s29
	s_nop 0
	global_load_lds_dwordx4 v150, s[14:15]
	s_waitcnt vmcnt(8)
	s_waitcnt lgkmcnt(0)
	s_setprio 1
	s_barrier
	v_mfma_f32_16x16x32_bf16 v[128:131], v[132:135], v[204:207], v[128:131]
	v_mfma_f32_16x16x32_bf16 v[124:127], v[158:161], v[204:207], v[124:127]
	v_mfma_f32_16x16x32_bf16 v[112:115], v[132:135], v[212:215], v[112:115]
	v_mfma_f32_16x16x32_bf16 v[108:111], v[158:161], v[212:215], v[108:111]
	v_mfma_f32_16x16x32_bf16 v[96:99], v[132:135], v[220:223], v[96:99]
	v_mfma_f32_16x16x32_bf16 v[92:95], v[158:161], v[220:223], v[92:95]
	v_mfma_f32_16x16x32_bf16 v[80:83], v[132:135], v[228:231], v[80:83]
	v_mfma_f32_16x16x32_bf16 v[76:79], v[158:161], v[228:231], v[76:79]
	v_mfma_f32_16x16x32_bf16 v[128:131], v[136:139], v[208:211], v[128:131]
	v_mfma_f32_16x16x32_bf16 v[124:127], v[162:165], v[208:211], v[124:127]
	v_mfma_f32_16x16x32_bf16 v[112:115], v[136:139], v[216:219], v[112:115]
	v_mfma_f32_16x16x32_bf16 v[108:111], v[162:165], v[216:219], v[108:111]
	v_mfma_f32_16x16x32_bf16 v[96:99], v[136:139], v[224:227], v[96:99]
	v_mfma_f32_16x16x32_bf16 v[92:95], v[162:165], v[224:227], v[92:95]
	v_mfma_f32_16x16x32_bf16 v[80:83], v[136:139], v[232:235], v[80:83]
	v_mfma_f32_16x16x32_bf16 v[76:79], v[162:165], v[232:235], v[76:79]
	v_mfma_f32_16x16x32_bf16 v[120:123], v[188:191], v[204:207], v[120:123]
	v_mfma_f32_16x16x32_bf16 v[116:119], v[196:199], v[204:207], v[116:119]
	v_mfma_f32_16x16x32_bf16 v[104:107], v[188:191], v[212:215], v[104:107]
	v_mfma_f32_16x16x32_bf16 v[100:103], v[196:199], v[212:215], v[100:103]
	v_mfma_f32_16x16x32_bf16 v[88:91], v[188:191], v[220:223], v[88:91]
	v_mfma_f32_16x16x32_bf16 v[84:87], v[196:199], v[220:223], v[84:87]
	v_mfma_f32_16x16x32_bf16 v[72:75], v[188:191], v[228:231], v[72:75]
	v_mfma_f32_16x16x32_bf16 v[68:71], v[196:199], v[228:231], v[68:71]
	v_mfma_f32_16x16x32_bf16 v[120:123], v[192:195], v[208:211], v[120:123]
	v_mfma_f32_16x16x32_bf16 v[116:119], v[200:203], v[208:211], v[116:119]
	v_mfma_f32_16x16x32_bf16 v[104:107], v[192:195], v[216:219], v[104:107]
	v_mfma_f32_16x16x32_bf16 v[100:103], v[200:203], v[216:219], v[100:103]
	v_mfma_f32_16x16x32_bf16 v[88:91], v[192:195], v[224:227], v[88:91]
	v_mfma_f32_16x16x32_bf16 v[84:87], v[200:203], v[224:227], v[84:87]
	v_mfma_f32_16x16x32_bf16 v[72:75], v[192:195], v[232:235], v[72:75]
	v_mfma_f32_16x16x32_bf16 v[68:71], v[200:203], v[232:235], v[68:71]
	s_barrier
	s_setprio 0
	s_add_i32 s14, s63, s25
	s_mov_b32 m0, s14
	ds_read_b128 v[204:207], v187 offset:49152
	ds_read_b128 v[208:211], v187 offset:50176
	ds_read_b128 v[212:215], v187 offset:51200
	ds_read_b128 v[216:219], v187 offset:52224
	ds_read_b128 v[220:223], v187 offset:53248
	ds_read_b128 v[224:227], v187 offset:54272
	ds_read_b128 v[228:231], v187 offset:55296
	ds_read_b128 v[232:235], v187 offset:56320
	s_add_u32 vcc_lo, s18, 0x80
	s_addc_u32 vcc_hi, s19, 0
	global_load_lds_dwordx4 v2, vcc
	s_add_i32 m0, s14, 0x2000
	s_add_u32 s14, s18, 0x160080
	v_lshl_add_u64 v[166:167], v[236:237], 0, s[36:37]
	s_addc_u32 s15, s19, 0
	s_add_i32 s18, s64, s25
	global_load_lds_dwordx4 v[166:167], off
	s_mov_b32 m0, s18
	s_nop 0
	global_load_lds_dwordx4 v2, s[14:15]
	v_lshl_add_u64 v[166:167], s[14:15], 0, v[152:153]
	s_add_i32 m0, s18, 0x2000
	s_nop 0
	global_load_lds_dwordx4 v[166:167], off
	s_mov_b32 m0, s30
	s_nop 0
	s_add_u32 vcc_lo, s20, 0x80
	s_addc_u32 vcc_hi, s21, 0
	global_load_lds_dwordx4 v0, vcc
	s_mov_b32 m0, s31
	s_nop 0
	s_add_u32 vcc_lo, s20, 0x80
	s_addc_u32 vcc_hi, s21, 0
	global_load_lds_dwordx4 v150, vcc
	s_waitcnt vmcnt(8)
	s_waitcnt lgkmcnt(0)
	s_setprio 1
	s_barrier
	v_mfma_f32_16x16x32_bf16 v[64:67], v[132:135], v[204:207], v[64:67]
	v_mfma_f32_16x16x32_bf16 v[60:63], v[158:161], v[204:207], v[60:63]
	v_mfma_f32_16x16x32_bf16 v[48:51], v[132:135], v[212:215], v[48:51]
	v_mfma_f32_16x16x32_bf16 v[44:47], v[158:161], v[212:215], v[44:47]
	v_mfma_f32_16x16x32_bf16 v[32:35], v[132:135], v[220:223], v[32:35]
	v_mfma_f32_16x16x32_bf16 v[28:31], v[158:161], v[220:223], v[28:31]
	v_mfma_f32_16x16x32_bf16 v[16:19], v[132:135], v[228:231], v[16:19]
	v_mfma_f32_16x16x32_bf16 v[12:15], v[158:161], v[228:231], v[12:15]
	v_mfma_f32_16x16x32_bf16 v[64:67], v[136:139], v[208:211], v[64:67]
	v_mfma_f32_16x16x32_bf16 v[60:63], v[162:165], v[208:211], v[60:63]
	v_mfma_f32_16x16x32_bf16 v[48:51], v[136:139], v[216:219], v[48:51]
	v_mfma_f32_16x16x32_bf16 v[44:47], v[162:165], v[216:219], v[44:47]
	v_mfma_f32_16x16x32_bf16 v[32:35], v[136:139], v[224:227], v[32:35]
	v_mfma_f32_16x16x32_bf16 v[28:31], v[162:165], v[224:227], v[28:31]
	v_mfma_f32_16x16x32_bf16 v[16:19], v[136:139], v[232:235], v[16:19]
	v_mfma_f32_16x16x32_bf16 v[12:15], v[162:165], v[232:235], v[12:15]
	v_mfma_f32_16x16x32_bf16 v[56:59], v[188:191], v[204:207], v[56:59]
	v_mfma_f32_16x16x32_bf16 v[52:55], v[196:199], v[204:207], v[52:55]
	v_mfma_f32_16x16x32_bf16 v[40:43], v[188:191], v[212:215], v[40:43]
	v_mfma_f32_16x16x32_bf16 v[36:39], v[196:199], v[212:215], v[36:39]
	v_mfma_f32_16x16x32_bf16 v[24:27], v[188:191], v[220:223], v[24:27]
	v_mfma_f32_16x16x32_bf16 v[20:23], v[196:199], v[220:223], v[20:23]
	v_mfma_f32_16x16x32_bf16 v[8:11], v[188:191], v[228:231], v[8:11]
	v_mfma_f32_16x16x32_bf16 v[4:7], v[196:199], v[228:231], v[4:7]
	v_mfma_f32_16x16x32_bf16 v[56:59], v[192:195], v[208:211], v[56:59]
	v_mfma_f32_16x16x32_bf16 v[52:55], v[200:203], v[208:211], v[52:55]
	v_mfma_f32_16x16x32_bf16 v[40:43], v[192:195], v[216:219], v[40:43]
	v_mfma_f32_16x16x32_bf16 v[36:39], v[200:203], v[216:219], v[36:39]
	v_mfma_f32_16x16x32_bf16 v[24:27], v[192:195], v[224:227], v[24:27]
	v_mfma_f32_16x16x32_bf16 v[20:23], v[200:203], v[224:227], v[20:23]
	v_mfma_f32_16x16x32_bf16 v[8:11], v[192:195], v[232:235], v[8:11]
	v_mfma_f32_16x16x32_bf16 v[4:7], v[200:203], v[232:235], v[4:7]
	s_barrier
	s_setprio 0
	s_add_i32 s57, s57, 2
	s_add_u32 s51, s51, 0x100
	s_addc_u32 s56, s56, 0
	s_cmpk_gt_u32 s57, 0x55
	s_mov_b64 s[14:15], s[16:17]
	s_cbranch_scc0 .LBB0_167
	s_and_b64 vcc, exec, s[10:11]
	s_cbranch_vccz .LBB0_170
	s_barrier

; #define PG8_STAGE(bufoff, gbase, voff) do { _Pragma("unroll") for (int _i = 0; _i < 2; ++_i) \
;         __builtin_amdgcn_global_load_lds((const unsigned*)((const char*)(gbase) + (voff)[_i]), (PG8_LAS unsigned*)(lds + (bufoff) + ldsw + _i * 8192), 16, 0, 0); } while (0)
; #define PG8_LDA(dst, b, h) do { _Pragma("unroll") for (int m = 0; m < 4; ++m) _Pragma("unroll") for (int k = 0; k < 2; ++k) dst[m][k] = *(const PG8_LAS bf16x8*)(lds + PG8_SA(b, h) + aoff + m * 2048 + k * 1024); } while (0)
; #define PG8_LDB(dst, b, h) do { _Pragma("unroll") for (int n = 0; n < 2; ++n) _Pragma("unroll") for (int k = 0; k < 2; ++k) dst[n][k] = *(const PG8_LAS bf16x8*)(lds + PG8_SB(b, h) + boff + n * 2048 + k * 1024); } while (0)
; #define PG8_WAIT_V(n) asm volatile("s_waitcnt vmcnt(" #n ")" ::: "memory")
; #define PG8_WAIT_L(n) asm volatile("s_waitcnt lgkmcnt(" #n ")" ::: "memory")
; #define PG8_BAR __builtin_amdgcn_s_barrier()
; #define PG8_SCHED __builtin_amdgcn_sched_barrier(0)
; template <class Epi, class Sched, bool ALIGN_EPI = false, bool SP2 = false>
; __device__ __forceinline__ void gemm_phase(PG8_LAS unsigned char* lds, const Gemm g, const Sched& S, const Epi& E) {
;     ...
;         const bool has_next = S.next(ui + 1, nxt);
;         const char* nA = has_next ? (const char*)g.A + (size_t)nxt.pm * tstep : cA; const char* nB = has_next ? (const char*)g.Bt + (size_t)nxt.pn * tstep : cB;
;         for (int t = 0; t < nt; t += 2) {
;             const bool last = (t == nt - 2);
;             const char* a1 = cA + (size_t)(t + 1) * kstep;
;             const char* a2 = last ? nA : cA + (size_t)(t + 2) * kstep; const char* b2 = last ? nB : cB + (size_t)(t + 2) * kstep;
;             const char* a3 = a2 + kstep; const char* b3 = b2 + kstep;
;             if (last && has_next) S.a_ready(nxt);
;             if constexpr (SP2) {
;             PG8_LDB(B0, 0, 0); PG8_LDB(B1, 0, 1); PG8_SCHED; PG8_LDA(At, 0, 0); PG8_STAGE(PG8_SA(1, 1), a1 + hstep, voffA);
;             PG8_WAIT_V(8); PG8_WAIT_L(0); PG8_BAR; PG8_MMA(0, 0, At, B0); PG8_MMA(0, 1, At, B1); PG8_BAR; PG8_SCHED;
;             PG8_LDA(At, 0, 1); PG8_STAGE(PG8_SB(0, 0), b2, voffB); PG8_STAGE(PG8_SB(0, 1), b2 + hstep, voffB); PG8_STAGE(PG8_SA(0, 0), a2, voffA);
;             PG8_WAIT_V(8); PG8_WAIT_L(0); PG8_BAR; PG8_MMA(1, 0, At, B0); PG8_MMA(1, 1, At, B1); PG8_BAR; PG8_SCHED;
.LBB0_250:
	s_ashr_i32 s11, s10, 31
	s_lshl_b64 s[12:13], s[10:11], 20
	s_add_u32 s12, s46, s12
	s_addc_u32 s13, s47, s13
	s_and_b64 s[14:15], s[2:3], exec
	s_cselect_b32 s11, s13, s19
	s_cselect_b32 s45, s12, s18
	s_ashr_i32 s7, s6, 31
	s_lshl_b64 s[14:15], s[6:7], 20
	s_add_u32 s14, s25, s14
	s_addc_u32 s15, s26, s15
	s_and_b64 s[22:23], s[2:3], exec
	s_cselect_b32 s7, s15, s21
	s_cselect_b32 s50, s14, s20
	s_add_u32 s18, s18, 0x80080
	s_addc_u32 s19, s19, 0
	s_add_u32 s51, s20, 0x100
	s_addc_u32 s56, s21, 0
	s_mov_b32 s57, -2
	s_add_u32 s20, s18, 0xfff80080
	s_addc_u32 s21, s19, -1
	s_add_i32 s63, 0, 0x10000
	s_cmp_eq_u32 s57, 28
	s_cselect_b32 s23, s11, s21
	s_cselect_b32 s22, s45, s20
	v_add_u32_e32 v151, s63, v156
	s_cselect_b32 s21, s7, s56
	s_cselect_b32 s20, s50, s51
	s_add_i32 s66, 0, 0x14000
	ds_read_b128 v[184:187], v151
	ds_read_b128 v[188:191], v151 offset:1024
	ds_read_b128 v[192:195], v151 offset:2048
	ds_read_b128 v[196:199], v151 offset:3072
	v_add_u32_e32 v151, s66, v156
	ds_read_b128 v[200:203], v151
	ds_read_b128 v[204:207], v151 offset:1024
	ds_read_b128 v[208:211], v151 offset:2048
	ds_read_b128 v[212:215], v151 offset:3072
	s_add_i32 m0, s17, 0xc000
	ds_read_b128 v[216:219], v160
	ds_read_b128 v[220:223], v160 offset:1024
	ds_read_b128 v[224:227], v160 offset:2048
	ds_read_b128 v[228:231], v160 offset:3072
	ds_read_b128 v[232:235], v160 offset:4096
	ds_read_b128 v[236:239], v160 offset:5120
	ds_read_b128 v[240:243], v160 offset:6144
	ds_read_b128 v[244:247], v160 offset:7168
	global_load_lds_dwordx4 v136, s[18:19]
	s_add_i32 m0, s17, 0xe000
	s_nop 0
	global_load_lds_dwordx4 v138, s[18:19]
	s_waitcnt vmcnt(8)
	s_waitcnt lgkmcnt(0)
	s_setprio 1
	s_barrier
	v_mfma_f32_16x16x32_bf16 v[128:131], v[184:187], v[216:219], 0
	v_mfma_f32_16x16x32_bf16 v[124:127], v[192:195], v[216:219], 0
	v_mfma_f32_16x16x32_bf16 v[112:115], v[184:187], v[224:227], 0
	v_mfma_f32_16x16x32_bf16 v[108:111], v[192:195], v[224:227], 0
	v_mfma_f32_16x16x32_bf16 v[96:99], v[184:187], v[232:235], 0
	v_mfma_f32_16x16x32_bf16 v[92:95], v[192:195], v[232:235], 0
	v_mfma_f32_16x16x32_bf16 v[80:83], v[184:187], v[240:243], 0
	v_mfma_f32_16x16x32_bf16 v[76:79], v[192:195], v[240:243], 0
	v_mfma_f32_16x16x32_bf16 v[128:131], v[188:191], v[220:223], v[128:131]
	v_mfma_f32_16x16x32_bf16 v[124:127], v[196:199], v[220:223], v[124:127]
	v_mfma_f32_16x16x32_bf16 v[112:115], v[188:191], v[228:231], v[112:115]
	v_mfma_f32_16x16x32_bf16 v[108:111], v[196:199], v[228:231], v[108:111]
	v_mfma_f32_16x16x32_bf16 v[96:99], v[188:191], v[236:239], v[96:99]
	v_mfma_f32_16x16x32_bf16 v[92:95], v[196:199], v[236:239], v[92:95]
	v_mfma_f32_16x16x32_bf16 v[80:83], v[188:191], v[244:247], v[80:83]
	v_mfma_f32_16x16x32_bf16 v[76:79], v[196:199], v[244:247], v[76:79]
	v_mfma_f32_16x16x32_bf16 v[120:123], v[200:203], v[216:219], 0
	v_mfma_f32_16x16x32_bf16 v[116:119], v[208:211], v[216:219], 0
	v_mfma_f32_16x16x32_bf16 v[104:107], v[200:203], v[224:227], 0
	v_mfma_f32_16x16x32_bf16 v[100:103], v[208:211], v[224:227], 0
	v_mfma_f32_16x16x32_bf16 v[88:91], v[200:203], v[232:235], 0
	v_mfma_f32_16x16x32_bf16 v[84:87], v[208:211], v[232:235], 0
	v_mfma_f32_16x16x32_bf16 v[72:75], v[200:203], v[240:243], 0
	v_mfma_f32_16x16x32_bf16 v[68:71], v[208:211], v[240:243], 0
	v_mfma_f32_16x16x32_bf16 v[120:123], v[204:207], v[220:223], v[120:123]
	v_mfma_f32_16x16x32_bf16 v[116:119], v[212:215], v[220:223], v[116:119]
	v_mfma_f32_16x16x32_bf16 v[104:107], v[204:207], v[228:231], v[104:107]
	v_mfma_f32_16x16x32_bf16 v[100:103], v[212:215], v[228:231], v[100:103]
	v_mfma_f32_16x16x32_bf16 v[88:91], v[204:207], v[236:239], v[88:91]
	v_mfma_f32_16x16x32_bf16 v[84:87], v[212:215], v[236:239], v[84:87]
	v_mfma_f32_16x16x32_bf16 v[72:75], v[204:207], v[244:247], v[72:75]
	v_mfma_f32_16x16x32_bf16 v[68:71], v[212:215], v[244:247], v[68:71]
	s_barrier
	s_setprio 0
	s_add_i32 s63, s63, s27
	s_mov_b32 m0, s63
	ds_read_b128 v[216:219], v160 offset:16384
	ds_read_b128 v[220:223], v160 offset:17408
	ds_read_b128 v[224:227], v160 offset:18432
	ds_read_b128 v[228:231], v160 offset:19456
	ds_read_b128 v[232:235], v160 offset:20480
	ds_read_b128 v[236:239], v160 offset:21504
	ds_read_b128 v[240:243], v160 offset:22528
	ds_read_b128 v[244:247], v160 offset:23552
	global_load_lds_dwordx4 v2, s[20:21]
	s_add_i32 m0, s63, 0x2000
	s_add_u32 s64, s20, 0x80000
	s_addc_u32 s65, s21, 0
	s_add_i32 s63, s66, s27
	global_load_lds_dwordx4 v0, s[20:21]
	s_mov_b32 m0, s63
	v_lshl_add_u64 v[250:251], s[22:23], 0, v[132:133]
	global_load_lds_dwordx4 v2, s[64:65]
	s_add_i32 m0, s63, 0x2000
	s_nop 0
	global_load_lds_dwordx4 v0, s[64:65]
	v_lshl_add_u64 v[248:249], s[22:23], 0, v[134:135]
	s_mov_b32 m0, s17
	s_nop 0
	global_load_lds_dwordx4 v[248:249], off
	s_mov_b32 m0, s29
	s_nop 0
	global_load_lds_dwordx4 v[250:251], off
	s_waitcnt vmcnt(8)
	s_waitcnt lgkmcnt(0)
	s_setprio 1
	s_barrier
; #define PG8_STAGE(bufoff, gbase, voff) do { _Pragma("unroll") for (int _i = 0; _i < 2; ++_i) \
;         __builtin_amdgcn_global_load_lds((const unsigned*)((const char*)(gbase) + (voff)[_i]), (PG8_LAS unsigned*)(lds + (bufoff) + ldsw + _i * 8192), 16, 0, 0); } while (0)
; #define PG8_LDA(dst, b, h) do { _Pragma("unroll") for (int m = 0; m < 4; ++m) _Pragma("unroll") for (int k = 0; k < 2; ++k) dst[m][k] = *(const PG8_LAS bf16x8*)(lds + PG8_SA(b, h) + aoff + m * 2048 + k * 1024); } while (0)
; #define PG8_LDB(dst, b, h) do { _Pragma("unroll") for (int n = 0; n < 2; ++n) _Pragma("unroll") for (int k = 0; k < 2; ++k) dst[n][k] = *(const PG8_LAS bf16x8*)(lds + PG8_SB(b, h) + boff + n * 2048 + k * 1024); } while (0)
; #define PG8_MMA(ai, bj, At, Bt) do { __builtin_amdgcn_s_setprio(1); _Pragma("unroll") for (int m = 0; m < 4; ++m) _Pragma("unroll") for (int n = 0; n < 2; ++n) _Pragma("unroll") for (int k = 0; k < 2; ++k) \
;         acc[ai][bj][m][n] = __builtin_amdgcn_mfma_f32_16x16x32_bf16(Bt[n][k], At[m][k], acc[ai][bj][m][n], 0, 0, 0); __builtin_amdgcn_s_setprio(0); } while (0)
; #define PG8_WAIT_V(n) asm volatile("s_waitcnt vmcnt(" #n ")" ::: "memory")
; #define PG8_WAIT_L(n) asm volatile("s_waitcnt lgkmcnt(" #n ")" ::: "memory")
; #define PG8_BAR __builtin_amdgcn_s_barrier()
; #define PG8_SCHED __builtin_amdgcn_sched_barrier(0)
; template <class Epi, class Sched, bool ALIGN_EPI = false, bool SP2 = false>
; __device__ __forceinline__ void gemm_phase(PG8_LAS unsigned char* lds, const Gemm g, const Sched& S, const Epi& E) {
;     ...
;             PG8_WAIT_V(8); PG8_WAIT_L(0); PG8_BAR; PG8_MMA(0, 0, At, B0); PG8_MMA(0, 1, At, B1); PG8_BAR; PG8_SCHED;
;             PG8_LDA(At, 0, 1); PG8_STAGE(PG8_SB(0, 0), b2, voffB); PG8_STAGE(PG8_SB(0, 1), b2 + hstep, voffB); PG8_STAGE(PG8_SA(0, 0), a2, voffA);
;             PG8_WAIT_V(8); PG8_WAIT_L(0); PG8_BAR; PG8_MMA(1, 0, At, B0); PG8_MMA(1, 1, At, B1); PG8_BAR; PG8_SCHED;
;             PG8_LDB(B0, 1, 0); PG8_LDB(B1, 1, 1); PG8_SCHED; PG8_LDA(At, 1, 0); PG8_STAGE(PG8_SA(0, 1), a2 + hstep, voffA);
;             PG8_WAIT_V(8); PG8_WAIT_L(0); PG8_BAR; PG8_MMA(0, 0, At, B0); PG8_MMA(0, 1, At, B1); PG8_BAR; PG8_SCHED;
	v_mfma_f32_16x16x32_bf16 v[64:67], v[184:187], v[216:219], 0
	v_mfma_f32_16x16x32_bf16 v[60:63], v[192:195], v[216:219], 0
	v_mfma_f32_16x16x32_bf16 v[48:51], v[184:187], v[224:227], 0
	v_mfma_f32_16x16x32_bf16 v[44:47], v[192:195], v[224:227], 0
	v_mfma_f32_16x16x32_bf16 v[32:35], v[184:187], v[232:235], 0
	v_mfma_f32_16x16x32_bf16 v[28:31], v[192:195], v[232:235], 0
	v_mfma_f32_16x16x32_bf16 v[16:19], v[184:187], v[240:243], 0
	v_mfma_f32_16x16x32_bf16 v[12:15], v[192:195], v[240:243], 0
	v_mfma_f32_16x16x32_bf16 v[64:67], v[188:191], v[220:223], v[64:67]
	v_mfma_f32_16x16x32_bf16 v[60:63], v[196:199], v[220:223], v[60:63]
	v_mfma_f32_16x16x32_bf16 v[48:51], v[188:191], v[228:231], v[48:51]
	v_mfma_f32_16x16x32_bf16 v[44:47], v[196:199], v[228:231], v[44:47]
	v_mfma_f32_16x16x32_bf16 v[32:35], v[188:191], v[236:239], v[32:35]
	v_mfma_f32_16x16x32_bf16 v[28:31], v[196:199], v[236:239], v[28:31]
	v_mfma_f32_16x16x32_bf16 v[16:19], v[188:191], v[244:247], v[16:19]
	v_mfma_f32_16x16x32_bf16 v[12:15], v[196:199], v[244:247], v[12:15]
	v_mfma_f32_16x16x32_bf16 v[56:59], v[200:203], v[216:219], 0
	v_mfma_f32_16x16x32_bf16 v[52:55], v[208:211], v[216:219], 0
	v_mfma_f32_16x16x32_bf16 v[40:43], v[200:203], v[224:227], 0
	v_mfma_f32_16x16x32_bf16 v[36:39], v[208:211], v[224:227], 0
	v_mfma_f32_16x16x32_bf16 v[24:27], v[200:203], v[232:235], 0
	v_mfma_f32_16x16x32_bf16 v[20:23], v[208:211], v[232:235], 0
	v_mfma_f32_16x16x32_bf16 v[8:11], v[200:203], v[240:243], 0
	v_mfma_f32_16x16x32_bf16 v[4:7], v[208:211], v[240:243], 0
	v_mfma_f32_16x16x32_bf16 v[56:59], v[204:207], v[220:223], v[56:59]
	v_mfma_f32_16x16x32_bf16 v[52:55], v[212:215], v[220:223], v[52:55]
	v_mfma_f32_16x16x32_bf16 v[40:43], v[204:207], v[228:231], v[40:43]
	v_mfma_f32_16x16x32_bf16 v[36:39], v[212:215], v[228:231], v[36:39]
	v_mfma_f32_16x16x32_bf16 v[24:27], v[204:207], v[236:239], v[24:27]
	v_mfma_f32_16x16x32_bf16 v[20:23], v[212:215], v[236:239], v[20:23]
	v_mfma_f32_16x16x32_bf16 v[8:11], v[204:207], v[244:247], v[8:11]
	v_mfma_f32_16x16x32_bf16 v[4:7], v[212:215], v[244:247], v[4:7]
	s_barrier
	s_setprio 0
	s_add_i32 s63, 0, 0x18000
	v_add_u32_e32 v151, s63, v156
	s_add_i32 s64, 0, 0x1c000
	ds_read_b128 v[184:187], v151
	ds_read_b128 v[188:191], v151 offset:1024
	ds_read_b128 v[192:195], v151 offset:2048
	ds_read_b128 v[196:199], v151 offset:3072
	v_add_u32_e32 v151, s64, v156
	ds_read_b128 v[200:203], v151
	ds_read_b128 v[204:207], v151 offset:1024
	ds_read_b128 v[208:211], v151 offset:2048
	ds_read_b128 v[212:215], v151 offset:3072
	s_add_u32 s22, s22, 0x80000
	s_addc_u32 s23, s23, 0
	s_mov_b32 m0, s30
	ds_read_b128 v[216:219], v160 offset:32768
	ds_read_b128 v[220:223], v160 offset:33792
	ds_read_b128 v[224:227], v160 offset:34816
	ds_read_b128 v[228:231], v160 offset:35840
	ds_read_b128 v[232:235], v160 offset:36864
	ds_read_b128 v[236:239], v160 offset:37888
	ds_read_b128 v[240:243], v160 offset:38912
	ds_read_b128 v[244:247], v160 offset:39936
	global_load_lds_dwordx4 v134, s[22:23]
	s_mov_b32 m0, s31
	s_nop 0
	global_load_lds_dwordx4 v132, s[22:23]
	s_waitcnt vmcnt(8)
	s_waitcnt lgkmcnt(0)
	s_setprio 1
	s_barrier
	v_mfma_f32_16x16x32_bf16 v[128:131], v[184:187], v[216:219], v[128:131]
	v_mfma_f32_16x16x32_bf16 v[124:127], v[192:195], v[216:219], v[124:127]
	v_mfma_f32_16x16x32_bf16 v[112:115], v[184:187], v[224:227], v[112:115]
	v_mfma_f32_16x16x32_bf16 v[108:111], v[192:195], v[224:227], v[108:111]
	v_mfma_f32_16x16x32_bf16 v[96:99], v[184:187], v[232:235], v[96:99]
	v_mfma_f32_16x16x32_bf16 v[92:95], v[192:195], v[232:235], v[92:95]
	v_mfma_f32_16x16x32_bf16 v[80:83], v[184:187], v[240:243], v[80:83]
	v_mfma_f32_16x16x32_bf16 v[76:79], v[192:195], v[240:243], v[76:79]
	v_mfma_f32_16x16x32_bf16 v[128:131], v[188:191], v[220:223], v[128:131]
	v_mfma_f32_16x16x32_bf16 v[124:127], v[196:199], v[220:223], v[124:127]
	v_mfma_f32_16x16x32_bf16 v[112:115], v[188:191], v[228:231], v[112:115]
	v_mfma_f32_16x16x32_bf16 v[108:111], v[196:199], v[228:231], v[108:111]
	v_mfma_f32_16x16x32_bf16 v[96:99], v[188:191], v[236:239], v[96:99]
	v_mfma_f32_16x16x32_bf16 v[92:95], v[196:199], v[236:239], v[92:95]
	v_mfma_f32_16x16x32_bf16 v[80:83], v[188:191], v[244:247], v[80:83]
	v_mfma_f32_16x16x32_bf16 v[76:79], v[196:199], v[244:247], v[76:79]
	v_mfma_f32_16x16x32_bf16 v[120:123], v[200:203], v[216:219], v[120:123]
	v_mfma_f32_16x16x32_bf16 v[116:119], v[208:211], v[216:219], v[116:119]
	v_mfma_f32_16x16x32_bf16 v[104:107], v[200:203], v[224:227], v[104:107]
	v_mfma_f32_16x16x32_bf16 v[100:103], v[208:211], v[224:227], v[100:103]
	v_mfma_f32_16x16x32_bf16 v[88:91], v[200:203], v[232:235], v[88:91]
	v_mfma_f32_16x16x32_bf16 v[84:87], v[208:211], v[232:235], v[84:87]
	v_mfma_f32_16x16x32_bf16 v[72:75], v[200:203], v[240:243], v[72:75]
	v_mfma_f32_16x16x32_bf16 v[68:71], v[208:211], v[240:243], v[68:71]
	v_mfma_f32_16x16x32_bf16 v[120:123], v[204:207], v[220:223], v[120:123]
	v_mfma_f32_16x16x32_bf16 v[116:119], v[212:215], v[220:223], v[116:119]
	v_mfma_f32_16x16x32_bf16 v[104:107], v[204:207], v[228:231], v[104:107]
	v_mfma_f32_16x16x32_bf16 v[100:103], v[212:215], v[228:231], v[100:103]
	v_mfma_f32_16x16x32_bf16 v[88:91], v[204:207], v[236:239], v[88:91]
	v_mfma_f32_16x16x32_bf16 v[84:87], v[212:215], v[236:239], v[84:87]
	v_mfma_f32_16x16x32_bf16 v[72:75], v[204:207], v[244:247], v[72:75]
	v_mfma_f32_16x16x32_bf16 v[68:71], v[212:215], v[244:247], v[68:71]
	s_barrier
; #define PG8_STAGE(bufoff, gbase, voff) do { _Pragma("unroll") for (int _i = 0; _i < 2; ++_i) \
;         __builtin_amdgcn_global_load_lds((const unsigned*)((const char*)(gbase) + (voff)[_i]), (PG8_LAS unsigned*)(lds + (bufoff) + ldsw + _i * 8192), 16, 0, 0); } while (0)
; #define PG8_LDA(dst, b, h) do { _Pragma("unroll") for (int m = 0; m < 4; ++m) _Pragma("unroll") for (int k = 0; k < 2; ++k) dst[m][k] = *(const PG8_LAS bf16x8*)(lds + PG8_SA(b, h) + aoff + m * 2048 + k * 1024); } while (0)
; #define PG8_LDB(dst, b, h) do { _Pragma("unroll") for (int n = 0; n < 2; ++n) _Pragma("unroll") for (int k = 0; k < 2; ++k) dst[n][k] = *(const PG8_LAS bf16x8*)(lds + PG8_SB(b, h) + boff + n * 2048 + k * 1024); } while (0)
; #define PG8_WAIT_V(n) asm volatile("s_waitcnt vmcnt(" #n ")" ::: "memory")
; #define PG8_WAIT_L(n) asm volatile("s_waitcnt lgkmcnt(" #n ")" ::: "memory")
; #define PG8_BAR __builtin_amdgcn_s_barrier()
; template <class Epi, class Sched, bool ALIGN_EPI = false, bool SP2 = false>
; __device__ __forceinline__ void gemm_phase(PG8_LAS unsigned char* lds, const Gemm g, const Sched& S, const Epi& E) {
;     ...
;         for (int t = 0; t < nt; t += 2) {
;             const bool last = (t == nt - 2);
;             const char* a1 = cA + (size_t)(t + 1) * kstep;
;             const char* a2 = last ? nA : cA + (size_t)(t + 2) * kstep; const char* b2 = last ? nB : cB + (size_t)(t + 2) * kstep;
;             const char* a3 = a2 + kstep; const char* b3 = b2 + kstep;
;             if (last && has_next) S.a_ready(nxt);
;             if constexpr (SP2) {
;             PG8_LDB(B0, 0, 0); PG8_LDB(B1, 0, 1); PG8_SCHED; PG8_LDA(At, 0, 0); PG8_STAGE(PG8_SA(1, 1), a1 + hstep, voffA);
;             PG8_WAIT_V(8); PG8_WAIT_L(0); PG8_BAR; PG8_MMA(0, 0, At, B0); PG8_MMA(0, 1, At, B1); PG8_BAR; PG8_SCHED;
;             PG8_LDA(At, 0, 1); PG8_STAGE(PG8_SB(0, 0), b2, voffB); PG8_STAGE(PG8_SB(0, 1), b2 + hstep, voffB); PG8_STAGE(PG8_SA(0, 0), a2, voffA);
;             PG8_WAIT_V(8); PG8_WAIT_L(0); PG8_BAR; PG8_MMA(1, 0, At, B0); PG8_MMA(1, 1, At, B1); PG8_BAR; PG8_SCHED;
;     ...
;             PG8_LDA(At, 1, 1); PG8_STAGE(PG8_SB(1, 0), b3, voffB); PG8_STAGE(PG8_SB(1, 1), b3 + hstep, voffB); PG8_STAGE(PG8_SA(1, 0), a3, voffA);
;             PG8_WAIT_V(8); PG8_WAIT_L(0); PG8_BAR; PG8_MMA(1, 0, At, B0); PG8_MMA(1, 1, At, B1); PG8_BAR; PG8_SCHED;
	s_setprio 0
	s_add_i32 s22, s63, s27
	s_mov_b32 m0, s22
	ds_read_b128 v[216:219], v160 offset:49152
	ds_read_b128 v[220:223], v160 offset:50176
	ds_read_b128 v[224:227], v160 offset:51200
	ds_read_b128 v[228:231], v160 offset:52224
	ds_read_b128 v[232:235], v160 offset:53248
	ds_read_b128 v[236:239], v160 offset:54272
	ds_read_b128 v[240:243], v160 offset:55296
	ds_read_b128 v[244:247], v160 offset:56320
	s_add_u32 vcc_lo, s20, 0x80
	s_addc_u32 vcc_hi, s21, 0
	global_load_lds_dwordx4 v2, vcc
	s_add_i32 m0, s22, 0x2000
	s_add_u32 s20, s20, 0x80080
	s_addc_u32 s21, s21, 0
	s_add_i32 s22, s64, s27
	s_add_u32 vcc_lo, s20, 0xfff80000
	s_addc_u32 vcc_hi, s21, -1
	global_load_lds_dwordx4 v0, vcc
	s_mov_b32 m0, s22
	s_nop 0
	global_load_lds_dwordx4 v2, s[20:21]
	s_add_i32 m0, s22, 0x2000
	s_nop 0
	global_load_lds_dwordx4 v0, s[20:21]
	v_lshl_add_u64 v[152:153], v[248:249], 0, s[36:37]
	s_mov_b32 m0, s34
	s_nop 0
	global_load_lds_dwordx4 v[152:153], off
	v_lshl_add_u64 v[152:153], v[250:251], 0, s[36:37]
	s_mov_b32 m0, s35
	s_nop 0
	global_load_lds_dwordx4 v[152:153], off
	s_waitcnt vmcnt(8)
	s_waitcnt lgkmcnt(0)
	s_setprio 1
	s_barrier
	v_mfma_f32_16x16x32_bf16 v[64:67], v[184:187], v[216:219], v[64:67]
	v_mfma_f32_16x16x32_bf16 v[60:63], v[192:195], v[216:219], v[60:63]
	v_mfma_f32_16x16x32_bf16 v[48:51], v[184:187], v[224:227], v[48:51]
	v_mfma_f32_16x16x32_bf16 v[44:47], v[192:195], v[224:227], v[44:47]
	v_mfma_f32_16x16x32_bf16 v[32:35], v[184:187], v[232:235], v[32:35]
	v_mfma_f32_16x16x32_bf16 v[28:31], v[192:195], v[232:235], v[28:31]
	v_mfma_f32_16x16x32_bf16 v[16:19], v[184:187], v[240:243], v[16:19]
	v_mfma_f32_16x16x32_bf16 v[12:15], v[192:195], v[240:243], v[12:15]
	v_mfma_f32_16x16x32_bf16 v[64:67], v[188:191], v[220:223], v[64:67]
	v_mfma_f32_16x16x32_bf16 v[60:63], v[196:199], v[220:223], v[60:63]
	v_mfma_f32_16x16x32_bf16 v[48:51], v[188:191], v[228:231], v[48:51]
	v_mfma_f32_16x16x32_bf16 v[44:47], v[196:199], v[228:231], v[44:47]
	v_mfma_f32_16x16x32_bf16 v[32:35], v[188:191], v[236:239], v[32:35]
	v_mfma_f32_16x16x32_bf16 v[28:31], v[196:199], v[236:239], v[28:31]
	v_mfma_f32_16x16x32_bf16 v[16:19], v[188:191], v[244:247], v[16:19]
	v_mfma_f32_16x16x32_bf16 v[12:15], v[196:199], v[244:247], v[12:15]
	v_mfma_f32_16x16x32_bf16 v[56:59], v[200:203], v[216:219], v[56:59]
	v_mfma_f32_16x16x32_bf16 v[52:55], v[208:211], v[216:219], v[52:55]
	v_mfma_f32_16x16x32_bf16 v[40:43], v[200:203], v[224:227], v[40:43]
	v_mfma_f32_16x16x32_bf16 v[36:39], v[208:211], v[224:227], v[36:39]
	v_mfma_f32_16x16x32_bf16 v[24:27], v[200:203], v[232:235], v[24:27]
	v_mfma_f32_16x16x32_bf16 v[20:23], v[208:211], v[232:235], v[20:23]
	v_mfma_f32_16x16x32_bf16 v[8:11], v[200:203], v[240:243], v[8:11]
	v_mfma_f32_16x16x32_bf16 v[4:7], v[208:211], v[240:243], v[4:7]
	v_mfma_f32_16x16x32_bf16 v[56:59], v[204:207], v[220:223], v[56:59]
	v_mfma_f32_16x16x32_bf16 v[52:55], v[212:215], v[220:223], v[52:55]
	v_mfma_f32_16x16x32_bf16 v[40:43], v[204:207], v[228:231], v[40:43]
	v_mfma_f32_16x16x32_bf16 v[36:39], v[212:215], v[228:231], v[36:39]
	v_mfma_f32_16x16x32_bf16 v[24:27], v[204:207], v[236:239], v[24:27]
	v_mfma_f32_16x16x32_bf16 v[20:23], v[212:215], v[236:239], v[20:23]
	v_mfma_f32_16x16x32_bf16 v[8:11], v[204:207], v[244:247], v[8:11]
	v_mfma_f32_16x16x32_bf16 v[4:7], v[212:215], v[244:247], v[4:7]
	s_barrier
	s_setprio 0
	s_add_i32 s57, s57, 2
	s_add_u32 s18, s18, 0x100
	s_addc_u32 s19, s19, 0
	s_add_u32 s51, s51, 0x100
	s_addc_u32 s56, s56, 0
	s_cmp_gt_u32 s57, 29
.LBB0_251:
	s_add_u32 s20, s18, 0xfff80080
	s_addc_u32 s21, s19, -1
	s_add_i32 s63, 0, 0x10000
	s_cmp_eq_u32 s57, 28
	s_cselect_b32 s23, s11, s21
	s_cselect_b32 s22, s45, s20
	v_add_u32_e32 v151, s63, v156
	s_cselect_b32 s21, s7, s56
	s_cselect_b32 s20, s50, s51
	s_add_i32 s66, 0, 0x14000
	ds_read_b128 v[184:187], v151
	ds_read_b128 v[188:191], v151 offset:1024
	ds_read_b128 v[192:195], v151 offset:2048
	ds_read_b128 v[196:199], v151 offset:3072
	v_add_u32_e32 v151, s66, v156
	ds_read_b128 v[200:203], v151
	ds_read_b128 v[204:207], v151 offset:1024
	ds_read_b128 v[208:211], v151 offset:2048
	ds_read_b128 v[212:215], v151 offset:3072
	s_add_i32 m0, s17, 0xc000
	ds_read_b128 v[216:219], v160
	ds_read_b128 v[220:223], v160 offset:1024
	ds_read_b128 v[224:227], v160 offset:2048
	ds_read_b128 v[228:231], v160 offset:3072
	ds_read_b128 v[232:235], v160 offset:4096
	ds_read_b128 v[236:239], v160 offset:5120
	ds_read_b128 v[240:243], v160 offset:6144
	ds_read_b128 v[244:247], v160 offset:7168
	global_load_lds_dwordx4 v136, s[18:19]
	s_add_i32 m0, s17, 0xe000
	s_nop 0
	global_load_lds_dwordx4 v138, s[18:19]
	s_waitcnt vmcnt(8)
	s_waitcnt lgkmcnt(0)
	s_setprio 1
	s_barrier
; #define PG8_STAGE(bufoff, gbase, voff) do { _Pragma("unroll") for (int _i = 0; _i < 2; ++_i) \
;         __builtin_amdgcn_global_load_lds((const unsigned*)((const char*)(gbase) + (voff)[_i]), (PG8_LAS unsigned*)(lds + (bufoff) + ldsw + _i * 8192), 16, 0, 0); } while (0)
; #define PG8_LDA(dst, b, h) do { _Pragma("unroll") for (int m = 0; m < 4; ++m) _Pragma("unroll") for (int k = 0; k < 2; ++k) dst[m][k] = *(const PG8_LAS bf16x8*)(lds + PG8_SA(b, h) + aoff + m * 2048 + k * 1024); } while (0)
; #define PG8_LDB(dst, b, h) do { _Pragma("unroll") for (int n = 0; n < 2; ++n) _Pragma("unroll") for (int k = 0; k < 2; ++k) dst[n][k] = *(const PG8_LAS bf16x8*)(lds + PG8_SB(b, h) + boff + n * 2048 + k * 1024); } while (0)
; #define PG8_MMA(ai, bj, At, Bt) do { __builtin_amdgcn_s_setprio(1); _Pragma("unroll") for (int m = 0; m < 4; ++m) _Pragma("unroll") for (int n = 0; n < 2; ++n) _Pragma("unroll") for (int k = 0; k < 2; ++k) \
;         acc[ai][bj][m][n] = __builtin_amdgcn_mfma_f32_16x16x32_bf16(Bt[n][k], At[m][k], acc[ai][bj][m][n], 0, 0, 0); __builtin_amdgcn_s_setprio(0); } while (0)
; #define PG8_WAIT_V(n) asm volatile("s_waitcnt vmcnt(" #n ")" ::: "memory")
; #define PG8_WAIT_L(n) asm volatile("s_waitcnt lgkmcnt(" #n ")" ::: "memory")
; #define PG8_BAR __builtin_amdgcn_s_barrier()
; #define PG8_SCHED __builtin_amdgcn_sched_barrier(0)
; template <class Epi, class Sched, bool ALIGN_EPI = false, bool SP2 = false>
; __device__ __forceinline__ void gemm_phase(PG8_LAS unsigned char* lds, const Gemm g, const Sched& S, const Epi& E) {
;     ...
;             PG8_WAIT_V(8); PG8_WAIT_L(0); PG8_BAR; PG8_MMA(0, 0, At, B0); PG8_MMA(0, 1, At, B1); PG8_BAR; PG8_SCHED;
;             PG8_LDA(At, 0, 1); PG8_STAGE(PG8_SB(0, 0), b2, voffB); PG8_STAGE(PG8_SB(0, 1), b2 + hstep, voffB); PG8_STAGE(PG8_SA(0, 0), a2, voffA);
;             PG8_WAIT_V(8); PG8_WAIT_L(0); PG8_BAR; PG8_MMA(1, 0, At, B0); PG8_MMA(1, 1, At, B1); PG8_BAR; PG8_SCHED;
;             PG8_LDB(B0, 1, 0); PG8_LDB(B1, 1, 1); PG8_SCHED; PG8_LDA(At, 1, 0); PG8_STAGE(PG8_SA(0, 1), a2 + hstep, voffA);
;             PG8_WAIT_V(8); PG8_WAIT_L(0); PG8_BAR; PG8_MMA(0, 0, At, B0); PG8_MMA(0, 1, At, B1); PG8_BAR; PG8_SCHED;
	v_mfma_f32_16x16x32_bf16 v[128:131], v[184:187], v[216:219], v[128:131]
	v_mfma_f32_16x16x32_bf16 v[124:127], v[192:195], v[216:219], v[124:127]
	v_mfma_f32_16x16x32_bf16 v[112:115], v[184:187], v[224:227], v[112:115]
	v_mfma_f32_16x16x32_bf16 v[108:111], v[192:195], v[224:227], v[108:111]
	v_mfma_f32_16x16x32_bf16 v[96:99], v[184:187], v[232:235], v[96:99]
	v_mfma_f32_16x16x32_bf16 v[92:95], v[192:195], v[232:235], v[92:95]
	v_mfma_f32_16x16x32_bf16 v[80:83], v[184:187], v[240:243], v[80:83]
	v_mfma_f32_16x16x32_bf16 v[76:79], v[192:195], v[240:243], v[76:79]
	v_mfma_f32_16x16x32_bf16 v[128:131], v[188:191], v[220:223], v[128:131]
	v_mfma_f32_16x16x32_bf16 v[124:127], v[196:199], v[220:223], v[124:127]
	v_mfma_f32_16x16x32_bf16 v[112:115], v[188:191], v[228:231], v[112:115]
	v_mfma_f32_16x16x32_bf16 v[108:111], v[196:199], v[228:231], v[108:111]
	v_mfma_f32_16x16x32_bf16 v[96:99], v[188:191], v[236:239], v[96:99]
	v_mfma_f32_16x16x32_bf16 v[92:95], v[196:199], v[236:239], v[92:95]
	v_mfma_f32_16x16x32_bf16 v[80:83], v[188:191], v[244:247], v[80:83]
	v_mfma_f32_16x16x32_bf16 v[76:79], v[196:199], v[244:247], v[76:79]
	v_mfma_f32_16x16x32_bf16 v[120:123], v[200:203], v[216:219], v[120:123]
	v_mfma_f32_16x16x32_bf16 v[116:119], v[208:211], v[216:219], v[116:119]
	v_mfma_f32_16x16x32_bf16 v[104:107], v[200:203], v[224:227], v[104:107]
	v_mfma_f32_16x16x32_bf16 v[100:103], v[208:211], v[224:227], v[100:103]
	v_mfma_f32_16x16x32_bf16 v[88:91], v[200:203], v[232:235], v[88:91]
	v_mfma_f32_16x16x32_bf16 v[84:87], v[208:211], v[232:235], v[84:87]
	v_mfma_f32_16x16x32_bf16 v[72:75], v[200:203], v[240:243], v[72:75]
	v_mfma_f32_16x16x32_bf16 v[68:71], v[208:211], v[240:243], v[68:71]
	v_mfma_f32_16x16x32_bf16 v[120:123], v[204:207], v[220:223], v[120:123]
	v_mfma_f32_16x16x32_bf16 v[116:119], v[212:215], v[220:223], v[116:119]
	v_mfma_f32_16x16x32_bf16 v[104:107], v[204:207], v[228:231], v[104:107]
	v_mfma_f32_16x16x32_bf16 v[100:103], v[212:215], v[228:231], v[100:103]
	v_mfma_f32_16x16x32_bf16 v[88:91], v[204:207], v[236:239], v[88:91]
	v_mfma_f32_16x16x32_bf16 v[84:87], v[212:215], v[236:239], v[84:87]
	v_mfma_f32_16x16x32_bf16 v[72:75], v[204:207], v[244:247], v[72:75]
	v_mfma_f32_16x16x32_bf16 v[68:71], v[212:215], v[244:247], v[68:71]
	s_barrier
	s_setprio 0
	s_add_i32 s63, s63, s27
	s_mov_b32 m0, s63
	ds_read_b128 v[216:219], v160 offset:16384
	ds_read_b128 v[220:223], v160 offset:17408
	ds_read_b128 v[224:227], v160 offset:18432
	ds_read_b128 v[228:231], v160 offset:19456
	ds_read_b128 v[232:235], v160 offset:20480
	ds_read_b128 v[236:239], v160 offset:21504
	ds_read_b128 v[240:243], v160 offset:22528
	ds_read_b128 v[244:247], v160 offset:23552
	global_load_lds_dwordx4 v2, s[20:21]
	s_add_i32 m0, s63, 0x2000
	s_add_u32 s64, s20, 0x80000
	s_addc_u32 s65, s21, 0
	s_add_i32 s63, s66, s27
	global_load_lds_dwordx4 v0, s[20:21]
	s_mov_b32 m0, s63
	v_lshl_add_u64 v[250:251], s[22:23], 0, v[132:133]
	global_load_lds_dwordx4 v2, s[64:65]
	s_add_i32 m0, s63, 0x2000
	s_nop 0
	global_load_lds_dwordx4 v0, s[64:65]
	v_lshl_add_u64 v[248:249], s[22:23], 0, v[134:135]
	s_mov_b32 m0, s17
	s_nop 0
	global_load_lds_dwordx4 v[248:249], off
	s_mov_b32 m0, s29
	s_nop 0
	global_load_lds_dwordx4 v[250:251], off
	s_waitcnt vmcnt(8)
	s_waitcnt lgkmcnt(0)
	s_setprio 1
	s_barrier
	v_mfma_f32_16x16x32_bf16 v[64:67], v[184:187], v[216:219], v[64:67]
	v_mfma_f32_16x16x32_bf16 v[60:63], v[192:195], v[216:219], v[60:63]
	v_mfma_f32_16x16x32_bf16 v[48:51], v[184:187], v[224:227], v[48:51]
	v_mfma_f32_16x16x32_bf16 v[44:47], v[192:195], v[224:227], v[44:47]
	v_mfma_f32_16x16x32_bf16 v[32:35], v[184:187], v[232:235], v[32:35]
	v_mfma_f32_16x16x32_bf16 v[28:31], v[192:195], v[232:235], v[28:31]
	v_mfma_f32_16x16x32_bf16 v[16:19], v[184:187], v[240:243], v[16:19]
	v_mfma_f32_16x16x32_bf16 v[12:15], v[192:195], v[240:243], v[12:15]
	v_mfma_f32_16x16x32_bf16 v[64:67], v[188:191], v[220:223], v[64:67]
	v_mfma_f32_16x16x32_bf16 v[60:63], v[196:199], v[220:223], v[60:63]
	v_mfma_f32_16x16x32_bf16 v[48:51], v[188:191], v[228:231], v[48:51]
	v_mfma_f32_16x16x32_bf16 v[44:47], v[196:199], v[228:231], v[44:47]
	v_mfma_f32_16x16x32_bf16 v[32:35], v[188:191], v[236:239], v[32:35]
	v_mfma_f32_16x16x32_bf16 v[28:31], v[196:199], v[236:239], v[28:31]
	v_mfma_f32_16x16x32_bf16 v[16:19], v[188:191], v[244:247], v[16:19]
	v_mfma_f32_16x16x32_bf16 v[12:15], v[196:199], v[244:247], v[12:15]
	v_mfma_f32_16x16x32_bf16 v[56:59], v[200:203], v[216:219], v[56:59]
	v_mfma_f32_16x16x32_bf16 v[52:55], v[208:211], v[216:219], v[52:55]
	v_mfma_f32_16x16x32_bf16 v[40:43], v[200:203], v[224:227], v[40:43]
	v_mfma_f32_16x16x32_bf16 v[36:39], v[208:211], v[224:227], v[36:39]
	v_mfma_f32_16x16x32_bf16 v[24:27], v[200:203], v[232:235], v[24:27]
	v_mfma_f32_16x16x32_bf16 v[20:23], v[208:211], v[232:235], v[20:23]
	v_mfma_f32_16x16x32_bf16 v[8:11], v[200:203], v[240:243], v[8:11]
	v_mfma_f32_16x16x32_bf16 v[4:7], v[208:211], v[240:243], v[4:7]
	v_mfma_f32_16x16x32_bf16 v[56:59], v[204:207], v[220:223], v[56:59]
	v_mfma_f32_16x16x32_bf16 v[52:55], v[212:215], v[220:223], v[52:55]
	v_mfma_f32_16x16x32_bf16 v[40:43], v[204:207], v[228:231], v[40:43]
	v_mfma_f32_16x16x32_bf16 v[36:39], v[212:215], v[228:231], v[36:39]
	v_mfma_f32_16x16x32_bf16 v[24:27], v[204:207], v[236:239], v[24:27]
	v_mfma_f32_16x16x32_bf16 v[20:23], v[212:215], v[236:239], v[20:23]
	v_mfma_f32_16x16x32_bf16 v[8:11], v[204:207], v[244:247], v[8:11]
	v_mfma_f32_16x16x32_bf16 v[4:7], v[212:215], v[244:247], v[4:7]
	s_barrier
; #define PG8_STAGE(bufoff, gbase, voff) do { _Pragma("unroll") for (int _i = 0; _i < 2; ++_i) \
;         __builtin_amdgcn_global_load_lds((const unsigned*)((const char*)(gbase) + (voff)[_i]), (PG8_LAS unsigned*)(lds + (bufoff) + ldsw + _i * 8192), 16, 0, 0); } while (0)
; #define PG8_LDA(dst, b, h) do { _Pragma("unroll") for (int m = 0; m < 4; ++m) _Pragma("unroll") for (int k = 0; k < 2; ++k) dst[m][k] = *(const PG8_LAS bf16x8*)(lds + PG8_SA(b, h) + aoff + m * 2048 + k * 1024); } while (0)
; #define PG8_LDB(dst, b, h) do { _Pragma("unroll") for (int n = 0; n < 2; ++n) _Pragma("unroll") for (int k = 0; k < 2; ++k) dst[n][k] = *(const PG8_LAS bf16x8*)(lds + PG8_SB(b, h) + boff + n * 2048 + k * 1024); } while (0)
; #define PG8_MMA(ai, bj, At, Bt) do { __builtin_amdgcn_s_setprio(1); _Pragma("unroll") for (int m = 0; m < 4; ++m) _Pragma("unroll") for (int n = 0; n < 2; ++n) _Pragma("unroll") for (int k = 0; k < 2; ++k) \
;         acc[ai][bj][m][n] = __builtin_amdgcn_mfma_f32_16x16x32_bf16(Bt[n][k], At[m][k], acc[ai][bj][m][n], 0, 0, 0); __builtin_amdgcn_s_setprio(0); } while (0)
; #define PG8_WAIT_V(n) asm volatile("s_waitcnt vmcnt(" #n ")" ::: "memory")
; #define PG8_WAIT_L(n) asm volatile("s_waitcnt lgkmcnt(" #n ")" ::: "memory")
; #define PG8_BAR __builtin_amdgcn_s_barrier()
; #define PG8_SCHED __builtin_amdgcn_sched_barrier(0)
; template <class Epi, class Sched, bool ALIGN_EPI = false, bool SP2 = false>
; __device__ __forceinline__ void gemm_phase(PG8_LAS unsigned char* lds, const Gemm g, const Sched& S, const Epi& E) {
;     ...
;             PG8_LDB(B0, 1, 0); PG8_LDB(B1, 1, 1); PG8_SCHED; PG8_LDA(At, 1, 0); PG8_STAGE(PG8_SA(0, 1), a2 + hstep, voffA);
;             PG8_WAIT_V(8); PG8_WAIT_L(0); PG8_BAR; PG8_MMA(0, 0, At, B0); PG8_MMA(0, 1, At, B1); PG8_BAR; PG8_SCHED;
;             PG8_LDA(At, 1, 1); PG8_STAGE(PG8_SB(1, 0), b3, voffB); PG8_STAGE(PG8_SB(1, 1), b3 + hstep, voffB); PG8_STAGE(PG8_SA(1, 0), a3, voffA);
;             PG8_WAIT_V(8); PG8_WAIT_L(0); PG8_BAR; PG8_MMA(1, 0, At, B0); PG8_MMA(1, 1, At, B1); PG8_BAR; PG8_SCHED;
;     ...
;         if constexpr (ALIGN_EPI) { if (wr == 0) PG8_BAR; }
	s_setprio 0
	s_add_i32 s63, 0, 0x18000
	v_add_u32_e32 v151, s63, v156
	s_add_i32 s64, 0, 0x1c000
	ds_read_b128 v[184:187], v151
	ds_read_b128 v[188:191], v151 offset:1024
	ds_read_b128 v[192:195], v151 offset:2048
	ds_read_b128 v[196:199], v151 offset:3072
	v_add_u32_e32 v151, s64, v156
	ds_read_b128 v[200:203], v151
	ds_read_b128 v[204:207], v151 offset:1024
	ds_read_b128 v[208:211], v151 offset:2048
	ds_read_b128 v[212:215], v151 offset:3072
	s_add_u32 s22, s22, 0x80000
	s_addc_u32 s23, s23, 0
	s_mov_b32 m0, s30
	ds_read_b128 v[216:219], v160 offset:32768
	ds_read_b128 v[220:223], v160 offset:33792
	ds_read_b128 v[224:227], v160 offset:34816
	ds_read_b128 v[228:231], v160 offset:35840
	ds_read_b128 v[232:235], v160 offset:36864
	ds_read_b128 v[236:239], v160 offset:37888
	ds_read_b128 v[240:243], v160 offset:38912
	ds_read_b128 v[244:247], v160 offset:39936
	global_load_lds_dwordx4 v134, s[22:23]
	s_mov_b32 m0, s31
	s_nop 0
	global_load_lds_dwordx4 v132, s[22:23]
	s_waitcnt vmcnt(8)
	s_waitcnt lgkmcnt(0)
	s_setprio 1
	s_barrier
	v_mfma_f32_16x16x32_bf16 v[128:131], v[184:187], v[216:219], v[128:131]
	v_mfma_f32_16x16x32_bf16 v[124:127], v[192:195], v[216:219], v[124:127]
	v_mfma_f32_16x16x32_bf16 v[112:115], v[184:187], v[224:227], v[112:115]
	v_mfma_f32_16x16x32_bf16 v[108:111], v[192:195], v[224:227], v[108:111]
	v_mfma_f32_16x16x32_bf16 v[96:99], v[184:187], v[232:235], v[96:99]
	v_mfma_f32_16x16x32_bf16 v[92:95], v[192:195], v[232:235], v[92:95]
	v_mfma_f32_16x16x32_bf16 v[80:83], v[184:187], v[240:243], v[80:83]
	v_mfma_f32_16x16x32_bf16 v[76:79], v[192:195], v[240:243], v[76:79]
	v_mfma_f32_16x16x32_bf16 v[128:131], v[188:191], v[220:223], v[128:131]
	v_mfma_f32_16x16x32_bf16 v[124:127], v[196:199], v[220:223], v[124:127]
	v_mfma_f32_16x16x32_bf16 v[112:115], v[188:191], v[228:231], v[112:115]
	v_mfma_f32_16x16x32_bf16 v[108:111], v[196:199], v[228:231], v[108:111]
	v_mfma_f32_16x16x32_bf16 v[96:99], v[188:191], v[236:239], v[96:99]
	v_mfma_f32_16x16x32_bf16 v[92:95], v[196:199], v[236:239], v[92:95]
	v_mfma_f32_16x16x32_bf16 v[80:83], v[188:191], v[244:247], v[80:83]
	v_mfma_f32_16x16x32_bf16 v[76:79], v[196:199], v[244:247], v[76:79]
	v_mfma_f32_16x16x32_bf16 v[120:123], v[200:203], v[216:219], v[120:123]
	v_mfma_f32_16x16x32_bf16 v[116:119], v[208:211], v[216:219], v[116:119]
	v_mfma_f32_16x16x32_bf16 v[104:107], v[200:203], v[224:227], v[104:107]
	v_mfma_f32_16x16x32_bf16 v[100:103], v[208:211], v[224:227], v[100:103]
	v_mfma_f32_16x16x32_bf16 v[88:91], v[200:203], v[232:235], v[88:91]
	v_mfma_f32_16x16x32_bf16 v[84:87], v[208:211], v[232:235], v[84:87]
	v_mfma_f32_16x16x32_bf16 v[72:75], v[200:203], v[240:243], v[72:75]
	v_mfma_f32_16x16x32_bf16 v[68:71], v[208:211], v[240:243], v[68:71]
	v_mfma_f32_16x16x32_bf16 v[120:123], v[204:207], v[220:223], v[120:123]
	v_mfma_f32_16x16x32_bf16 v[116:119], v[212:215], v[220:223], v[116:119]
	v_mfma_f32_16x16x32_bf16 v[104:107], v[204:207], v[228:231], v[104:107]
	v_mfma_f32_16x16x32_bf16 v[100:103], v[212:215], v[228:231], v[100:103]
	v_mfma_f32_16x16x32_bf16 v[88:91], v[204:207], v[236:239], v[88:91]
	v_mfma_f32_16x16x32_bf16 v[84:87], v[212:215], v[236:239], v[84:87]
	v_mfma_f32_16x16x32_bf16 v[72:75], v[204:207], v[244:247], v[72:75]
	v_mfma_f32_16x16x32_bf16 v[68:71], v[212:215], v[244:247], v[68:71]
	s_barrier
	s_setprio 0
	s_add_i32 s22, s63, s27
	s_mov_b32 m0, s22
	ds_read_b128 v[216:219], v160 offset:49152
	ds_read_b128 v[220:223], v160 offset:50176
	ds_read_b128 v[224:227], v160 offset:51200
	ds_read_b128 v[228:231], v160 offset:52224
	ds_read_b128 v[232:235], v160 offset:53248
	ds_read_b128 v[236:239], v160 offset:54272
	ds_read_b128 v[240:243], v160 offset:55296
	ds_read_b128 v[244:247], v160 offset:56320
	s_add_u32 vcc_lo, s20, 0x80
	s_addc_u32 vcc_hi, s21, 0
	global_load_lds_dwordx4 v2, vcc
	s_add_i32 m0, s22, 0x2000
	s_add_u32 s20, s20, 0x80080
	s_addc_u32 s21, s21, 0
	s_add_i32 s22, s64, s27
	s_add_u32 vcc_lo, s20, 0xfff80000
	s_addc_u32 vcc_hi, s21, -1
	global_load_lds_dwordx4 v0, vcc
	s_mov_b32 m0, s22
	s_nop 0
	global_load_lds_dwordx4 v2, s[20:21]
	s_add_i32 m0, s22, 0x2000
	s_nop 0
	global_load_lds_dwordx4 v0, s[20:21]
	v_lshl_add_u64 v[152:153], v[248:249], 0, s[36:37]
	s_mov_b32 m0, s34
	s_nop 0
	global_load_lds_dwordx4 v[152:153], off
	v_lshl_add_u64 v[152:153], v[250:251], 0, s[36:37]
	s_mov_b32 m0, s35
	s_nop 0
	global_load_lds_dwordx4 v[152:153], off
	s_waitcnt vmcnt(8)
	s_waitcnt lgkmcnt(0)
	s_setprio 1
	s_barrier
	v_mfma_f32_16x16x32_bf16 v[64:67], v[184:187], v[216:219], v[64:67]
	v_mfma_f32_16x16x32_bf16 v[60:63], v[192:195], v[216:219], v[60:63]
	v_mfma_f32_16x16x32_bf16 v[48:51], v[184:187], v[224:227], v[48:51]
	v_mfma_f32_16x16x32_bf16 v[44:47], v[192:195], v[224:227], v[44:47]
	v_mfma_f32_16x16x32_bf16 v[32:35], v[184:187], v[232:235], v[32:35]
	v_mfma_f32_16x16x32_bf16 v[28:31], v[192:195], v[232:235], v[28:31]
	v_mfma_f32_16x16x32_bf16 v[16:19], v[184:187], v[240:243], v[16:19]
	v_mfma_f32_16x16x32_bf16 v[12:15], v[192:195], v[240:243], v[12:15]
	v_mfma_f32_16x16x32_bf16 v[64:67], v[188:191], v[220:223], v[64:67]
	v_mfma_f32_16x16x32_bf16 v[60:63], v[196:199], v[220:223], v[60:63]
	v_mfma_f32_16x16x32_bf16 v[48:51], v[188:191], v[228:231], v[48:51]
	v_mfma_f32_16x16x32_bf16 v[44:47], v[196:199], v[228:231], v[44:47]
	v_mfma_f32_16x16x32_bf16 v[32:35], v[188:191], v[236:239], v[32:35]
	v_mfma_f32_16x16x32_bf16 v[28:31], v[196:199], v[236:239], v[28:31]
	v_mfma_f32_16x16x32_bf16 v[16:19], v[188:191], v[244:247], v[16:19]
	v_mfma_f32_16x16x32_bf16 v[12:15], v[196:199], v[244:247], v[12:15]
	v_mfma_f32_16x16x32_bf16 v[56:59], v[200:203], v[216:219], v[56:59]
	v_mfma_f32_16x16x32_bf16 v[52:55], v[208:211], v[216:219], v[52:55]
	v_mfma_f32_16x16x32_bf16 v[40:43], v[200:203], v[224:227], v[40:43]
	v_mfma_f32_16x16x32_bf16 v[36:39], v[208:211], v[224:227], v[36:39]
	v_mfma_f32_16x16x32_bf16 v[24:27], v[200:203], v[232:235], v[24:27]
	v_mfma_f32_16x16x32_bf16 v[20:23], v[208:211], v[232:235], v[20:23]
	v_mfma_f32_16x16x32_bf16 v[8:11], v[200:203], v[240:243], v[8:11]
	v_mfma_f32_16x16x32_bf16 v[4:7], v[208:211], v[240:243], v[4:7]
	v_mfma_f32_16x16x32_bf16 v[56:59], v[204:207], v[220:223], v[56:59]
	v_mfma_f32_16x16x32_bf16 v[52:55], v[212:215], v[220:223], v[52:55]
	v_mfma_f32_16x16x32_bf16 v[40:43], v[204:207], v[228:231], v[40:43]
	v_mfma_f32_16x16x32_bf16 v[36:39], v[212:215], v[228:231], v[36:39]
	v_mfma_f32_16x16x32_bf16 v[24:27], v[204:207], v[236:239], v[24:27]
	v_mfma_f32_16x16x32_bf16 v[20:23], v[212:215], v[236:239], v[20:23]
	v_mfma_f32_16x16x32_bf16 v[8:11], v[204:207], v[244:247], v[8:11]
	v_mfma_f32_16x16x32_bf16 v[4:7], v[212:215], v[244:247], v[4:7]
	s_barrier
	s_setprio 0
	s_add_i32 s57, s57, 2
	s_add_u32 s18, s18, 0x100
	s_addc_u32 s19, s19, 0
	s_add_u32 s51, s51, 0x100
	s_addc_u32 s56, s56, 0
	s_cmp_gt_u32 s57, 29
	s_cbranch_scc0 .LBB0_251
	s_and_b64 vcc, exec, s[4:5]
	s_cbranch_vccz .LBB0_254
	s_barrier

; #define PG8_STAGE(bufoff, gbase, voff) do { _Pragma("unroll") for (int _i = 0; _i < 2; ++_i) \
;         __builtin_amdgcn_global_load_lds((const unsigned*)((const char*)(gbase) + (voff)[_i]), (PG8_LAS unsigned*)(lds + (bufoff) + ldsw + _i * 8192), 16, 0, 0); } while (0)
; #define PG8_LDA(dst, b, h) do { _Pragma("unroll") for (int m = 0; m < 4; ++m) _Pragma("unroll") for (int k = 0; k < 2; ++k) dst[m][k] = *(const PG8_LAS bf16x8*)(lds + PG8_SA(b, h) + aoff + m * 2048 + k * 1024); } while (0)
; #define PG8_LDB(dst, b, h) do { _Pragma("unroll") for (int n = 0; n < 2; ++n) _Pragma("unroll") for (int k = 0; k < 2; ++k) dst[n][k] = *(const PG8_LAS bf16x8*)(lds + PG8_SB(b, h) + boff + n * 2048 + k * 1024); } while (0)
; #define PG8_WAIT_V(n) asm volatile("s_waitcnt vmcnt(" #n ")" ::: "memory")
; #define PG8_WAIT_L(n) asm volatile("s_waitcnt lgkmcnt(" #n ")" ::: "memory")
; #define PG8_BAR __builtin_amdgcn_s_barrier()
; #define PG8_SCHED __builtin_amdgcn_sched_barrier(0)
; template <class Epi, class Sched, bool ALIGN_EPI = false, bool SP2 = false>
; __device__ __forceinline__ void gemm_phase(PG8_LAS unsigned char* lds, const Gemm g, const Sched& S, const Epi& E) {
;     ...
;         const bool has_next = S.next(ui + 1, nxt);
;         const char* nA = has_next ? (const char*)g.A + (size_t)nxt.pm * tstep : cA; const char* nB = has_next ? (const char*)g.Bt + (size_t)nxt.pn * tstep : cB;
;         for (int t = 0; t < nt; t += 2) {
;             const bool last = (t == nt - 2);
;             const char* a1 = cA + (size_t)(t + 1) * kstep;
;             const char* a2 = last ? nA : cA + (size_t)(t + 2) * kstep; const char* b2 = last ? nB : cB + (size_t)(t + 2) * kstep;
;             const char* a3 = a2 + kstep; const char* b3 = b2 + kstep;
;             if (last && has_next) S.a_ready(nxt);
;             if constexpr (SP2) {
;             PG8_LDB(B0, 0, 0); PG8_LDB(B1, 0, 1); PG8_SCHED; PG8_LDA(At, 0, 0); PG8_STAGE(PG8_SA(1, 1), a1 + hstep, voffA);
;             PG8_WAIT_V(8); PG8_WAIT_L(0); PG8_BAR; PG8_MMA(0, 0, At, B0); PG8_MMA(0, 1, At, B1); PG8_BAR; PG8_SCHED;
;             PG8_LDA(At, 0, 1); PG8_STAGE(PG8_SB(0, 0), b2, voffB); PG8_STAGE(PG8_SB(0, 1), b2 + hstep, voffB); PG8_STAGE(PG8_SA(0, 0), a2, voffA);
;             PG8_WAIT_V(8); PG8_WAIT_L(0); PG8_BAR; PG8_MMA(1, 0, At, B0); PG8_MMA(1, 1, At, B1); PG8_BAR; PG8_SCHED;
.LBB0_482:
	s_ashr_i32 s13, s12, 31
	s_lshl_b64 s[14:15], s[12:13], 20
	s_add_u32 s14, s54, s14
	s_addc_u32 s15, s55, s15
	s_and_b64 s[16:17], s[4:5], exec
	s_cselect_b32 s13, s15, s23
	s_cselect_b32 s19, s14, s22
	s_ashr_i32 s11, s10, 31
	s_lshl_b64 s[16:17], s[10:11], 20
	s_add_u32 s16, s29, s16
	s_addc_u32 s17, s30, s17
	s_and_b64 s[26:27], s[4:5], exec
	s_cselect_b32 s11, s17, s25
	s_cselect_b32 s56, s16, s24
	s_add_u32 s22, s22, 0x80080
	s_addc_u32 s23, s23, 0
	s_add_u32 s57, s24, 0x100
	s_addc_u32 s63, s25, 0
	s_mov_b32 s64, -2
	s_waitcnt lgkmcnt(0)
	s_add_u32 s24, s22, 0xfff80080
	s_addc_u32 s25, s23, -1
	s_add_i32 s65, 0, 0x10000
	s_cmp_eq_u32 s64, 28
	s_cselect_b32 s27, s13, s25
	s_cselect_b32 s26, s19, s24
	s_cselect_b32 s25, s11, s63
	s_cselect_b32 s24, s56, s57
	s_add_i32 s76, 0, 0x14000
	v_add_u32_e32 v162, s65, v185
	v_add_u32_e32 v166, s76, v185
	ds_read_b128 v[132:135], v162
	ds_read_b128 v[136:139], v162 offset:1024
	ds_read_b128 v[158:161], v162 offset:2048
	ds_read_b128 v[162:165], v162 offset:3072
	ds_read_b128 v[188:191], v166
	ds_read_b128 v[192:195], v166 offset:1024
	ds_read_b128 v[196:199], v166 offset:2048
	ds_read_b128 v[200:203], v166 offset:3072
	s_add_i32 m0, s21, 0xc000
	ds_read_b128 v[204:207], v187
	ds_read_b128 v[208:211], v187 offset:1024
	ds_read_b128 v[212:215], v187 offset:2048
	ds_read_b128 v[216:219], v187 offset:3072
	ds_read_b128 v[220:223], v187 offset:4096
	ds_read_b128 v[224:227], v187 offset:5120
	ds_read_b128 v[228:231], v187 offset:6144
	ds_read_b128 v[232:235], v187 offset:7168
	global_load_lds_dwordx4 v154, s[22:23]
	s_add_i32 m0, s21, 0xe000
	s_nop 0
	global_load_lds_dwordx4 v156, s[22:23]
	s_waitcnt vmcnt(8)
	s_waitcnt lgkmcnt(0)
	s_setprio 1
	s_barrier
	v_mfma_f32_16x16x32_bf16 v[128:131], v[132:135], v[204:207], 0
	v_mfma_f32_16x16x32_bf16 v[124:127], v[158:161], v[204:207], 0
	v_mfma_f32_16x16x32_bf16 v[112:115], v[132:135], v[212:215], 0
	v_mfma_f32_16x16x32_bf16 v[108:111], v[158:161], v[212:215], 0
	v_mfma_f32_16x16x32_bf16 v[96:99], v[132:135], v[220:223], 0
	v_mfma_f32_16x16x32_bf16 v[92:95], v[158:161], v[220:223], 0
	v_mfma_f32_16x16x32_bf16 v[80:83], v[132:135], v[228:231], 0
	v_mfma_f32_16x16x32_bf16 v[76:79], v[158:161], v[228:231], 0
	v_mfma_f32_16x16x32_bf16 v[128:131], v[136:139], v[208:211], v[128:131]
	v_mfma_f32_16x16x32_bf16 v[124:127], v[162:165], v[208:211], v[124:127]
	v_mfma_f32_16x16x32_bf16 v[112:115], v[136:139], v[216:219], v[112:115]
	v_mfma_f32_16x16x32_bf16 v[108:111], v[162:165], v[216:219], v[108:111]
	v_mfma_f32_16x16x32_bf16 v[96:99], v[136:139], v[224:227], v[96:99]
	v_mfma_f32_16x16x32_bf16 v[92:95], v[162:165], v[224:227], v[92:95]
	v_mfma_f32_16x16x32_bf16 v[80:83], v[136:139], v[232:235], v[80:83]
	v_mfma_f32_16x16x32_bf16 v[76:79], v[162:165], v[232:235], v[76:79]
	v_mfma_f32_16x16x32_bf16 v[120:123], v[188:191], v[204:207], 0
	v_mfma_f32_16x16x32_bf16 v[116:119], v[196:199], v[204:207], 0
	v_mfma_f32_16x16x32_bf16 v[104:107], v[188:191], v[212:215], 0
	v_mfma_f32_16x16x32_bf16 v[100:103], v[196:199], v[212:215], 0
	v_mfma_f32_16x16x32_bf16 v[88:91], v[188:191], v[220:223], 0
	v_mfma_f32_16x16x32_bf16 v[84:87], v[196:199], v[220:223], 0
	v_mfma_f32_16x16x32_bf16 v[72:75], v[188:191], v[228:231], 0
	v_mfma_f32_16x16x32_bf16 v[68:71], v[196:199], v[228:231], 0
	v_mfma_f32_16x16x32_bf16 v[120:123], v[192:195], v[208:211], v[120:123]
	v_mfma_f32_16x16x32_bf16 v[116:119], v[200:203], v[208:211], v[116:119]
	v_mfma_f32_16x16x32_bf16 v[104:107], v[192:195], v[216:219], v[104:107]
	v_mfma_f32_16x16x32_bf16 v[100:103], v[200:203], v[216:219], v[100:103]
	v_mfma_f32_16x16x32_bf16 v[88:91], v[192:195], v[224:227], v[88:91]
	v_mfma_f32_16x16x32_bf16 v[84:87], v[200:203], v[224:227], v[84:87]
	v_mfma_f32_16x16x32_bf16 v[72:75], v[192:195], v[232:235], v[72:75]
	v_mfma_f32_16x16x32_bf16 v[68:71], v[200:203], v[232:235], v[68:71]
	s_barrier
	s_setprio 0
	s_add_i32 s65, s65, s31
	s_mov_b32 m0, s65
	ds_read_b128 v[204:207], v187 offset:16384
	ds_read_b128 v[208:211], v187 offset:17408
	ds_read_b128 v[212:215], v187 offset:18432
	ds_read_b128 v[216:219], v187 offset:19456
	ds_read_b128 v[220:223], v187 offset:20480
	ds_read_b128 v[224:227], v187 offset:21504
	ds_read_b128 v[228:231], v187 offset:22528
	ds_read_b128 v[232:235], v187 offset:23552
	global_load_lds_dwordx4 v2, s[24:25]
	s_add_i32 m0, s65, 0x2000
	s_add_u32 s66, s24, 0x80000
	s_addc_u32 s67, s25, 0
	s_add_i32 s65, s76, s31
	global_load_lds_dwordx4 v152, s[24:25]
	s_mov_b32 m0, s65
	v_lshl_add_u64 v[240:241], s[26:27], 0, v[150:151]
	global_load_lds_dwordx4 v2, s[66:67]
	s_add_i32 m0, s65, 0x2000
	s_nop 0
	global_load_lds_dwordx4 v152, s[66:67]
	v_lshl_add_u64 v[238:239], s[26:27], 0, v[0:1]
	s_mov_b32 m0, s21
	s_nop 0
	global_load_lds_dwordx4 v[238:239], off
	s_mov_b32 m0, s34
	s_nop 0
	global_load_lds_dwordx4 v[240:241], off
	s_waitcnt vmcnt(8)
	s_waitcnt lgkmcnt(0)
	s_setprio 1
	s_barrier
; #define PG8_STAGE(bufoff, gbase, voff) do { _Pragma("unroll") for (int _i = 0; _i < 2; ++_i) \
;         __builtin_amdgcn_global_load_lds((const unsigned*)((const char*)(gbase) + (voff)[_i]), (PG8_LAS unsigned*)(lds + (bufoff) + ldsw + _i * 8192), 16, 0, 0); } while (0)
; #define PG8_LDA(dst, b, h) do { _Pragma("unroll") for (int m = 0; m < 4; ++m) _Pragma("unroll") for (int k = 0; k < 2; ++k) dst[m][k] = *(const PG8_LAS bf16x8*)(lds + PG8_SA(b, h) + aoff + m * 2048 + k * 1024); } while (0)
; #define PG8_LDB(dst, b, h) do { _Pragma("unroll") for (int n = 0; n < 2; ++n) _Pragma("unroll") for (int k = 0; k < 2; ++k) dst[n][k] = *(const PG8_LAS bf16x8*)(lds + PG8_SB(b, h) + boff + n * 2048 + k * 1024); } while (0)
; #define PG8_MMA(ai, bj, At, Bt) do { __builtin_amdgcn_s_setprio(1); _Pragma("unroll") for (int m = 0; m < 4; ++m) _Pragma("unroll") for (int n = 0; n < 2; ++n) _Pragma("unroll") for (int k = 0; k < 2; ++k) \
;         acc[ai][bj][m][n] = __builtin_amdgcn_mfma_f32_16x16x32_bf16(Bt[n][k], At[m][k], acc[ai][bj][m][n], 0, 0, 0); __builtin_amdgcn_s_setprio(0); } while (0)
; #define PG8_WAIT_V(n) asm volatile("s_waitcnt vmcnt(" #n ")" ::: "memory")
; #define PG8_WAIT_L(n) asm volatile("s_waitcnt lgkmcnt(" #n ")" ::: "memory")
; #define PG8_BAR __builtin_amdgcn_s_barrier()
; #define PG8_SCHED __builtin_amdgcn_sched_barrier(0)
; template <class Epi, class Sched, bool ALIGN_EPI = false, bool SP2 = false>
; __device__ __forceinline__ void gemm_phase(PG8_LAS unsigned char* lds, const Gemm g, const Sched& S, const Epi& E) {
;     ...
;             PG8_WAIT_V(8); PG8_WAIT_L(0); PG8_BAR; PG8_MMA(0, 0, At, B0); PG8_MMA(0, 1, At, B1); PG8_BAR; PG8_SCHED;
;             PG8_LDA(At, 0, 1); PG8_STAGE(PG8_SB(0, 0), b2, voffB); PG8_STAGE(PG8_SB(0, 1), b2 + hstep, voffB); PG8_STAGE(PG8_SA(0, 0), a2, voffA);
;             PG8_WAIT_V(8); PG8_WAIT_L(0); PG8_BAR; PG8_MMA(1, 0, At, B0); PG8_MMA(1, 1, At, B1); PG8_BAR; PG8_SCHED;
;             PG8_LDB(B0, 1, 0); PG8_LDB(B1, 1, 1); PG8_SCHED; PG8_LDA(At, 1, 0); PG8_STAGE(PG8_SA(0, 1), a2 + hstep, voffA);
;             PG8_WAIT_V(8); PG8_WAIT_L(0); PG8_BAR; PG8_MMA(0, 0, At, B0); PG8_MMA(0, 1, At, B1); PG8_BAR; PG8_SCHED;
	v_mfma_f32_16x16x32_bf16 v[64:67], v[132:135], v[204:207], 0
	v_mfma_f32_16x16x32_bf16 v[60:63], v[158:161], v[204:207], 0
	v_mfma_f32_16x16x32_bf16 v[48:51], v[132:135], v[212:215], 0
	v_mfma_f32_16x16x32_bf16 v[44:47], v[158:161], v[212:215], 0
	v_mfma_f32_16x16x32_bf16 v[32:35], v[132:135], v[220:223], 0
	v_mfma_f32_16x16x32_bf16 v[28:31], v[158:161], v[220:223], 0
	v_mfma_f32_16x16x32_bf16 v[16:19], v[132:135], v[228:231], 0
	v_mfma_f32_16x16x32_bf16 v[12:15], v[158:161], v[228:231], 0
	v_mfma_f32_16x16x32_bf16 v[64:67], v[136:139], v[208:211], v[64:67]
	v_mfma_f32_16x16x32_bf16 v[60:63], v[162:165], v[208:211], v[60:63]
	v_mfma_f32_16x16x32_bf16 v[48:51], v[136:139], v[216:219], v[48:51]
	v_mfma_f32_16x16x32_bf16 v[44:47], v[162:165], v[216:219], v[44:47]
	v_mfma_f32_16x16x32_bf16 v[32:35], v[136:139], v[224:227], v[32:35]
	v_mfma_f32_16x16x32_bf16 v[28:31], v[162:165], v[224:227], v[28:31]
	v_mfma_f32_16x16x32_bf16 v[16:19], v[136:139], v[232:235], v[16:19]
	v_mfma_f32_16x16x32_bf16 v[12:15], v[162:165], v[232:235], v[12:15]
	v_mfma_f32_16x16x32_bf16 v[56:59], v[188:191], v[204:207], 0
	v_mfma_f32_16x16x32_bf16 v[52:55], v[196:199], v[204:207], 0
	v_mfma_f32_16x16x32_bf16 v[40:43], v[188:191], v[212:215], 0
	v_mfma_f32_16x16x32_bf16 v[36:39], v[196:199], v[212:215], 0
	v_mfma_f32_16x16x32_bf16 v[24:27], v[188:191], v[220:223], 0
	v_mfma_f32_16x16x32_bf16 v[20:23], v[196:199], v[220:223], 0
	v_mfma_f32_16x16x32_bf16 v[8:11], v[188:191], v[228:231], 0
	v_mfma_f32_16x16x32_bf16 v[4:7], v[196:199], v[228:231], 0
	v_mfma_f32_16x16x32_bf16 v[56:59], v[192:195], v[208:211], v[56:59]
	v_mfma_f32_16x16x32_bf16 v[52:55], v[200:203], v[208:211], v[52:55]
	v_mfma_f32_16x16x32_bf16 v[40:43], v[192:195], v[216:219], v[40:43]
	v_mfma_f32_16x16x32_bf16 v[36:39], v[200:203], v[216:219], v[36:39]
	v_mfma_f32_16x16x32_bf16 v[24:27], v[192:195], v[224:227], v[24:27]
	v_mfma_f32_16x16x32_bf16 v[20:23], v[200:203], v[224:227], v[20:23]
	v_mfma_f32_16x16x32_bf16 v[8:11], v[192:195], v[232:235], v[8:11]
	v_mfma_f32_16x16x32_bf16 v[4:7], v[200:203], v[232:235], v[4:7]
	s_barrier
	s_setprio 0
	s_add_i32 s65, 0, 0x18000
	s_add_i32 s66, 0, 0x1c000
	v_add_u32_e32 v162, s65, v185
	v_add_u32_e32 v200, s66, v185
	ds_read_b128 v[132:135], v162
	ds_read_b128 v[136:139], v162 offset:1024
	ds_read_b128 v[158:161], v162 offset:2048
	ds_read_b128 v[162:165], v162 offset:3072
	ds_read_b128 v[188:191], v200
	ds_read_b128 v[192:195], v200 offset:1024
	ds_read_b128 v[196:199], v200 offset:2048
	ds_read_b128 v[200:203], v200 offset:3072
	s_add_u32 s26, s26, 0x80000
	s_addc_u32 s27, s27, 0
	s_mov_b32 m0, s35
	ds_read_b128 v[204:207], v187 offset:32768
	ds_read_b128 v[208:211], v187 offset:33792
	ds_read_b128 v[212:215], v187 offset:34816
	ds_read_b128 v[216:219], v187 offset:35840
	ds_read_b128 v[220:223], v187 offset:36864
	ds_read_b128 v[224:227], v187 offset:37888
	ds_read_b128 v[228:231], v187 offset:38912
	ds_read_b128 v[232:235], v187 offset:39936
	global_load_lds_dwordx4 v0, s[26:27]
	s_mov_b32 m0, s42
	s_nop 0
	global_load_lds_dwordx4 v150, s[26:27]
	s_waitcnt vmcnt(8)
	s_waitcnt lgkmcnt(0)
	s_setprio 1
	s_barrier
	v_mfma_f32_16x16x32_bf16 v[128:131], v[132:135], v[204:207], v[128:131]
	v_mfma_f32_16x16x32_bf16 v[124:127], v[158:161], v[204:207], v[124:127]
	v_mfma_f32_16x16x32_bf16 v[112:115], v[132:135], v[212:215], v[112:115]
	v_mfma_f32_16x16x32_bf16 v[108:111], v[158:161], v[212:215], v[108:111]
	v_mfma_f32_16x16x32_bf16 v[96:99], v[132:135], v[220:223], v[96:99]
	v_mfma_f32_16x16x32_bf16 v[92:95], v[158:161], v[220:223], v[92:95]
	v_mfma_f32_16x16x32_bf16 v[80:83], v[132:135], v[228:231], v[80:83]
	v_mfma_f32_16x16x32_bf16 v[76:79], v[158:161], v[228:231], v[76:79]
	v_mfma_f32_16x16x32_bf16 v[128:131], v[136:139], v[208:211], v[128:131]
	v_mfma_f32_16x16x32_bf16 v[124:127], v[162:165], v[208:211], v[124:127]
	v_mfma_f32_16x16x32_bf16 v[112:115], v[136:139], v[216:219], v[112:115]
	v_mfma_f32_16x16x32_bf16 v[108:111], v[162:165], v[216:219], v[108:111]
	v_mfma_f32_16x16x32_bf16 v[96:99], v[136:139], v[224:227], v[96:99]
	v_mfma_f32_16x16x32_bf16 v[92:95], v[162:165], v[224:227], v[92:95]
	v_mfma_f32_16x16x32_bf16 v[80:83], v[136:139], v[232:235], v[80:83]
	v_mfma_f32_16x16x32_bf16 v[76:79], v[162:165], v[232:235], v[76:79]
	v_mfma_f32_16x16x32_bf16 v[120:123], v[188:191], v[204:207], v[120:123]
	v_mfma_f32_16x16x32_bf16 v[116:119], v[196:199], v[204:207], v[116:119]
	v_mfma_f32_16x16x32_bf16 v[104:107], v[188:191], v[212:215], v[104:107]
	v_mfma_f32_16x16x32_bf16 v[100:103], v[196:199], v[212:215], v[100:103]
	v_mfma_f32_16x16x32_bf16 v[88:91], v[188:191], v[220:223], v[88:91]
	v_mfma_f32_16x16x32_bf16 v[84:87], v[196:199], v[220:223], v[84:87]
	v_mfma_f32_16x16x32_bf16 v[72:75], v[188:191], v[228:231], v[72:75]
	v_mfma_f32_16x16x32_bf16 v[68:71], v[196:199], v[228:231], v[68:71]
	v_mfma_f32_16x16x32_bf16 v[120:123], v[192:195], v[208:211], v[120:123]
	v_mfma_f32_16x16x32_bf16 v[116:119], v[200:203], v[208:211], v[116:119]
	v_mfma_f32_16x16x32_bf16 v[104:107], v[192:195], v[216:219], v[104:107]
	v_mfma_f32_16x16x32_bf16 v[100:103], v[200:203], v[216:219], v[100:103]
	v_mfma_f32_16x16x32_bf16 v[88:91], v[192:195], v[224:227], v[88:91]
	v_mfma_f32_16x16x32_bf16 v[84:87], v[200:203], v[224:227], v[84:87]
	v_mfma_f32_16x16x32_bf16 v[72:75], v[192:195], v[232:235], v[72:75]
	v_mfma_f32_16x16x32_bf16 v[68:71], v[200:203], v[232:235], v[68:71]
	s_barrier
; #define PG8_STAGE(bufoff, gbase, voff) do { _Pragma("unroll") for (int _i = 0; _i < 2; ++_i) \
;         __builtin_amdgcn_global_load_lds((const unsigned*)((const char*)(gbase) + (voff)[_i]), (PG8_LAS unsigned*)(lds + (bufoff) + ldsw + _i * 8192), 16, 0, 0); } while (0)
; #define PG8_LDA(dst, b, h) do { _Pragma("unroll") for (int m = 0; m < 4; ++m) _Pragma("unroll") for (int k = 0; k < 2; ++k) dst[m][k] = *(const PG8_LAS bf16x8*)(lds + PG8_SA(b, h) + aoff + m * 2048 + k * 1024); } while (0)
; #define PG8_LDB(dst, b, h) do { _Pragma("unroll") for (int n = 0; n < 2; ++n) _Pragma("unroll") for (int k = 0; k < 2; ++k) dst[n][k] = *(const PG8_LAS bf16x8*)(lds + PG8_SB(b, h) + boff + n * 2048 + k * 1024); } while (0)
; #define PG8_WAIT_V(n) asm volatile("s_waitcnt vmcnt(" #n ")" ::: "memory")
; #define PG8_WAIT_L(n) asm volatile("s_waitcnt lgkmcnt(" #n ")" ::: "memory")
; #define PG8_BAR __builtin_amdgcn_s_barrier()
; template <class Epi, class Sched, bool ALIGN_EPI = false, bool SP2 = false>
; __device__ __forceinline__ void gemm_phase(PG8_LAS unsigned char* lds, const Gemm g, const Sched& S, const Epi& E) {
;     ...
;         for (int t = 0; t < nt; t += 2) {
;             const bool last = (t == nt - 2);
;             const char* a1 = cA + (size_t)(t + 1) * kstep;
;             const char* a2 = last ? nA : cA + (size_t)(t + 2) * kstep; const char* b2 = last ? nB : cB + (size_t)(t + 2) * kstep;
;             const char* a3 = a2 + kstep; const char* b3 = b2 + kstep;
;             if (last && has_next) S.a_ready(nxt);
;             if constexpr (SP2) {
;             PG8_LDB(B0, 0, 0); PG8_LDB(B1, 0, 1); PG8_SCHED; PG8_LDA(At, 0, 0); PG8_STAGE(PG8_SA(1, 1), a1 + hstep, voffA);
;             PG8_WAIT_V(8); PG8_WAIT_L(0); PG8_BAR; PG8_MMA(0, 0, At, B0); PG8_MMA(0, 1, At, B1); PG8_BAR; PG8_SCHED;
;             PG8_LDA(At, 0, 1); PG8_STAGE(PG8_SB(0, 0), b2, voffB); PG8_STAGE(PG8_SB(0, 1), b2 + hstep, voffB); PG8_STAGE(PG8_SA(0, 0), a2, voffA);
;             PG8_WAIT_V(8); PG8_WAIT_L(0); PG8_BAR; PG8_MMA(1, 0, At, B0); PG8_MMA(1, 1, At, B1); PG8_BAR; PG8_SCHED;
;     ...
;             PG8_LDA(At, 1, 1); PG8_STAGE(PG8_SB(1, 0), b3, voffB); PG8_STAGE(PG8_SB(1, 1), b3 + hstep, voffB); PG8_STAGE(PG8_SA(1, 0), a3, voffA);
;             PG8_WAIT_V(8); PG8_WAIT_L(0); PG8_BAR; PG8_MMA(1, 0, At, B0); PG8_MMA(1, 1, At, B1); PG8_BAR; PG8_SCHED;
	s_setprio 0
	s_add_i32 s26, s65, s31
	s_mov_b32 m0, s26
	ds_read_b128 v[204:207], v187 offset:49152
	ds_read_b128 v[208:211], v187 offset:50176
	ds_read_b128 v[212:215], v187 offset:51200
	ds_read_b128 v[216:219], v187 offset:52224
	ds_read_b128 v[220:223], v187 offset:53248
	ds_read_b128 v[224:227], v187 offset:54272
	ds_read_b128 v[228:231], v187 offset:55296
	ds_read_b128 v[232:235], v187 offset:56320
	s_add_u32 vcc_lo, s24, 0x80
	s_addc_u32 vcc_hi, s25, 0
	global_load_lds_dwordx4 v2, vcc
	s_add_i32 m0, s26, 0x2000
	s_add_u32 s24, s24, 0x80080
	s_addc_u32 s25, s25, 0
	s_add_i32 s26, s66, s31
	s_add_u32 vcc_lo, s24, 0xfff80000
	s_addc_u32 vcc_hi, s25, -1
	global_load_lds_dwordx4 v152, vcc
	s_mov_b32 m0, s26
	s_nop 0
	global_load_lds_dwordx4 v2, s[24:25]
	s_add_i32 m0, s26, 0x2000
	s_nop 0
	global_load_lds_dwordx4 v152, s[24:25]
	v_lshl_add_u64 v[166:167], v[238:239], 0, s[36:37]
	s_mov_b32 m0, s44
	s_nop 0
	global_load_lds_dwordx4 v[166:167], off
	v_lshl_add_u64 v[166:167], v[240:241], 0, s[36:37]
	s_mov_b32 m0, s45
	s_nop 0
	global_load_lds_dwordx4 v[166:167], off
	s_waitcnt vmcnt(8)
	s_waitcnt lgkmcnt(0)
	s_setprio 1
	s_barrier
	v_mfma_f32_16x16x32_bf16 v[64:67], v[132:135], v[204:207], v[64:67]
	v_mfma_f32_16x16x32_bf16 v[60:63], v[158:161], v[204:207], v[60:63]
	v_mfma_f32_16x16x32_bf16 v[48:51], v[132:135], v[212:215], v[48:51]
	v_mfma_f32_16x16x32_bf16 v[44:47], v[158:161], v[212:215], v[44:47]
	v_mfma_f32_16x16x32_bf16 v[32:35], v[132:135], v[220:223], v[32:35]
	v_mfma_f32_16x16x32_bf16 v[28:31], v[158:161], v[220:223], v[28:31]
	v_mfma_f32_16x16x32_bf16 v[16:19], v[132:135], v[228:231], v[16:19]
	v_mfma_f32_16x16x32_bf16 v[12:15], v[158:161], v[228:231], v[12:15]
	v_mfma_f32_16x16x32_bf16 v[64:67], v[136:139], v[208:211], v[64:67]
	v_mfma_f32_16x16x32_bf16 v[60:63], v[162:165], v[208:211], v[60:63]
	v_mfma_f32_16x16x32_bf16 v[48:51], v[136:139], v[216:219], v[48:51]
	v_mfma_f32_16x16x32_bf16 v[44:47], v[162:165], v[216:219], v[44:47]
	v_mfma_f32_16x16x32_bf16 v[32:35], v[136:139], v[224:227], v[32:35]
	v_mfma_f32_16x16x32_bf16 v[28:31], v[162:165], v[224:227], v[28:31]
	v_mfma_f32_16x16x32_bf16 v[16:19], v[136:139], v[232:235], v[16:19]
	v_mfma_f32_16x16x32_bf16 v[12:15], v[162:165], v[232:235], v[12:15]
	v_mfma_f32_16x16x32_bf16 v[56:59], v[188:191], v[204:207], v[56:59]
	v_mfma_f32_16x16x32_bf16 v[52:55], v[196:199], v[204:207], v[52:55]
	v_mfma_f32_16x16x32_bf16 v[40:43], v[188:191], v[212:215], v[40:43]
	v_mfma_f32_16x16x32_bf16 v[36:39], v[196:199], v[212:215], v[36:39]
	v_mfma_f32_16x16x32_bf16 v[24:27], v[188:191], v[220:223], v[24:27]
	v_mfma_f32_16x16x32_bf16 v[20:23], v[196:199], v[220:223], v[20:23]
	v_mfma_f32_16x16x32_bf16 v[8:11], v[188:191], v[228:231], v[8:11]
	v_mfma_f32_16x16x32_bf16 v[4:7], v[196:199], v[228:231], v[4:7]
	v_mfma_f32_16x16x32_bf16 v[56:59], v[192:195], v[208:211], v[56:59]
	v_mfma_f32_16x16x32_bf16 v[52:55], v[200:203], v[208:211], v[52:55]
	v_mfma_f32_16x16x32_bf16 v[40:43], v[192:195], v[216:219], v[40:43]
	v_mfma_f32_16x16x32_bf16 v[36:39], v[200:203], v[216:219], v[36:39]
	v_mfma_f32_16x16x32_bf16 v[24:27], v[192:195], v[224:227], v[24:27]
	v_mfma_f32_16x16x32_bf16 v[20:23], v[200:203], v[224:227], v[20:23]
	v_mfma_f32_16x16x32_bf16 v[8:11], v[192:195], v[232:235], v[8:11]
	v_mfma_f32_16x16x32_bf16 v[4:7], v[200:203], v[232:235], v[4:7]
	s_barrier
	s_setprio 0
	s_add_i32 s64, s64, 2
	s_add_u32 s22, s22, 0x100
	s_addc_u32 s23, s23, 0
	s_add_u32 s57, s57, 0x100
	s_addc_u32 s63, s63, 0
	s_cmp_gt_u32 s64, 29
.LBB0_483:
	s_add_u32 s24, s22, 0xfff80080
	s_addc_u32 s25, s23, -1
	s_add_i32 s65, 0, 0x10000
	s_cmp_eq_u32 s64, 28
	s_cselect_b32 s27, s13, s25
	s_cselect_b32 s26, s19, s24
	s_cselect_b32 s25, s11, s63
	s_cselect_b32 s24, s56, s57
	s_add_i32 s76, 0, 0x14000
	v_add_u32_e32 v162, s65, v185
	v_add_u32_e32 v166, s76, v185
	ds_read_b128 v[132:135], v162
	ds_read_b128 v[136:139], v162 offset:1024
	ds_read_b128 v[158:161], v162 offset:2048
	ds_read_b128 v[162:165], v162 offset:3072
	ds_read_b128 v[188:191], v166
	ds_read_b128 v[192:195], v166 offset:1024
	ds_read_b128 v[196:199], v166 offset:2048
	ds_read_b128 v[200:203], v166 offset:3072
	s_add_i32 m0, s21, 0xc000
	ds_read_b128 v[204:207], v187
	ds_read_b128 v[208:211], v187 offset:1024
	ds_read_b128 v[212:215], v187 offset:2048
	ds_read_b128 v[216:219], v187 offset:3072
	ds_read_b128 v[220:223], v187 offset:4096
	ds_read_b128 v[224:227], v187 offset:5120
	ds_read_b128 v[228:231], v187 offset:6144
	ds_read_b128 v[232:235], v187 offset:7168
	global_load_lds_dwordx4 v154, s[22:23]
	s_add_i32 m0, s21, 0xe000
	s_nop 0
	global_load_lds_dwordx4 v156, s[22:23]
	s_waitcnt vmcnt(8)
	s_waitcnt lgkmcnt(0)
	s_setprio 1
	s_barrier
; #define PG8_STAGE(bufoff, gbase, voff) do { _Pragma("unroll") for (int _i = 0; _i < 2; ++_i) \
;         __builtin_amdgcn_global_load_lds((const unsigned*)((const char*)(gbase) + (voff)[_i]), (PG8_LAS unsigned*)(lds + (bufoff) + ldsw + _i * 8192), 16, 0, 0); } while (0)
; #define PG8_LDA(dst, b, h) do { _Pragma("unroll") for (int m = 0; m < 4; ++m) _Pragma("unroll") for (int k = 0; k < 2; ++k) dst[m][k] = *(const PG8_LAS bf16x8*)(lds + PG8_SA(b, h) + aoff + m * 2048 + k * 1024); } while (0)
; #define PG8_LDB(dst, b, h) do { _Pragma("unroll") for (int n = 0; n < 2; ++n) _Pragma("unroll") for (int k = 0; k < 2; ++k) dst[n][k] = *(const PG8_LAS bf16x8*)(lds + PG8_SB(b, h) + boff + n * 2048 + k * 1024); } while (0)
; #define PG8_MMA(ai, bj, At, Bt) do { __builtin_amdgcn_s_setprio(1); _Pragma("unroll") for (int m = 0; m < 4; ++m) _Pragma("unroll") for (int n = 0; n < 2; ++n) _Pragma("unroll") for (int k = 0; k < 2; ++k) \
;         acc[ai][bj][m][n] = __builtin_amdgcn_mfma_f32_16x16x32_bf16(Bt[n][k], At[m][k], acc[ai][bj][m][n], 0, 0, 0); __builtin_amdgcn_s_setprio(0); } while (0)
; #define PG8_WAIT_V(n) asm volatile("s_waitcnt vmcnt(" #n ")" ::: "memory")
; #define PG8_WAIT_L(n) asm volatile("s_waitcnt lgkmcnt(" #n ")" ::: "memory")
; #define PG8_BAR __builtin_amdgcn_s_barrier()
; #define PG8_SCHED __builtin_amdgcn_sched_barrier(0)
; template <class Epi, class Sched, bool ALIGN_EPI = false, bool SP2 = false>
; __device__ __forceinline__ void gemm_phase(PG8_LAS unsigned char* lds, const Gemm g, const Sched& S, const Epi& E) {
;     ...
;             PG8_WAIT_V(8); PG8_WAIT_L(0); PG8_BAR; PG8_MMA(0, 0, At, B0); PG8_MMA(0, 1, At, B1); PG8_BAR; PG8_SCHED;
;             PG8_LDA(At, 0, 1); PG8_STAGE(PG8_SB(0, 0), b2, voffB); PG8_STAGE(PG8_SB(0, 1), b2 + hstep, voffB); PG8_STAGE(PG8_SA(0, 0), a2, voffA);
;             PG8_WAIT_V(8); PG8_WAIT_L(0); PG8_BAR; PG8_MMA(1, 0, At, B0); PG8_MMA(1, 1, At, B1); PG8_BAR; PG8_SCHED;
;             PG8_LDB(B0, 1, 0); PG8_LDB(B1, 1, 1); PG8_SCHED; PG8_LDA(At, 1, 0); PG8_STAGE(PG8_SA(0, 1), a2 + hstep, voffA);
;             PG8_WAIT_V(8); PG8_WAIT_L(0); PG8_BAR; PG8_MMA(0, 0, At, B0); PG8_MMA(0, 1, At, B1); PG8_BAR; PG8_SCHED;
	v_mfma_f32_16x16x32_bf16 v[128:131], v[132:135], v[204:207], v[128:131]
	v_mfma_f32_16x16x32_bf16 v[124:127], v[158:161], v[204:207], v[124:127]
	v_mfma_f32_16x16x32_bf16 v[112:115], v[132:135], v[212:215], v[112:115]
	v_mfma_f32_16x16x32_bf16 v[108:111], v[158:161], v[212:215], v[108:111]
	v_mfma_f32_16x16x32_bf16 v[96:99], v[132:135], v[220:223], v[96:99]
	v_mfma_f32_16x16x32_bf16 v[92:95], v[158:161], v[220:223], v[92:95]
	v_mfma_f32_16x16x32_bf16 v[80:83], v[132:135], v[228:231], v[80:83]
	v_mfma_f32_16x16x32_bf16 v[76:79], v[158:161], v[228:231], v[76:79]
	v_mfma_f32_16x16x32_bf16 v[128:131], v[136:139], v[208:211], v[128:131]
	v_mfma_f32_16x16x32_bf16 v[124:127], v[162:165], v[208:211], v[124:127]
	v_mfma_f32_16x16x32_bf16 v[112:115], v[136:139], v[216:219], v[112:115]
	v_mfma_f32_16x16x32_bf16 v[108:111], v[162:165], v[216:219], v[108:111]
	v_mfma_f32_16x16x32_bf16 v[96:99], v[136:139], v[224:227], v[96:99]
	v_mfma_f32_16x16x32_bf16 v[92:95], v[162:165], v[224:227], v[92:95]
	v_mfma_f32_16x16x32_bf16 v[80:83], v[136:139], v[232:235], v[80:83]
	v_mfma_f32_16x16x32_bf16 v[76:79], v[162:165], v[232:235], v[76:79]
	v_mfma_f32_16x16x32_bf16 v[120:123], v[188:191], v[204:207], v[120:123]
	v_mfma_f32_16x16x32_bf16 v[116:119], v[196:199], v[204:207], v[116:119]
	v_mfma_f32_16x16x32_bf16 v[104:107], v[188:191], v[212:215], v[104:107]
	v_mfma_f32_16x16x32_bf16 v[100:103], v[196:199], v[212:215], v[100:103]
	v_mfma_f32_16x16x32_bf16 v[88:91], v[188:191], v[220:223], v[88:91]
	v_mfma_f32_16x16x32_bf16 v[84:87], v[196:199], v[220:223], v[84:87]
	v_mfma_f32_16x16x32_bf16 v[72:75], v[188:191], v[228:231], v[72:75]
	v_mfma_f32_16x16x32_bf16 v[68:71], v[196:199], v[228:231], v[68:71]
	v_mfma_f32_16x16x32_bf16 v[120:123], v[192:195], v[208:211], v[120:123]
	v_mfma_f32_16x16x32_bf16 v[116:119], v[200:203], v[208:211], v[116:119]
	v_mfma_f32_16x16x32_bf16 v[104:107], v[192:195], v[216:219], v[104:107]
	v_mfma_f32_16x16x32_bf16 v[100:103], v[200:203], v[216:219], v[100:103]
	v_mfma_f32_16x16x32_bf16 v[88:91], v[192:195], v[224:227], v[88:91]
	v_mfma_f32_16x16x32_bf16 v[84:87], v[200:203], v[224:227], v[84:87]
	v_mfma_f32_16x16x32_bf16 v[72:75], v[192:195], v[232:235], v[72:75]
	v_mfma_f32_16x16x32_bf16 v[68:71], v[200:203], v[232:235], v[68:71]
	s_barrier
	s_setprio 0
	s_add_i32 s65, s65, s31
	s_mov_b32 m0, s65
	ds_read_b128 v[204:207], v187 offset:16384
	ds_read_b128 v[208:211], v187 offset:17408
	ds_read_b128 v[212:215], v187 offset:18432
	ds_read_b128 v[216:219], v187 offset:19456
	ds_read_b128 v[220:223], v187 offset:20480
	ds_read_b128 v[224:227], v187 offset:21504
	ds_read_b128 v[228:231], v187 offset:22528
	ds_read_b128 v[232:235], v187 offset:23552
	global_load_lds_dwordx4 v2, s[24:25]
	s_add_i32 m0, s65, 0x2000
	s_add_u32 s66, s24, 0x80000
	s_addc_u32 s67, s25, 0
	s_add_i32 s65, s76, s31
	global_load_lds_dwordx4 v152, s[24:25]
	s_mov_b32 m0, s65
	v_lshl_add_u64 v[240:241], s[26:27], 0, v[150:151]
	global_load_lds_dwordx4 v2, s[66:67]
	s_add_i32 m0, s65, 0x2000
	s_nop 0
	global_load_lds_dwordx4 v152, s[66:67]
	v_lshl_add_u64 v[238:239], s[26:27], 0, v[0:1]
	s_mov_b32 m0, s21
	s_nop 0
	global_load_lds_dwordx4 v[238:239], off
	s_mov_b32 m0, s34
	s_nop 0
	global_load_lds_dwordx4 v[240:241], off
	s_waitcnt vmcnt(8)
	s_waitcnt lgkmcnt(0)
	s_setprio 1
	s_barrier
	v_mfma_f32_16x16x32_bf16 v[64:67], v[132:135], v[204:207], v[64:67]
	v_mfma_f32_16x16x32_bf16 v[60:63], v[158:161], v[204:207], v[60:63]
	v_mfma_f32_16x16x32_bf16 v[48:51], v[132:135], v[212:215], v[48:51]
	v_mfma_f32_16x16x32_bf16 v[44:47], v[158:161], v[212:215], v[44:47]
	v_mfma_f32_16x16x32_bf16 v[32:35], v[132:135], v[220:223], v[32:35]
	v_mfma_f32_16x16x32_bf16 v[28:31], v[158:161], v[220:223], v[28:31]
	v_mfma_f32_16x16x32_bf16 v[16:19], v[132:135], v[228:231], v[16:19]
	v_mfma_f32_16x16x32_bf16 v[12:15], v[158:161], v[228:231], v[12:15]
	v_mfma_f32_16x16x32_bf16 v[64:67], v[136:139], v[208:211], v[64:67]
	v_mfma_f32_16x16x32_bf16 v[60:63], v[162:165], v[208:211], v[60:63]
	v_mfma_f32_16x16x32_bf16 v[48:51], v[136:139], v[216:219], v[48:51]
	v_mfma_f32_16x16x32_bf16 v[44:47], v[162:165], v[216:219], v[44:47]
	v_mfma_f32_16x16x32_bf16 v[32:35], v[136:139], v[224:227], v[32:35]
	v_mfma_f32_16x16x32_bf16 v[28:31], v[162:165], v[224:227], v[28:31]
	v_mfma_f32_16x16x32_bf16 v[16:19], v[136:139], v[232:235], v[16:19]
	v_mfma_f32_16x16x32_bf16 v[12:15], v[162:165], v[232:235], v[12:15]
	v_mfma_f32_16x16x32_bf16 v[56:59], v[188:191], v[204:207], v[56:59]
	v_mfma_f32_16x16x32_bf16 v[52:55], v[196:199], v[204:207], v[52:55]
	v_mfma_f32_16x16x32_bf16 v[40:43], v[188:191], v[212:215], v[40:43]
	v_mfma_f32_16x16x32_bf16 v[36:39], v[196:199], v[212:215], v[36:39]
	v_mfma_f32_16x16x32_bf16 v[24:27], v[188:191], v[220:223], v[24:27]
	v_mfma_f32_16x16x32_bf16 v[20:23], v[196:199], v[220:223], v[20:23]
	v_mfma_f32_16x16x32_bf16 v[8:11], v[188:191], v[228:231], v[8:11]
	v_mfma_f32_16x16x32_bf16 v[4:7], v[196:199], v[228:231], v[4:7]
	v_mfma_f32_16x16x32_bf16 v[56:59], v[192:195], v[208:211], v[56:59]
	v_mfma_f32_16x16x32_bf16 v[52:55], v[200:203], v[208:211], v[52:55]
	v_mfma_f32_16x16x32_bf16 v[40:43], v[192:195], v[216:219], v[40:43]
	v_mfma_f32_16x16x32_bf16 v[36:39], v[200:203], v[216:219], v[36:39]
	v_mfma_f32_16x16x32_bf16 v[24:27], v[192:195], v[224:227], v[24:27]
	v_mfma_f32_16x16x32_bf16 v[20:23], v[200:203], v[224:227], v[20:23]
	v_mfma_f32_16x16x32_bf16 v[8:11], v[192:195], v[232:235], v[8:11]
	v_mfma_f32_16x16x32_bf16 v[4:7], v[200:203], v[232:235], v[4:7]
	s_barrier
; #define PG8_STAGE(bufoff, gbase, voff) do { _Pragma("unroll") for (int _i = 0; _i < 2; ++_i) \
;         __builtin_amdgcn_global_load_lds((const unsigned*)((const char*)(gbase) + (voff)[_i]), (PG8_LAS unsigned*)(lds + (bufoff) + ldsw + _i * 8192), 16, 0, 0); } while (0)
; #define PG8_LDA(dst, b, h) do { _Pragma("unroll") for (int m = 0; m < 4; ++m) _Pragma("unroll") for (int k = 0; k < 2; ++k) dst[m][k] = *(const PG8_LAS bf16x8*)(lds + PG8_SA(b, h) + aoff + m * 2048 + k * 1024); } while (0)
; #define PG8_LDB(dst, b, h) do { _Pragma("unroll") for (int n = 0; n < 2; ++n) _Pragma("unroll") for (int k = 0; k < 2; ++k) dst[n][k] = *(const PG8_LAS bf16x8*)(lds + PG8_SB(b, h) + boff + n * 2048 + k * 1024); } while (0)
; #define PG8_MMA(ai, bj, At, Bt) do { __builtin_amdgcn_s_setprio(1); _Pragma("unroll") for (int m = 0; m < 4; ++m) _Pragma("unroll") for (int n = 0; n < 2; ++n) _Pragma("unroll") for (int k = 0; k < 2; ++k) \
;         acc[ai][bj][m][n] = __builtin_amdgcn_mfma_f32_16x16x32_bf16(Bt[n][k], At[m][k], acc[ai][bj][m][n], 0, 0, 0); __builtin_amdgcn_s_setprio(0); } while (0)
; #define PG8_WAIT_V(n) asm volatile("s_waitcnt vmcnt(" #n ")" ::: "memory")
; #define PG8_WAIT_L(n) asm volatile("s_waitcnt lgkmcnt(" #n ")" ::: "memory")
; #define PG8_BAR __builtin_amdgcn_s_barrier()
; #define PG8_SCHED __builtin_amdgcn_sched_barrier(0)
; template <class Epi, class Sched, bool ALIGN_EPI = false, bool SP2 = false>
; __device__ __forceinline__ void gemm_phase(PG8_LAS unsigned char* lds, const Gemm g, const Sched& S, const Epi& E) {
;     ...
;             PG8_LDB(B0, 1, 0); PG8_LDB(B1, 1, 1); PG8_SCHED; PG8_LDA(At, 1, 0); PG8_STAGE(PG8_SA(0, 1), a2 + hstep, voffA);
;             PG8_WAIT_V(8); PG8_WAIT_L(0); PG8_BAR; PG8_MMA(0, 0, At, B0); PG8_MMA(0, 1, At, B1); PG8_BAR; PG8_SCHED;
;             PG8_LDA(At, 1, 1); PG8_STAGE(PG8_SB(1, 0), b3, voffB); PG8_STAGE(PG8_SB(1, 1), b3 + hstep, voffB); PG8_STAGE(PG8_SA(1, 0), a3, voffA);
;             PG8_WAIT_V(8); PG8_WAIT_L(0); PG8_BAR; PG8_MMA(1, 0, At, B0); PG8_MMA(1, 1, At, B1); PG8_BAR; PG8_SCHED;
;     ...
;         if constexpr (ALIGN_EPI) { if (wr == 0) PG8_BAR; }
	s_setprio 0
	s_add_i32 s65, 0, 0x18000
	s_add_i32 s66, 0, 0x1c000
	v_add_u32_e32 v162, s65, v185
	v_add_u32_e32 v200, s66, v185
	ds_read_b128 v[132:135], v162
	ds_read_b128 v[136:139], v162 offset:1024
	ds_read_b128 v[158:161], v162 offset:2048
	ds_read_b128 v[162:165], v162 offset:3072
	ds_read_b128 v[188:191], v200
	ds_read_b128 v[192:195], v200 offset:1024
	ds_read_b128 v[196:199], v200 offset:2048
	ds_read_b128 v[200:203], v200 offset:3072
	s_add_u32 s26, s26, 0x80000
	s_addc_u32 s27, s27, 0
	s_mov_b32 m0, s35
	ds_read_b128 v[204:207], v187 offset:32768
	ds_read_b128 v[208:211], v187 offset:33792
	ds_read_b128 v[212:215], v187 offset:34816
	ds_read_b128 v[216:219], v187 offset:35840
	ds_read_b128 v[220:223], v187 offset:36864
	ds_read_b128 v[224:227], v187 offset:37888
	ds_read_b128 v[228:231], v187 offset:38912
	ds_read_b128 v[232:235], v187 offset:39936
	global_load_lds_dwordx4 v0, s[26:27]
	s_mov_b32 m0, s42
	s_nop 0
	global_load_lds_dwordx4 v150, s[26:27]
	s_waitcnt vmcnt(8)
	s_waitcnt lgkmcnt(0)
	s_setprio 1
	s_barrier
	v_mfma_f32_16x16x32_bf16 v[128:131], v[132:135], v[204:207], v[128:131]
	v_mfma_f32_16x16x32_bf16 v[124:127], v[158:161], v[204:207], v[124:127]
	v_mfma_f32_16x16x32_bf16 v[112:115], v[132:135], v[212:215], v[112:115]
	v_mfma_f32_16x16x32_bf16 v[108:111], v[158:161], v[212:215], v[108:111]
	v_mfma_f32_16x16x32_bf16 v[96:99], v[132:135], v[220:223], v[96:99]
	v_mfma_f32_16x16x32_bf16 v[92:95], v[158:161], v[220:223], v[92:95]
	v_mfma_f32_16x16x32_bf16 v[80:83], v[132:135], v[228:231], v[80:83]
	v_mfma_f32_16x16x32_bf16 v[76:79], v[158:161], v[228:231], v[76:79]
	v_mfma_f32_16x16x32_bf16 v[128:131], v[136:139], v[208:211], v[128:131]
	v_mfma_f32_16x16x32_bf16 v[124:127], v[162:165], v[208:211], v[124:127]
	v_mfma_f32_16x16x32_bf16 v[112:115], v[136:139], v[216:219], v[112:115]
	v_mfma_f32_16x16x32_bf16 v[108:111], v[162:165], v[216:219], v[108:111]
	v_mfma_f32_16x16x32_bf16 v[96:99], v[136:139], v[224:227], v[96:99]
	v_mfma_f32_16x16x32_bf16 v[92:95], v[162:165], v[224:227], v[92:95]
	v_mfma_f32_16x16x32_bf16 v[80:83], v[136:139], v[232:235], v[80:83]
	v_mfma_f32_16x16x32_bf16 v[76:79], v[162:165], v[232:235], v[76:79]
	v_mfma_f32_16x16x32_bf16 v[120:123], v[188:191], v[204:207], v[120:123]
	v_mfma_f32_16x16x32_bf16 v[116:119], v[196:199], v[204:207], v[116:119]
	v_mfma_f32_16x16x32_bf16 v[104:107], v[188:191], v[212:215], v[104:107]
	v_mfma_f32_16x16x32_bf16 v[100:103], v[196:199], v[212:215], v[100:103]
	v_mfma_f32_16x16x32_bf16 v[88:91], v[188:191], v[220:223], v[88:91]
	v_mfma_f32_16x16x32_bf16 v[84:87], v[196:199], v[220:223], v[84:87]
	v_mfma_f32_16x16x32_bf16 v[72:75], v[188:191], v[228:231], v[72:75]
	v_mfma_f32_16x16x32_bf16 v[68:71], v[196:199], v[228:231], v[68:71]
	v_mfma_f32_16x16x32_bf16 v[120:123], v[192:195], v[208:211], v[120:123]
	v_mfma_f32_16x16x32_bf16 v[116:119], v[200:203], v[208:211], v[116:119]
	v_mfma_f32_16x16x32_bf16 v[104:107], v[192:195], v[216:219], v[104:107]
	v_mfma_f32_16x16x32_bf16 v[100:103], v[200:203], v[216:219], v[100:103]
	v_mfma_f32_16x16x32_bf16 v[88:91], v[192:195], v[224:227], v[88:91]
	v_mfma_f32_16x16x32_bf16 v[84:87], v[200:203], v[224:227], v[84:87]
	v_mfma_f32_16x16x32_bf16 v[72:75], v[192:195], v[232:235], v[72:75]
	v_mfma_f32_16x16x32_bf16 v[68:71], v[200:203], v[232:235], v[68:71]
	s_barrier
	s_setprio 0
	s_add_i32 s26, s65, s31
	s_mov_b32 m0, s26
	ds_read_b128 v[204:207], v187 offset:49152
	ds_read_b128 v[208:211], v187 offset:50176
	ds_read_b128 v[212:215], v187 offset:51200
	ds_read_b128 v[216:219], v187 offset:52224
	ds_read_b128 v[220:223], v187 offset:53248
	ds_read_b128 v[224:227], v187 offset:54272
	ds_read_b128 v[228:231], v187 offset:55296
	ds_read_b128 v[232:235], v187 offset:56320
	s_add_u32 vcc_lo, s24, 0x80
	s_addc_u32 vcc_hi, s25, 0
	global_load_lds_dwordx4 v2, vcc
	s_add_i32 m0, s26, 0x2000
	s_add_u32 s24, s24, 0x80080
	s_addc_u32 s25, s25, 0
	s_add_i32 s26, s66, s31
	s_add_u32 vcc_lo, s24, 0xfff80000
	s_addc_u32 vcc_hi, s25, -1
	global_load_lds_dwordx4 v152, vcc
	s_mov_b32 m0, s26
	s_nop 0
	global_load_lds_dwordx4 v2, s[24:25]
	s_add_i32 m0, s26, 0x2000
	s_nop 0
	global_load_lds_dwordx4 v152, s[24:25]
	v_lshl_add_u64 v[166:167], v[238:239], 0, s[36:37]
	s_mov_b32 m0, s44
	s_nop 0
	global_load_lds_dwordx4 v[166:167], off
	v_lshl_add_u64 v[166:167], v[240:241], 0, s[36:37]
	s_mov_b32 m0, s45
	s_nop 0
	global_load_lds_dwordx4 v[166:167], off
	s_waitcnt vmcnt(8)
	s_waitcnt lgkmcnt(0)
	s_setprio 1
	s_barrier
	v_mfma_f32_16x16x32_bf16 v[64:67], v[132:135], v[204:207], v[64:67]
	v_mfma_f32_16x16x32_bf16 v[60:63], v[158:161], v[204:207], v[60:63]
	v_mfma_f32_16x16x32_bf16 v[48:51], v[132:135], v[212:215], v[48:51]
	v_mfma_f32_16x16x32_bf16 v[44:47], v[158:161], v[212:215], v[44:47]
	v_mfma_f32_16x16x32_bf16 v[32:35], v[132:135], v[220:223], v[32:35]
	v_mfma_f32_16x16x32_bf16 v[28:31], v[158:161], v[220:223], v[28:31]
	v_mfma_f32_16x16x32_bf16 v[16:19], v[132:135], v[228:231], v[16:19]
	v_mfma_f32_16x16x32_bf16 v[12:15], v[158:161], v[228:231], v[12:15]
	v_mfma_f32_16x16x32_bf16 v[64:67], v[136:139], v[208:211], v[64:67]
	v_mfma_f32_16x16x32_bf16 v[60:63], v[162:165], v[208:211], v[60:63]
	v_mfma_f32_16x16x32_bf16 v[48:51], v[136:139], v[216:219], v[48:51]
	v_mfma_f32_16x16x32_bf16 v[44:47], v[162:165], v[216:219], v[44:47]
	v_mfma_f32_16x16x32_bf16 v[32:35], v[136:139], v[224:227], v[32:35]
	v_mfma_f32_16x16x32_bf16 v[28:31], v[162:165], v[224:227], v[28:31]
	v_mfma_f32_16x16x32_bf16 v[16:19], v[136:139], v[232:235], v[16:19]
	v_mfma_f32_16x16x32_bf16 v[12:15], v[162:165], v[232:235], v[12:15]
	v_mfma_f32_16x16x32_bf16 v[56:59], v[188:191], v[204:207], v[56:59]
	v_mfma_f32_16x16x32_bf16 v[52:55], v[196:199], v[204:207], v[52:55]
	v_mfma_f32_16x16x32_bf16 v[40:43], v[188:191], v[212:215], v[40:43]
	v_mfma_f32_16x16x32_bf16 v[36:39], v[196:199], v[212:215], v[36:39]
	v_mfma_f32_16x16x32_bf16 v[24:27], v[188:191], v[220:223], v[24:27]
	v_mfma_f32_16x16x32_bf16 v[20:23], v[196:199], v[220:223], v[20:23]
	v_mfma_f32_16x16x32_bf16 v[8:11], v[188:191], v[228:231], v[8:11]
	v_mfma_f32_16x16x32_bf16 v[4:7], v[196:199], v[228:231], v[4:7]
	v_mfma_f32_16x16x32_bf16 v[56:59], v[192:195], v[208:211], v[56:59]
	v_mfma_f32_16x16x32_bf16 v[52:55], v[200:203], v[208:211], v[52:55]
	v_mfma_f32_16x16x32_bf16 v[40:43], v[192:195], v[216:219], v[40:43]
	v_mfma_f32_16x16x32_bf16 v[36:39], v[200:203], v[216:219], v[36:39]
	v_mfma_f32_16x16x32_bf16 v[24:27], v[192:195], v[224:227], v[24:27]
	v_mfma_f32_16x16x32_bf16 v[20:23], v[200:203], v[224:227], v[20:23]
	v_mfma_f32_16x16x32_bf16 v[8:11], v[192:195], v[232:235], v[8:11]
	v_mfma_f32_16x16x32_bf16 v[4:7], v[200:203], v[232:235], v[4:7]
	s_barrier
	s_setprio 0
	s_add_i32 s64, s64, 2
	s_add_u32 s22, s22, 0x100
	s_addc_u32 s23, s23, 0
	s_add_u32 s57, s57, 0x100
	s_addc_u32 s63, s63, 0
	s_cmp_gt_u32 s64, 29
	s_cbranch_scc0 .LBB0_483
	s_and_b64 vcc, exec, s[8:9]
	s_cbranch_vccz .LBB0_486
	s_barrier

; #define PG8_STAGE(bufoff, gbase, voff) do { _Pragma("unroll") for (int _i = 0; _i < 2; ++_i) \
;         __builtin_amdgcn_global_load_lds((const unsigned*)((const char*)(gbase) + (voff)[_i]), (PG8_LAS unsigned*)(lds + (bufoff) + ldsw + _i * 8192), 16, 0, 0); } while (0)
; #define PG8_LDA(dst, b, h) do { _Pragma("unroll") for (int m = 0; m < 4; ++m) _Pragma("unroll") for (int k = 0; k < 2; ++k) dst[m][k] = *(const PG8_LAS bf16x8*)(lds + PG8_SA(b, h) + aoff + m * 2048 + k * 1024); } while (0)
; #define PG8_LDB(dst, b, h) do { _Pragma("unroll") for (int n = 0; n < 2; ++n) _Pragma("unroll") for (int k = 0; k < 2; ++k) dst[n][k] = *(const PG8_LAS bf16x8*)(lds + PG8_SB(b, h) + boff + n * 2048 + k * 1024); } while (0)
; #define PG8_WAIT_V(n) asm volatile("s_waitcnt vmcnt(" #n ")" ::: "memory")
; #define PG8_WAIT_L(n) asm volatile("s_waitcnt lgkmcnt(" #n ")" ::: "memory")
; #define PG8_BAR __builtin_amdgcn_s_barrier()
; #define PG8_SCHED __builtin_amdgcn_sched_barrier(0)
; template <class Epi, class Sched, bool ALIGN_EPI = false, bool SP2 = false>
; __device__ __forceinline__ void gemm_phase(PG8_LAS unsigned char* lds, const Gemm g, const Sched& S, const Epi& E) {
;     ...
;         const bool has_next = S.next(ui + 1, nxt);
;         const char* nA = has_next ? (const char*)g.A + (size_t)nxt.pm * tstep : cA; const char* nB = has_next ? (const char*)g.Bt + (size_t)nxt.pn * tstep : cB;
;         for (int t = 0; t < nt; t += 2) {
;             const bool last = (t == nt - 2);
;             const char* a1 = cA + (size_t)(t + 1) * kstep;
;             const char* a2 = last ? nA : cA + (size_t)(t + 2) * kstep; const char* b2 = last ? nB : cB + (size_t)(t + 2) * kstep;
;             const char* a3 = a2 + kstep; const char* b3 = b2 + kstep;
;             if (last && has_next) S.a_ready(nxt);
;             if constexpr (SP2) {
;             PG8_LDB(B0, 0, 0); PG8_LDB(B1, 0, 1); PG8_SCHED; PG8_LDA(At, 0, 0); PG8_STAGE(PG8_SA(1, 1), a1 + hstep, voffA);
;             PG8_WAIT_V(8); PG8_WAIT_L(0); PG8_BAR; PG8_MMA(0, 0, At, B0); PG8_MMA(0, 1, At, B1); PG8_BAR; PG8_SCHED;
;             PG8_LDA(At, 0, 1); PG8_STAGE(PG8_SB(0, 0), b2, voffB); PG8_STAGE(PG8_SB(0, 1), b2 + hstep, voffB); PG8_STAGE(PG8_SA(0, 0), a2, voffA);
;             PG8_WAIT_V(8); PG8_WAIT_L(0); PG8_BAR; PG8_MMA(1, 0, At, B0); PG8_MMA(1, 1, At, B1); PG8_BAR; PG8_SCHED;
.LBB0_566:
	s_ashr_i32 s11, s10, 31
	s_lshl_b64 s[12:13], s[10:11], 20
	s_add_u32 s12, s46, s12
	s_addc_u32 s13, s47, s13
	s_and_b64 s[14:15], s[2:3], exec
	s_cselect_b32 s11, s13, s19
	s_cselect_b32 s45, s12, s18
	s_ashr_i32 s9, s8, 31
	s_lshl_b64 s[14:15], s[8:9], 20
	s_add_u32 s14, s25, s14
	s_addc_u32 s15, s26, s15
	s_and_b64 s[22:23], s[2:3], exec
	s_cselect_b32 s9, s15, s21
	s_cselect_b32 s50, s14, s20
	s_add_u32 s18, s18, 0x80080
	s_addc_u32 s19, s19, 0
	s_add_u32 s51, s20, 0x100
	s_addc_u32 s56, s21, 0
	s_mov_b32 s57, -2
	s_add_u32 s20, s18, 0xfff80080
	s_addc_u32 s21, s19, -1
	s_add_i32 s63, 0, 0x10000
	s_cmp_eq_u32 s57, 28
	s_cselect_b32 s23, s11, s21
	s_cselect_b32 s22, s45, s20
	v_add_u32_e32 v150, s63, v153
	s_cselect_b32 s21, s9, s56
	s_cselect_b32 s20, s50, s51
	s_add_i32 s66, 0, 0x14000
	ds_read_b128 v[184:187], v150
	ds_read_b128 v[188:191], v150 offset:1024
	ds_read_b128 v[192:195], v150 offset:2048
	ds_read_b128 v[196:199], v150 offset:3072
	v_add_u32_e32 v150, s66, v153
	ds_read_b128 v[200:203], v150
	ds_read_b128 v[204:207], v150 offset:1024
	ds_read_b128 v[208:211], v150 offset:2048
	ds_read_b128 v[212:215], v150 offset:3072
	s_add_i32 m0, s29, 0xc000
	ds_read_b128 v[216:219], v155
	ds_read_b128 v[220:223], v155 offset:1024
	ds_read_b128 v[224:227], v155 offset:2048
	ds_read_b128 v[228:231], v155 offset:3072
	ds_read_b128 v[232:235], v155 offset:4096
	ds_read_b128 v[236:239], v155 offset:5120
	ds_read_b128 v[240:243], v155 offset:6144
	ds_read_b128 v[244:247], v155 offset:7168
	global_load_lds_dwordx4 v136, s[18:19]
	s_add_i32 m0, s29, 0xe000
	s_nop 0
	global_load_lds_dwordx4 v138, s[18:19]
	s_waitcnt vmcnt(8)
	s_waitcnt lgkmcnt(0)
	s_setprio 1
	s_barrier
	v_mfma_f32_16x16x32_bf16 v[128:131], v[184:187], v[216:219], 0
	v_mfma_f32_16x16x32_bf16 v[120:123], v[192:195], v[216:219], 0
	v_mfma_f32_16x16x32_bf16 v[112:115], v[184:187], v[224:227], 0
	v_mfma_f32_16x16x32_bf16 v[104:107], v[192:195], v[224:227], 0
	v_mfma_f32_16x16x32_bf16 v[96:99], v[184:187], v[232:235], 0
	v_mfma_f32_16x16x32_bf16 v[88:91], v[192:195], v[232:235], 0
	v_mfma_f32_16x16x32_bf16 v[80:83], v[184:187], v[240:243], 0
	v_mfma_f32_16x16x32_bf16 v[72:75], v[192:195], v[240:243], 0
	v_mfma_f32_16x16x32_bf16 v[128:131], v[188:191], v[220:223], v[128:131]
	v_mfma_f32_16x16x32_bf16 v[120:123], v[196:199], v[220:223], v[120:123]
	v_mfma_f32_16x16x32_bf16 v[112:115], v[188:191], v[228:231], v[112:115]
	v_mfma_f32_16x16x32_bf16 v[104:107], v[196:199], v[228:231], v[104:107]
	v_mfma_f32_16x16x32_bf16 v[96:99], v[188:191], v[236:239], v[96:99]
	v_mfma_f32_16x16x32_bf16 v[88:91], v[196:199], v[236:239], v[88:91]
	v_mfma_f32_16x16x32_bf16 v[80:83], v[188:191], v[244:247], v[80:83]
	v_mfma_f32_16x16x32_bf16 v[72:75], v[196:199], v[244:247], v[72:75]
	v_mfma_f32_16x16x32_bf16 v[124:127], v[200:203], v[216:219], 0
	v_mfma_f32_16x16x32_bf16 v[116:119], v[208:211], v[216:219], 0
	v_mfma_f32_16x16x32_bf16 v[108:111], v[200:203], v[224:227], 0
	v_mfma_f32_16x16x32_bf16 v[100:103], v[208:211], v[224:227], 0
	v_mfma_f32_16x16x32_bf16 v[92:95], v[200:203], v[232:235], 0
	v_mfma_f32_16x16x32_bf16 v[84:87], v[208:211], v[232:235], 0
	v_mfma_f32_16x16x32_bf16 v[76:79], v[200:203], v[240:243], 0
	v_mfma_f32_16x16x32_bf16 v[68:71], v[208:211], v[240:243], 0
	v_mfma_f32_16x16x32_bf16 v[124:127], v[204:207], v[220:223], v[124:127]
	v_mfma_f32_16x16x32_bf16 v[116:119], v[212:215], v[220:223], v[116:119]
	v_mfma_f32_16x16x32_bf16 v[108:111], v[204:207], v[228:231], v[108:111]
	v_mfma_f32_16x16x32_bf16 v[100:103], v[212:215], v[228:231], v[100:103]
	v_mfma_f32_16x16x32_bf16 v[92:95], v[204:207], v[236:239], v[92:95]
	v_mfma_f32_16x16x32_bf16 v[84:87], v[212:215], v[236:239], v[84:87]
	v_mfma_f32_16x16x32_bf16 v[76:79], v[204:207], v[244:247], v[76:79]
	v_mfma_f32_16x16x32_bf16 v[68:71], v[212:215], v[244:247], v[68:71]
	s_barrier
	s_setprio 0
	s_add_i32 s63, s63, s27
	s_mov_b32 m0, s63
	ds_read_b128 v[216:219], v155 offset:16384
	ds_read_b128 v[220:223], v155 offset:17408
	ds_read_b128 v[224:227], v155 offset:18432
	ds_read_b128 v[228:231], v155 offset:19456
	ds_read_b128 v[232:235], v155 offset:20480
	ds_read_b128 v[236:239], v155 offset:21504
	ds_read_b128 v[240:243], v155 offset:22528
	ds_read_b128 v[244:247], v155 offset:23552
	global_load_lds_dwordx4 v2, s[20:21]
	s_add_i32 m0, s63, 0x2000
	s_add_u32 s64, s20, 0x80000
	s_addc_u32 s65, s21, 0
	s_add_i32 s63, s66, s27
	global_load_lds_dwordx4 v0, s[20:21]
	s_mov_b32 m0, s63
	v_lshl_add_u64 v[250:251], s[22:23], 0, v[132:133]
	global_load_lds_dwordx4 v2, s[64:65]
	s_add_i32 m0, s63, 0x2000
	s_nop 0
	global_load_lds_dwordx4 v0, s[64:65]
	v_lshl_add_u64 v[248:249], s[22:23], 0, v[134:135]
	s_mov_b32 m0, s29
	s_nop 0
	global_load_lds_dwordx4 v[248:249], off
	s_mov_b32 m0, s30
	s_nop 0
	global_load_lds_dwordx4 v[250:251], off
	s_waitcnt vmcnt(8)
	s_waitcnt lgkmcnt(0)
	s_setprio 1
	s_barrier
; #define PG8_STAGE(bufoff, gbase, voff) do { _Pragma("unroll") for (int _i = 0; _i < 2; ++_i) \
;         __builtin_amdgcn_global_load_lds((const unsigned*)((const char*)(gbase) + (voff)[_i]), (PG8_LAS unsigned*)(lds + (bufoff) + ldsw + _i * 8192), 16, 0, 0); } while (0)
; #define PG8_LDA(dst, b, h) do { _Pragma("unroll") for (int m = 0; m < 4; ++m) _Pragma("unroll") for (int k = 0; k < 2; ++k) dst[m][k] = *(const PG8_LAS bf16x8*)(lds + PG8_SA(b, h) + aoff + m * 2048 + k * 1024); } while (0)
; #define PG8_LDB(dst, b, h) do { _Pragma("unroll") for (int n = 0; n < 2; ++n) _Pragma("unroll") for (int k = 0; k < 2; ++k) dst[n][k] = *(const PG8_LAS bf16x8*)(lds + PG8_SB(b, h) + boff + n * 2048 + k * 1024); } while (0)
; #define PG8_MMA(ai, bj, At, Bt) do { __builtin_amdgcn_s_setprio(1); _Pragma("unroll") for (int m = 0; m < 4; ++m) _Pragma("unroll") for (int n = 0; n < 2; ++n) _Pragma("unroll") for (int k = 0; k < 2; ++k) \
;         acc[ai][bj][m][n] = __builtin_amdgcn_mfma_f32_16x16x32_bf16(Bt[n][k], At[m][k], acc[ai][bj][m][n], 0, 0, 0); __builtin_amdgcn_s_setprio(0); } while (0)
; #define PG8_WAIT_V(n) asm volatile("s_waitcnt vmcnt(" #n ")" ::: "memory")
; #define PG8_WAIT_L(n) asm volatile("s_waitcnt lgkmcnt(" #n ")" ::: "memory")
; #define PG8_BAR __builtin_amdgcn_s_barrier()
; #define PG8_SCHED __builtin_amdgcn_sched_barrier(0)
; template <class Epi, class Sched, bool ALIGN_EPI = false, bool SP2 = false>
; __device__ __forceinline__ void gemm_phase(PG8_LAS unsigned char* lds, const Gemm g, const Sched& S, const Epi& E) {
;     ...
;             PG8_WAIT_V(8); PG8_WAIT_L(0); PG8_BAR; PG8_MMA(0, 0, At, B0); PG8_MMA(0, 1, At, B1); PG8_BAR; PG8_SCHED;
;             PG8_LDA(At, 0, 1); PG8_STAGE(PG8_SB(0, 0), b2, voffB); PG8_STAGE(PG8_SB(0, 1), b2 + hstep, voffB); PG8_STAGE(PG8_SA(0, 0), a2, voffA);
;             PG8_WAIT_V(8); PG8_WAIT_L(0); PG8_BAR; PG8_MMA(1, 0, At, B0); PG8_MMA(1, 1, At, B1); PG8_BAR; PG8_SCHED;
;             PG8_LDB(B0, 1, 0); PG8_LDB(B1, 1, 1); PG8_SCHED; PG8_LDA(At, 1, 0); PG8_STAGE(PG8_SA(0, 1), a2 + hstep, voffA);
;             PG8_WAIT_V(8); PG8_WAIT_L(0); PG8_BAR; PG8_MMA(0, 0, At, B0); PG8_MMA(0, 1, At, B1); PG8_BAR; PG8_SCHED;
	v_mfma_f32_16x16x32_bf16 v[64:67], v[184:187], v[216:219], 0
	v_mfma_f32_16x16x32_bf16 v[56:59], v[192:195], v[216:219], 0
	v_mfma_f32_16x16x32_bf16 v[48:51], v[184:187], v[224:227], 0
	v_mfma_f32_16x16x32_bf16 v[40:43], v[192:195], v[224:227], 0
	v_mfma_f32_16x16x32_bf16 v[32:35], v[184:187], v[232:235], 0
	v_mfma_f32_16x16x32_bf16 v[24:27], v[192:195], v[232:235], 0
	v_mfma_f32_16x16x32_bf16 v[16:19], v[184:187], v[240:243], 0
	v_mfma_f32_16x16x32_bf16 v[8:11], v[192:195], v[240:243], 0
	v_mfma_f32_16x16x32_bf16 v[64:67], v[188:191], v[220:223], v[64:67]
	v_mfma_f32_16x16x32_bf16 v[56:59], v[196:199], v[220:223], v[56:59]
	v_mfma_f32_16x16x32_bf16 v[48:51], v[188:191], v[228:231], v[48:51]
	v_mfma_f32_16x16x32_bf16 v[40:43], v[196:199], v[228:231], v[40:43]
	v_mfma_f32_16x16x32_bf16 v[32:35], v[188:191], v[236:239], v[32:35]
	v_mfma_f32_16x16x32_bf16 v[24:27], v[196:199], v[236:239], v[24:27]
	v_mfma_f32_16x16x32_bf16 v[16:19], v[188:191], v[244:247], v[16:19]
	v_mfma_f32_16x16x32_bf16 v[8:11], v[196:199], v[244:247], v[8:11]
	v_mfma_f32_16x16x32_bf16 v[60:63], v[200:203], v[216:219], 0
	v_mfma_f32_16x16x32_bf16 v[52:55], v[208:211], v[216:219], 0
	v_mfma_f32_16x16x32_bf16 v[44:47], v[200:203], v[224:227], 0
	v_mfma_f32_16x16x32_bf16 v[36:39], v[208:211], v[224:227], 0
	v_mfma_f32_16x16x32_bf16 v[28:31], v[200:203], v[232:235], 0
	v_mfma_f32_16x16x32_bf16 v[20:23], v[208:211], v[232:235], 0
	v_mfma_f32_16x16x32_bf16 v[12:15], v[200:203], v[240:243], 0
	v_mfma_f32_16x16x32_bf16 v[4:7], v[208:211], v[240:243], 0
	v_mfma_f32_16x16x32_bf16 v[60:63], v[204:207], v[220:223], v[60:63]
	v_mfma_f32_16x16x32_bf16 v[52:55], v[212:215], v[220:223], v[52:55]
	v_mfma_f32_16x16x32_bf16 v[44:47], v[204:207], v[228:231], v[44:47]
	v_mfma_f32_16x16x32_bf16 v[36:39], v[212:215], v[228:231], v[36:39]
	v_mfma_f32_16x16x32_bf16 v[28:31], v[204:207], v[236:239], v[28:31]
	v_mfma_f32_16x16x32_bf16 v[20:23], v[212:215], v[236:239], v[20:23]
	v_mfma_f32_16x16x32_bf16 v[12:15], v[204:207], v[244:247], v[12:15]
	v_mfma_f32_16x16x32_bf16 v[4:7], v[212:215], v[244:247], v[4:7]
	s_barrier
	s_setprio 0
	s_add_i32 s63, 0, 0x18000
	v_add_u32_e32 v161, s63, v153
	s_add_i32 s64, 0, 0x1c000
	ds_read_b128 v[184:187], v161
	ds_read_b128 v[188:191], v161 offset:1024
	ds_read_b128 v[192:195], v161 offset:2048
	ds_read_b128 v[196:199], v161 offset:3072
	v_add_u32_e32 v161, s64, v153
	ds_read_b128 v[200:203], v161
	ds_read_b128 v[204:207], v161 offset:1024
	ds_read_b128 v[208:211], v161 offset:2048
	ds_read_b128 v[212:215], v161 offset:3072
	s_add_u32 s22, s22, 0x80000
	s_addc_u32 s23, s23, 0
	s_mov_b32 m0, s31
	ds_read_b128 v[216:219], v155 offset:32768
	ds_read_b128 v[220:223], v155 offset:33792
	ds_read_b128 v[224:227], v155 offset:34816
	ds_read_b128 v[228:231], v155 offset:35840
	ds_read_b128 v[232:235], v155 offset:36864
	ds_read_b128 v[236:239], v155 offset:37888
	ds_read_b128 v[240:243], v155 offset:38912
	ds_read_b128 v[244:247], v155 offset:39936
	global_load_lds_dwordx4 v134, s[22:23]
	s_mov_b32 m0, s34
	s_nop 0
	global_load_lds_dwordx4 v132, s[22:23]
	s_waitcnt vmcnt(8)
	s_waitcnt lgkmcnt(0)
	s_setprio 1
	s_barrier
	v_mfma_f32_16x16x32_bf16 v[128:131], v[184:187], v[216:219], v[128:131]
	v_mfma_f32_16x16x32_bf16 v[120:123], v[192:195], v[216:219], v[120:123]
	v_mfma_f32_16x16x32_bf16 v[112:115], v[184:187], v[224:227], v[112:115]
	v_mfma_f32_16x16x32_bf16 v[104:107], v[192:195], v[224:227], v[104:107]
	v_mfma_f32_16x16x32_bf16 v[96:99], v[184:187], v[232:235], v[96:99]
	v_mfma_f32_16x16x32_bf16 v[88:91], v[192:195], v[232:235], v[88:91]
	v_mfma_f32_16x16x32_bf16 v[80:83], v[184:187], v[240:243], v[80:83]
	v_mfma_f32_16x16x32_bf16 v[72:75], v[192:195], v[240:243], v[72:75]
	v_mfma_f32_16x16x32_bf16 v[128:131], v[188:191], v[220:223], v[128:131]
	v_mfma_f32_16x16x32_bf16 v[120:123], v[196:199], v[220:223], v[120:123]
	v_mfma_f32_16x16x32_bf16 v[112:115], v[188:191], v[228:231], v[112:115]
	v_mfma_f32_16x16x32_bf16 v[104:107], v[196:199], v[228:231], v[104:107]
	v_mfma_f32_16x16x32_bf16 v[96:99], v[188:191], v[236:239], v[96:99]
	v_mfma_f32_16x16x32_bf16 v[88:91], v[196:199], v[236:239], v[88:91]
	v_mfma_f32_16x16x32_bf16 v[80:83], v[188:191], v[244:247], v[80:83]
	v_mfma_f32_16x16x32_bf16 v[72:75], v[196:199], v[244:247], v[72:75]
	v_mfma_f32_16x16x32_bf16 v[124:127], v[200:203], v[216:219], v[124:127]
	v_mfma_f32_16x16x32_bf16 v[116:119], v[208:211], v[216:219], v[116:119]
	v_mfma_f32_16x16x32_bf16 v[108:111], v[200:203], v[224:227], v[108:111]
	v_mfma_f32_16x16x32_bf16 v[100:103], v[208:211], v[224:227], v[100:103]
	v_mfma_f32_16x16x32_bf16 v[92:95], v[200:203], v[232:235], v[92:95]
	v_mfma_f32_16x16x32_bf16 v[84:87], v[208:211], v[232:235], v[84:87]
	v_mfma_f32_16x16x32_bf16 v[76:79], v[200:203], v[240:243], v[76:79]
	v_mfma_f32_16x16x32_bf16 v[68:71], v[208:211], v[240:243], v[68:71]
	v_mfma_f32_16x16x32_bf16 v[124:127], v[204:207], v[220:223], v[124:127]
	v_mfma_f32_16x16x32_bf16 v[116:119], v[212:215], v[220:223], v[116:119]
	v_mfma_f32_16x16x32_bf16 v[108:111], v[204:207], v[228:231], v[108:111]
	v_mfma_f32_16x16x32_bf16 v[100:103], v[212:215], v[228:231], v[100:103]
	v_mfma_f32_16x16x32_bf16 v[92:95], v[204:207], v[236:239], v[92:95]
	v_mfma_f32_16x16x32_bf16 v[84:87], v[212:215], v[236:239], v[84:87]
	v_mfma_f32_16x16x32_bf16 v[76:79], v[204:207], v[244:247], v[76:79]
	v_mfma_f32_16x16x32_bf16 v[68:71], v[212:215], v[244:247], v[68:71]
	s_barrier
; #define PG8_STAGE(bufoff, gbase, voff) do { _Pragma("unroll") for (int _i = 0; _i < 2; ++_i) \
;         __builtin_amdgcn_global_load_lds((const unsigned*)((const char*)(gbase) + (voff)[_i]), (PG8_LAS unsigned*)(lds + (bufoff) + ldsw + _i * 8192), 16, 0, 0); } while (0)
; #define PG8_LDA(dst, b, h) do { _Pragma("unroll") for (int m = 0; m < 4; ++m) _Pragma("unroll") for (int k = 0; k < 2; ++k) dst[m][k] = *(const PG8_LAS bf16x8*)(lds + PG8_SA(b, h) + aoff + m * 2048 + k * 1024); } while (0)
; #define PG8_LDB(dst, b, h) do { _Pragma("unroll") for (int n = 0; n < 2; ++n) _Pragma("unroll") for (int k = 0; k < 2; ++k) dst[n][k] = *(const PG8_LAS bf16x8*)(lds + PG8_SB(b, h) + boff + n * 2048 + k * 1024); } while (0)
; #define PG8_WAIT_V(n) asm volatile("s_waitcnt vmcnt(" #n ")" ::: "memory")
; #define PG8_WAIT_L(n) asm volatile("s_waitcnt lgkmcnt(" #n ")" ::: "memory")
; #define PG8_BAR __builtin_amdgcn_s_barrier()
; template <class Epi, class Sched, bool ALIGN_EPI = false, bool SP2 = false>
; __device__ __forceinline__ void gemm_phase(PG8_LAS unsigned char* lds, const Gemm g, const Sched& S, const Epi& E) {
;     ...
;         for (int t = 0; t < nt; t += 2) {
;             const bool last = (t == nt - 2);
;             const char* a1 = cA + (size_t)(t + 1) * kstep;
;             const char* a2 = last ? nA : cA + (size_t)(t + 2) * kstep; const char* b2 = last ? nB : cB + (size_t)(t + 2) * kstep;
;             const char* a3 = a2 + kstep; const char* b3 = b2 + kstep;
;             if (last && has_next) S.a_ready(nxt);
;             if constexpr (SP2) {
;             PG8_LDB(B0, 0, 0); PG8_LDB(B1, 0, 1); PG8_SCHED; PG8_LDA(At, 0, 0); PG8_STAGE(PG8_SA(1, 1), a1 + hstep, voffA);
;             PG8_WAIT_V(8); PG8_WAIT_L(0); PG8_BAR; PG8_MMA(0, 0, At, B0); PG8_MMA(0, 1, At, B1); PG8_BAR; PG8_SCHED;
;             PG8_LDA(At, 0, 1); PG8_STAGE(PG8_SB(0, 0), b2, voffB); PG8_STAGE(PG8_SB(0, 1), b2 + hstep, voffB); PG8_STAGE(PG8_SA(0, 0), a2, voffA);
;             PG8_WAIT_V(8); PG8_WAIT_L(0); PG8_BAR; PG8_MMA(1, 0, At, B0); PG8_MMA(1, 1, At, B1); PG8_BAR; PG8_SCHED;
;     ...
;             PG8_LDA(At, 1, 1); PG8_STAGE(PG8_SB(1, 0), b3, voffB); PG8_STAGE(PG8_SB(1, 1), b3 + hstep, voffB); PG8_STAGE(PG8_SA(1, 0), a3, voffA);
;             PG8_WAIT_V(8); PG8_WAIT_L(0); PG8_BAR; PG8_MMA(1, 0, At, B0); PG8_MMA(1, 1, At, B1); PG8_BAR; PG8_SCHED;
	s_setprio 0
	s_add_i32 s22, s63, s27
	s_mov_b32 m0, s22
	ds_read_b128 v[216:219], v155 offset:49152
	ds_read_b128 v[220:223], v155 offset:50176
	ds_read_b128 v[224:227], v155 offset:51200
	ds_read_b128 v[228:231], v155 offset:52224
	ds_read_b128 v[232:235], v155 offset:53248
	ds_read_b128 v[236:239], v155 offset:54272
	ds_read_b128 v[240:243], v155 offset:55296
	ds_read_b128 v[244:247], v155 offset:56320
	s_add_u32 vcc_lo, s20, 0x80
	s_addc_u32 vcc_hi, s21, 0
	global_load_lds_dwordx4 v2, vcc
	s_add_i32 m0, s22, 0x2000
	s_add_u32 s20, s20, 0x80080
	s_addc_u32 s21, s21, 0
	s_add_i32 s22, s64, s27
	s_add_u32 vcc_lo, s20, 0xfff80000
	s_addc_u32 vcc_hi, s21, -1
	global_load_lds_dwordx4 v0, vcc
	s_mov_b32 m0, s22
	s_nop 0
	global_load_lds_dwordx4 v2, s[20:21]
	s_add_i32 m0, s22, 0x2000
	s_nop 0
	global_load_lds_dwordx4 v0, s[20:21]
	v_lshl_add_u64 v[150:151], v[248:249], 0, s[36:37]
	s_mov_b32 m0, s35
	s_nop 0
	global_load_lds_dwordx4 v[150:151], off
	v_lshl_add_u64 v[150:151], v[250:251], 0, s[36:37]
	s_mov_b32 m0, s42
	s_nop 0
	global_load_lds_dwordx4 v[150:151], off
	s_waitcnt vmcnt(8)
	s_waitcnt lgkmcnt(0)
	s_setprio 1
	s_barrier
	v_mfma_f32_16x16x32_bf16 v[64:67], v[184:187], v[216:219], v[64:67]
	v_mfma_f32_16x16x32_bf16 v[56:59], v[192:195], v[216:219], v[56:59]
	v_mfma_f32_16x16x32_bf16 v[48:51], v[184:187], v[224:227], v[48:51]
	v_mfma_f32_16x16x32_bf16 v[40:43], v[192:195], v[224:227], v[40:43]
	v_mfma_f32_16x16x32_bf16 v[32:35], v[184:187], v[232:235], v[32:35]
	v_mfma_f32_16x16x32_bf16 v[24:27], v[192:195], v[232:235], v[24:27]
	v_mfma_f32_16x16x32_bf16 v[16:19], v[184:187], v[240:243], v[16:19]
	v_mfma_f32_16x16x32_bf16 v[8:11], v[192:195], v[240:243], v[8:11]
	v_mfma_f32_16x16x32_bf16 v[64:67], v[188:191], v[220:223], v[64:67]
	v_mfma_f32_16x16x32_bf16 v[56:59], v[196:199], v[220:223], v[56:59]
	v_mfma_f32_16x16x32_bf16 v[48:51], v[188:191], v[228:231], v[48:51]
	v_mfma_f32_16x16x32_bf16 v[40:43], v[196:199], v[228:231], v[40:43]
	v_mfma_f32_16x16x32_bf16 v[32:35], v[188:191], v[236:239], v[32:35]
	v_mfma_f32_16x16x32_bf16 v[24:27], v[196:199], v[236:239], v[24:27]
	v_mfma_f32_16x16x32_bf16 v[16:19], v[188:191], v[244:247], v[16:19]
	v_mfma_f32_16x16x32_bf16 v[8:11], v[196:199], v[244:247], v[8:11]
	v_mfma_f32_16x16x32_bf16 v[60:63], v[200:203], v[216:219], v[60:63]
	v_mfma_f32_16x16x32_bf16 v[52:55], v[208:211], v[216:219], v[52:55]
	v_mfma_f32_16x16x32_bf16 v[44:47], v[200:203], v[224:227], v[44:47]
	v_mfma_f32_16x16x32_bf16 v[36:39], v[208:211], v[224:227], v[36:39]
	v_mfma_f32_16x16x32_bf16 v[28:31], v[200:203], v[232:235], v[28:31]
	v_mfma_f32_16x16x32_bf16 v[20:23], v[208:211], v[232:235], v[20:23]
	v_mfma_f32_16x16x32_bf16 v[12:15], v[200:203], v[240:243], v[12:15]
	v_mfma_f32_16x16x32_bf16 v[4:7], v[208:211], v[240:243], v[4:7]
	v_mfma_f32_16x16x32_bf16 v[60:63], v[204:207], v[220:223], v[60:63]
	v_mfma_f32_16x16x32_bf16 v[52:55], v[212:215], v[220:223], v[52:55]
	v_mfma_f32_16x16x32_bf16 v[44:47], v[204:207], v[228:231], v[44:47]
	v_mfma_f32_16x16x32_bf16 v[36:39], v[212:215], v[228:231], v[36:39]
	v_mfma_f32_16x16x32_bf16 v[28:31], v[204:207], v[236:239], v[28:31]
	v_mfma_f32_16x16x32_bf16 v[20:23], v[212:215], v[236:239], v[20:23]
	v_mfma_f32_16x16x32_bf16 v[12:15], v[204:207], v[244:247], v[12:15]
	v_mfma_f32_16x16x32_bf16 v[4:7], v[212:215], v[244:247], v[4:7]
	s_barrier
	s_setprio 0
	s_add_i32 s57, s57, 2
	s_add_u32 s18, s18, 0x100
	s_addc_u32 s19, s19, 0
	s_add_u32 s51, s51, 0x100
	s_addc_u32 s56, s56, 0
	s_cmp_gt_u32 s57, 29
.LBB0_567:
	s_add_u32 s20, s18, 0xfff80080
	s_addc_u32 s21, s19, -1
	s_add_i32 s63, 0, 0x10000
	s_cmp_eq_u32 s57, 28
	s_cselect_b32 s23, s11, s21
	s_cselect_b32 s22, s45, s20
	v_add_u32_e32 v150, s63, v153
	s_cselect_b32 s21, s9, s56
	s_cselect_b32 s20, s50, s51
	s_add_i32 s66, 0, 0x14000
	ds_read_b128 v[184:187], v150
	ds_read_b128 v[188:191], v150 offset:1024
	ds_read_b128 v[192:195], v150 offset:2048
	ds_read_b128 v[196:199], v150 offset:3072
	v_add_u32_e32 v150, s66, v153
	ds_read_b128 v[200:203], v150
	ds_read_b128 v[204:207], v150 offset:1024
	ds_read_b128 v[208:211], v150 offset:2048
	ds_read_b128 v[212:215], v150 offset:3072
	s_add_i32 m0, s29, 0xc000
	ds_read_b128 v[216:219], v155
	ds_read_b128 v[220:223], v155 offset:1024
	ds_read_b128 v[224:227], v155 offset:2048
	ds_read_b128 v[228:231], v155 offset:3072
	ds_read_b128 v[232:235], v155 offset:4096
	ds_read_b128 v[236:239], v155 offset:5120
	ds_read_b128 v[240:243], v155 offset:6144
	ds_read_b128 v[244:247], v155 offset:7168
	global_load_lds_dwordx4 v136, s[18:19]
	s_add_i32 m0, s29, 0xe000
	s_nop 0
	global_load_lds_dwordx4 v138, s[18:19]
	s_waitcnt vmcnt(8)
	s_waitcnt lgkmcnt(0)
	s_setprio 1
	s_barrier
; #define PG8_STAGE(bufoff, gbase, voff) do { _Pragma("unroll") for (int _i = 0; _i < 2; ++_i) \
;         __builtin_amdgcn_global_load_lds((const unsigned*)((const char*)(gbase) + (voff)[_i]), (PG8_LAS unsigned*)(lds + (bufoff) + ldsw + _i * 8192), 16, 0, 0); } while (0)
; #define PG8_LDA(dst, b, h) do { _Pragma("unroll") for (int m = 0; m < 4; ++m) _Pragma("unroll") for (int k = 0; k < 2; ++k) dst[m][k] = *(const PG8_LAS bf16x8*)(lds + PG8_SA(b, h) + aoff + m * 2048 + k * 1024); } while (0)
; #define PG8_LDB(dst, b, h) do { _Pragma("unroll") for (int n = 0; n < 2; ++n) _Pragma("unroll") for (int k = 0; k < 2; ++k) dst[n][k] = *(const PG8_LAS bf16x8*)(lds + PG8_SB(b, h) + boff + n * 2048 + k * 1024); } while (0)
; #define PG8_MMA(ai, bj, At, Bt) do { __builtin_amdgcn_s_setprio(1); _Pragma("unroll") for (int m = 0; m < 4; ++m) _Pragma("unroll") for (int n = 0; n < 2; ++n) _Pragma("unroll") for (int k = 0; k < 2; ++k) \
;         acc[ai][bj][m][n] = __builtin_amdgcn_mfma_f32_16x16x32_bf16(Bt[n][k], At[m][k], acc[ai][bj][m][n], 0, 0, 0); __builtin_amdgcn_s_setprio(0); } while (0)
; #define PG8_WAIT_V(n) asm volatile("s_waitcnt vmcnt(" #n ")" ::: "memory")
; #define PG8_WAIT_L(n) asm volatile("s_waitcnt lgkmcnt(" #n ")" ::: "memory")
; #define PG8_BAR __builtin_amdgcn_s_barrier()
; #define PG8_SCHED __builtin_amdgcn_sched_barrier(0)
; template <class Epi, class Sched, bool ALIGN_EPI = false, bool SP2 = false>
; __device__ __forceinline__ void gemm_phase(PG8_LAS unsigned char* lds, const Gemm g, const Sched& S, const Epi& E) {
;     ...
;             PG8_WAIT_V(8); PG8_WAIT_L(0); PG8_BAR; PG8_MMA(0, 0, At, B0); PG8_MMA(0, 1, At, B1); PG8_BAR; PG8_SCHED;
;             PG8_LDA(At, 0, 1); PG8_STAGE(PG8_SB(0, 0), b2, voffB); PG8_STAGE(PG8_SB(0, 1), b2 + hstep, voffB); PG8_STAGE(PG8_SA(0, 0), a2, voffA);
;             PG8_WAIT_V(8); PG8_WAIT_L(0); PG8_BAR; PG8_MMA(1, 0, At, B0); PG8_MMA(1, 1, At, B1); PG8_BAR; PG8_SCHED;
;             PG8_LDB(B0, 1, 0); PG8_LDB(B1, 1, 1); PG8_SCHED; PG8_LDA(At, 1, 0); PG8_STAGE(PG8_SA(0, 1), a2 + hstep, voffA);
;             PG8_WAIT_V(8); PG8_WAIT_L(0); PG8_BAR; PG8_MMA(0, 0, At, B0); PG8_MMA(0, 1, At, B1); PG8_BAR; PG8_SCHED;
	v_mfma_f32_16x16x32_bf16 v[128:131], v[184:187], v[216:219], v[128:131]
	v_mfma_f32_16x16x32_bf16 v[120:123], v[192:195], v[216:219], v[120:123]
	v_mfma_f32_16x16x32_bf16 v[112:115], v[184:187], v[224:227], v[112:115]
	v_mfma_f32_16x16x32_bf16 v[104:107], v[192:195], v[224:227], v[104:107]
	v_mfma_f32_16x16x32_bf16 v[96:99], v[184:187], v[232:235], v[96:99]
	v_mfma_f32_16x16x32_bf16 v[88:91], v[192:195], v[232:235], v[88:91]
	v_mfma_f32_16x16x32_bf16 v[80:83], v[184:187], v[240:243], v[80:83]
	v_mfma_f32_16x16x32_bf16 v[72:75], v[192:195], v[240:243], v[72:75]
	v_mfma_f32_16x16x32_bf16 v[128:131], v[188:191], v[220:223], v[128:131]
	v_mfma_f32_16x16x32_bf16 v[120:123], v[196:199], v[220:223], v[120:123]
	v_mfma_f32_16x16x32_bf16 v[112:115], v[188:191], v[228:231], v[112:115]
	v_mfma_f32_16x16x32_bf16 v[104:107], v[196:199], v[228:231], v[104:107]
	v_mfma_f32_16x16x32_bf16 v[96:99], v[188:191], v[236:239], v[96:99]
	v_mfma_f32_16x16x32_bf16 v[88:91], v[196:199], v[236:239], v[88:91]
	v_mfma_f32_16x16x32_bf16 v[80:83], v[188:191], v[244:247], v[80:83]
	v_mfma_f32_16x16x32_bf16 v[72:75], v[196:199], v[244:247], v[72:75]
	v_mfma_f32_16x16x32_bf16 v[124:127], v[200:203], v[216:219], v[124:127]
	v_mfma_f32_16x16x32_bf16 v[116:119], v[208:211], v[216:219], v[116:119]
	v_mfma_f32_16x16x32_bf16 v[108:111], v[200:203], v[224:227], v[108:111]
	v_mfma_f32_16x16x32_bf16 v[100:103], v[208:211], v[224:227], v[100:103]
	v_mfma_f32_16x16x32_bf16 v[92:95], v[200:203], v[232:235], v[92:95]
	v_mfma_f32_16x16x32_bf16 v[84:87], v[208:211], v[232:235], v[84:87]
	v_mfma_f32_16x16x32_bf16 v[76:79], v[200:203], v[240:243], v[76:79]
	v_mfma_f32_16x16x32_bf16 v[68:71], v[208:211], v[240:243], v[68:71]
	v_mfma_f32_16x16x32_bf16 v[124:127], v[204:207], v[220:223], v[124:127]
	v_mfma_f32_16x16x32_bf16 v[116:119], v[212:215], v[220:223], v[116:119]
	v_mfma_f32_16x16x32_bf16 v[108:111], v[204:207], v[228:231], v[108:111]
	v_mfma_f32_16x16x32_bf16 v[100:103], v[212:215], v[228:231], v[100:103]
	v_mfma_f32_16x16x32_bf16 v[92:95], v[204:207], v[236:239], v[92:95]
	v_mfma_f32_16x16x32_bf16 v[84:87], v[212:215], v[236:239], v[84:87]
	v_mfma_f32_16x16x32_bf16 v[76:79], v[204:207], v[244:247], v[76:79]
	v_mfma_f32_16x16x32_bf16 v[68:71], v[212:215], v[244:247], v[68:71]
	s_barrier
	s_setprio 0
	s_add_i32 s63, s63, s27
	s_mov_b32 m0, s63
	ds_read_b128 v[216:219], v155 offset:16384
	ds_read_b128 v[220:223], v155 offset:17408
	ds_read_b128 v[224:227], v155 offset:18432
	ds_read_b128 v[228:231], v155 offset:19456
	ds_read_b128 v[232:235], v155 offset:20480
	ds_read_b128 v[236:239], v155 offset:21504
	ds_read_b128 v[240:243], v155 offset:22528
	ds_read_b128 v[244:247], v155 offset:23552
	global_load_lds_dwordx4 v2, s[20:21]
	s_add_i32 m0, s63, 0x2000
	s_add_u32 s64, s20, 0x80000
	s_addc_u32 s65, s21, 0
	s_add_i32 s63, s66, s27
	global_load_lds_dwordx4 v0, s[20:21]
	s_mov_b32 m0, s63
	v_lshl_add_u64 v[250:251], s[22:23], 0, v[132:133]
	global_load_lds_dwordx4 v2, s[64:65]
	s_add_i32 m0, s63, 0x2000
	s_nop 0
	global_load_lds_dwordx4 v0, s[64:65]
	v_lshl_add_u64 v[248:249], s[22:23], 0, v[134:135]
	s_mov_b32 m0, s29
	s_nop 0
	global_load_lds_dwordx4 v[248:249], off
	s_mov_b32 m0, s30
	s_nop 0
	global_load_lds_dwordx4 v[250:251], off
	s_waitcnt vmcnt(8)
	s_waitcnt lgkmcnt(0)
	s_setprio 1
	s_barrier
	v_mfma_f32_16x16x32_bf16 v[64:67], v[184:187], v[216:219], v[64:67]
	v_mfma_f32_16x16x32_bf16 v[56:59], v[192:195], v[216:219], v[56:59]
	v_mfma_f32_16x16x32_bf16 v[48:51], v[184:187], v[224:227], v[48:51]
	v_mfma_f32_16x16x32_bf16 v[40:43], v[192:195], v[224:227], v[40:43]
	v_mfma_f32_16x16x32_bf16 v[32:35], v[184:187], v[232:235], v[32:35]
	v_mfma_f32_16x16x32_bf16 v[24:27], v[192:195], v[232:235], v[24:27]
	v_mfma_f32_16x16x32_bf16 v[16:19], v[184:187], v[240:243], v[16:19]
	v_mfma_f32_16x16x32_bf16 v[8:11], v[192:195], v[240:243], v[8:11]
	v_mfma_f32_16x16x32_bf16 v[64:67], v[188:191], v[220:223], v[64:67]
	v_mfma_f32_16x16x32_bf16 v[56:59], v[196:199], v[220:223], v[56:59]
	v_mfma_f32_16x16x32_bf16 v[48:51], v[188:191], v[228:231], v[48:51]
	v_mfma_f32_16x16x32_bf16 v[40:43], v[196:199], v[228:231], v[40:43]
	v_mfma_f32_16x16x32_bf16 v[32:35], v[188:191], v[236:239], v[32:35]
	v_mfma_f32_16x16x32_bf16 v[24:27], v[196:199], v[236:239], v[24:27]
	v_mfma_f32_16x16x32_bf16 v[16:19], v[188:191], v[244:247], v[16:19]
	v_mfma_f32_16x16x32_bf16 v[8:11], v[196:199], v[244:247], v[8:11]
	v_mfma_f32_16x16x32_bf16 v[60:63], v[200:203], v[216:219], v[60:63]
	v_mfma_f32_16x16x32_bf16 v[52:55], v[208:211], v[216:219], v[52:55]
	v_mfma_f32_16x16x32_bf16 v[44:47], v[200:203], v[224:227], v[44:47]
	v_mfma_f32_16x16x32_bf16 v[36:39], v[208:211], v[224:227], v[36:39]
	v_mfma_f32_16x16x32_bf16 v[28:31], v[200:203], v[232:235], v[28:31]
	v_mfma_f32_16x16x32_bf16 v[20:23], v[208:211], v[232:235], v[20:23]
	v_mfma_f32_16x16x32_bf16 v[12:15], v[200:203], v[240:243], v[12:15]
	v_mfma_f32_16x16x32_bf16 v[4:7], v[208:211], v[240:243], v[4:7]
	v_mfma_f32_16x16x32_bf16 v[60:63], v[204:207], v[220:223], v[60:63]
	v_mfma_f32_16x16x32_bf16 v[52:55], v[212:215], v[220:223], v[52:55]
	v_mfma_f32_16x16x32_bf16 v[44:47], v[204:207], v[228:231], v[44:47]
	v_mfma_f32_16x16x32_bf16 v[36:39], v[212:215], v[228:231], v[36:39]
	v_mfma_f32_16x16x32_bf16 v[28:31], v[204:207], v[236:239], v[28:31]
	v_mfma_f32_16x16x32_bf16 v[20:23], v[212:215], v[236:239], v[20:23]
	v_mfma_f32_16x16x32_bf16 v[12:15], v[204:207], v[244:247], v[12:15]
	v_mfma_f32_16x16x32_bf16 v[4:7], v[212:215], v[244:247], v[4:7]
	s_barrier
; #define PG8_STAGE(bufoff, gbase, voff) do { _Pragma("unroll") for (int _i = 0; _i < 2; ++_i) \
;         __builtin_amdgcn_global_load_lds((const unsigned*)((const char*)(gbase) + (voff)[_i]), (PG8_LAS unsigned*)(lds + (bufoff) + ldsw + _i * 8192), 16, 0, 0); } while (0)
; #define PG8_LDA(dst, b, h) do { _Pragma("unroll") for (int m = 0; m < 4; ++m) _Pragma("unroll") for (int k = 0; k < 2; ++k) dst[m][k] = *(const PG8_LAS bf16x8*)(lds + PG8_SA(b, h) + aoff + m * 2048 + k * 1024); } while (0)
; #define PG8_LDB(dst, b, h) do { _Pragma("unroll") for (int n = 0; n < 2; ++n) _Pragma("unroll") for (int k = 0; k < 2; ++k) dst[n][k] = *(const PG8_LAS bf16x8*)(lds + PG8_SB(b, h) + boff + n * 2048 + k * 1024); } while (0)
; #define PG8_MMA(ai, bj, At, Bt) do { __builtin_amdgcn_s_setprio(1); _Pragma("unroll") for (int m = 0; m < 4; ++m) _Pragma("unroll") for (int n = 0; n < 2; ++n) _Pragma("unroll") for (int k = 0; k < 2; ++k) \
;         acc[ai][bj][m][n] = __builtin_amdgcn_mfma_f32_16x16x32_bf16(Bt[n][k], At[m][k], acc[ai][bj][m][n], 0, 0, 0); __builtin_amdgcn_s_setprio(0); } while (0)
; #define PG8_WAIT_V(n) asm volatile("s_waitcnt vmcnt(" #n ")" ::: "memory")
; #define PG8_WAIT_L(n) asm volatile("s_waitcnt lgkmcnt(" #n ")" ::: "memory")
; #define PG8_BAR __builtin_amdgcn_s_barrier()
; #define PG8_SCHED __builtin_amdgcn_sched_barrier(0)
; template <class Epi, class Sched, bool ALIGN_EPI = false, bool SP2 = false>
; __device__ __forceinline__ void gemm_phase(PG8_LAS unsigned char* lds, const Gemm g, const Sched& S, const Epi& E) {
;     ...
;             PG8_LDB(B0, 1, 0); PG8_LDB(B1, 1, 1); PG8_SCHED; PG8_LDA(At, 1, 0); PG8_STAGE(PG8_SA(0, 1), a2 + hstep, voffA);
;             PG8_WAIT_V(8); PG8_WAIT_L(0); PG8_BAR; PG8_MMA(0, 0, At, B0); PG8_MMA(0, 1, At, B1); PG8_BAR; PG8_SCHED;
;             PG8_LDA(At, 1, 1); PG8_STAGE(PG8_SB(1, 0), b3, voffB); PG8_STAGE(PG8_SB(1, 1), b3 + hstep, voffB); PG8_STAGE(PG8_SA(1, 0), a3, voffA);
;             PG8_WAIT_V(8); PG8_WAIT_L(0); PG8_BAR; PG8_MMA(1, 0, At, B0); PG8_MMA(1, 1, At, B1); PG8_BAR; PG8_SCHED;
;     ...
;         if constexpr (ALIGN_EPI) { if (wr == 0) PG8_BAR; }
	s_setprio 0
	s_add_i32 s63, 0, 0x18000
	v_add_u32_e32 v161, s63, v153
	s_add_i32 s64, 0, 0x1c000
	ds_read_b128 v[184:187], v161
	ds_read_b128 v[188:191], v161 offset:1024
	ds_read_b128 v[192:195], v161 offset:2048
	ds_read_b128 v[196:199], v161 offset:3072
	v_add_u32_e32 v161, s64, v153
	ds_read_b128 v[200:203], v161
	ds_read_b128 v[204:207], v161 offset:1024
	ds_read_b128 v[208:211], v161 offset:2048
	ds_read_b128 v[212:215], v161 offset:3072
	s_add_u32 s22, s22, 0x80000
	s_addc_u32 s23, s23, 0
	s_mov_b32 m0, s31
	ds_read_b128 v[216:219], v155 offset:32768
	ds_read_b128 v[220:223], v155 offset:33792
	ds_read_b128 v[224:227], v155 offset:34816
	ds_read_b128 v[228:231], v155 offset:35840
	ds_read_b128 v[232:235], v155 offset:36864
	ds_read_b128 v[236:239], v155 offset:37888
	ds_read_b128 v[240:243], v155 offset:38912
	ds_read_b128 v[244:247], v155 offset:39936
	global_load_lds_dwordx4 v134, s[22:23]
	s_mov_b32 m0, s34
	s_nop 0
	global_load_lds_dwordx4 v132, s[22:23]
	s_waitcnt vmcnt(8)
	s_waitcnt lgkmcnt(0)
	s_setprio 1
	s_barrier
	v_mfma_f32_16x16x32_bf16 v[128:131], v[184:187], v[216:219], v[128:131]
	v_mfma_f32_16x16x32_bf16 v[120:123], v[192:195], v[216:219], v[120:123]
	v_mfma_f32_16x16x32_bf16 v[112:115], v[184:187], v[224:227], v[112:115]
	v_mfma_f32_16x16x32_bf16 v[104:107], v[192:195], v[224:227], v[104:107]
	v_mfma_f32_16x16x32_bf16 v[96:99], v[184:187], v[232:235], v[96:99]
	v_mfma_f32_16x16x32_bf16 v[88:91], v[192:195], v[232:235], v[88:91]
	v_mfma_f32_16x16x32_bf16 v[80:83], v[184:187], v[240:243], v[80:83]
	v_mfma_f32_16x16x32_bf16 v[72:75], v[192:195], v[240:243], v[72:75]
	v_mfma_f32_16x16x32_bf16 v[128:131], v[188:191], v[220:223], v[128:131]
	v_mfma_f32_16x16x32_bf16 v[120:123], v[196:199], v[220:223], v[120:123]
	v_mfma_f32_16x16x32_bf16 v[112:115], v[188:191], v[228:231], v[112:115]
	v_mfma_f32_16x16x32_bf16 v[104:107], v[196:199], v[228:231], v[104:107]
	v_mfma_f32_16x16x32_bf16 v[96:99], v[188:191], v[236:239], v[96:99]
	v_mfma_f32_16x16x32_bf16 v[88:91], v[196:199], v[236:239], v[88:91]
	v_mfma_f32_16x16x32_bf16 v[80:83], v[188:191], v[244:247], v[80:83]
	v_mfma_f32_16x16x32_bf16 v[72:75], v[196:199], v[244:247], v[72:75]
	v_mfma_f32_16x16x32_bf16 v[124:127], v[200:203], v[216:219], v[124:127]
	v_mfma_f32_16x16x32_bf16 v[116:119], v[208:211], v[216:219], v[116:119]
	v_mfma_f32_16x16x32_bf16 v[108:111], v[200:203], v[224:227], v[108:111]
	v_mfma_f32_16x16x32_bf16 v[100:103], v[208:211], v[224:227], v[100:103]
	v_mfma_f32_16x16x32_bf16 v[92:95], v[200:203], v[232:235], v[92:95]
	v_mfma_f32_16x16x32_bf16 v[84:87], v[208:211], v[232:235], v[84:87]
	v_mfma_f32_16x16x32_bf16 v[76:79], v[200:203], v[240:243], v[76:79]
	v_mfma_f32_16x16x32_bf16 v[68:71], v[208:211], v[240:243], v[68:71]
	v_mfma_f32_16x16x32_bf16 v[124:127], v[204:207], v[220:223], v[124:127]
	v_mfma_f32_16x16x32_bf16 v[116:119], v[212:215], v[220:223], v[116:119]
	v_mfma_f32_16x16x32_bf16 v[108:111], v[204:207], v[228:231], v[108:111]
	v_mfma_f32_16x16x32_bf16 v[100:103], v[212:215], v[228:231], v[100:103]
	v_mfma_f32_16x16x32_bf16 v[92:95], v[204:207], v[236:239], v[92:95]
	v_mfma_f32_16x16x32_bf16 v[84:87], v[212:215], v[236:239], v[84:87]
	v_mfma_f32_16x16x32_bf16 v[76:79], v[204:207], v[244:247], v[76:79]
	v_mfma_f32_16x16x32_bf16 v[68:71], v[212:215], v[244:247], v[68:71]
	s_barrier
	s_setprio 0
	s_add_i32 s22, s63, s27
	s_mov_b32 m0, s22
	ds_read_b128 v[216:219], v155 offset:49152
	ds_read_b128 v[220:223], v155 offset:50176
	ds_read_b128 v[224:227], v155 offset:51200
	ds_read_b128 v[228:231], v155 offset:52224
	ds_read_b128 v[232:235], v155 offset:53248
	ds_read_b128 v[236:239], v155 offset:54272
	ds_read_b128 v[240:243], v155 offset:55296
	ds_read_b128 v[244:247], v155 offset:56320
	s_add_u32 vcc_lo, s20, 0x80
	s_addc_u32 vcc_hi, s21, 0
	global_load_lds_dwordx4 v2, vcc
	s_add_i32 m0, s22, 0x2000
	s_add_u32 s20, s20, 0x80080
	s_addc_u32 s21, s21, 0
	s_add_i32 s22, s64, s27
	s_add_u32 vcc_lo, s20, 0xfff80000
	s_addc_u32 vcc_hi, s21, -1
	global_load_lds_dwordx4 v0, vcc
	s_mov_b32 m0, s22
	s_nop 0
	global_load_lds_dwordx4 v2, s[20:21]
	s_add_i32 m0, s22, 0x2000
	s_nop 0
	global_load_lds_dwordx4 v0, s[20:21]
	v_lshl_add_u64 v[150:151], v[248:249], 0, s[36:37]
	s_mov_b32 m0, s35
	s_nop 0
	global_load_lds_dwordx4 v[150:151], off
	v_lshl_add_u64 v[150:151], v[250:251], 0, s[36:37]
	s_mov_b32 m0, s42
	s_nop 0
	global_load_lds_dwordx4 v[150:151], off
	s_waitcnt vmcnt(8)
	s_waitcnt lgkmcnt(0)
	s_setprio 1
	s_barrier
	v_mfma_f32_16x16x32_bf16 v[64:67], v[184:187], v[216:219], v[64:67]
	v_mfma_f32_16x16x32_bf16 v[56:59], v[192:195], v[216:219], v[56:59]
	v_mfma_f32_16x16x32_bf16 v[48:51], v[184:187], v[224:227], v[48:51]
	v_mfma_f32_16x16x32_bf16 v[40:43], v[192:195], v[224:227], v[40:43]
	v_mfma_f32_16x16x32_bf16 v[32:35], v[184:187], v[232:235], v[32:35]
	v_mfma_f32_16x16x32_bf16 v[24:27], v[192:195], v[232:235], v[24:27]
	v_mfma_f32_16x16x32_bf16 v[16:19], v[184:187], v[240:243], v[16:19]
	v_mfma_f32_16x16x32_bf16 v[8:11], v[192:195], v[240:243], v[8:11]
	v_mfma_f32_16x16x32_bf16 v[64:67], v[188:191], v[220:223], v[64:67]
	v_mfma_f32_16x16x32_bf16 v[56:59], v[196:199], v[220:223], v[56:59]
	v_mfma_f32_16x16x32_bf16 v[48:51], v[188:191], v[228:231], v[48:51]
	v_mfma_f32_16x16x32_bf16 v[40:43], v[196:199], v[228:231], v[40:43]
	v_mfma_f32_16x16x32_bf16 v[32:35], v[188:191], v[236:239], v[32:35]
	v_mfma_f32_16x16x32_bf16 v[24:27], v[196:199], v[236:239], v[24:27]
	v_mfma_f32_16x16x32_bf16 v[16:19], v[188:191], v[244:247], v[16:19]
	v_mfma_f32_16x16x32_bf16 v[8:11], v[196:199], v[244:247], v[8:11]
	v_mfma_f32_16x16x32_bf16 v[60:63], v[200:203], v[216:219], v[60:63]
	v_mfma_f32_16x16x32_bf16 v[52:55], v[208:211], v[216:219], v[52:55]
	v_mfma_f32_16x16x32_bf16 v[44:47], v[200:203], v[224:227], v[44:47]
	v_mfma_f32_16x16x32_bf16 v[36:39], v[208:211], v[224:227], v[36:39]
	v_mfma_f32_16x16x32_bf16 v[28:31], v[200:203], v[232:235], v[28:31]
	v_mfma_f32_16x16x32_bf16 v[20:23], v[208:211], v[232:235], v[20:23]
	v_mfma_f32_16x16x32_bf16 v[12:15], v[200:203], v[240:243], v[12:15]
	v_mfma_f32_16x16x32_bf16 v[4:7], v[208:211], v[240:243], v[4:7]
	v_mfma_f32_16x16x32_bf16 v[60:63], v[204:207], v[220:223], v[60:63]
	v_mfma_f32_16x16x32_bf16 v[52:55], v[212:215], v[220:223], v[52:55]
	v_mfma_f32_16x16x32_bf16 v[44:47], v[204:207], v[228:231], v[44:47]
	v_mfma_f32_16x16x32_bf16 v[36:39], v[212:215], v[228:231], v[36:39]
	v_mfma_f32_16x16x32_bf16 v[28:31], v[204:207], v[236:239], v[28:31]
	v_mfma_f32_16x16x32_bf16 v[20:23], v[212:215], v[236:239], v[20:23]
	v_mfma_f32_16x16x32_bf16 v[12:15], v[204:207], v[244:247], v[12:15]
	v_mfma_f32_16x16x32_bf16 v[4:7], v[212:215], v[244:247], v[4:7]
	s_barrier
	s_setprio 0
	s_add_i32 s57, s57, 2
	s_add_u32 s18, s18, 0x100
	s_addc_u32 s19, s19, 0
	s_add_u32 s51, s51, 0x100
	s_addc_u32 s56, s56, 0
	s_cmp_gt_u32 s57, 29
	s_cbranch_scc0 .LBB0_567
	s_and_b64 vcc, exec, s[6:7]
	s_cbranch_vccz .LBB0_570
	s_barrier
